# filter tap loop: the 64 LDS weight reads per step went through flat_load (generic address); now ds_read_b128; also LDS index padding computed with two VALU ops instead of four in the FFT butterflies
# speedup vs baseline: 1.0232x; 1.0103x over previous
; DI void filter_phase(const P& p, unsigned char* lds) {
;     ...
;         const float4* zr = (const float4*)(z2 + (size_t)t * 64);
;         const float* b3p = p.in[I_HB3] + l * 1024 + c;
;         float a0 = b3p[0], a1 = b3p[256], a2 = b3p[512], a3 = b3p[768];
;         const float* w3s = w3s_;
;         asm volatile("" : "+v"(w3s));
; #pragma unroll
;         for (int i = 0; i < 16; ++i) {
;           float4 z = zr[i];
;           a0 += z.x * w3s[4 * i] + z.y * w3s[4 * i + 1] + z.z * w3s[4 * i + 2] + z.w * w3s[4 * i + 3];
;           a1 += z.x * w3s[64 + 4 * i] + z.y * w3s[64 + 4 * i + 1] + z.z * w3s[64 + 4 * i + 2] + z.w * w3s[64 + 4 * i + 3];
;           a2 += z.x * w3s[128 + 4 * i] + z.y * w3s[128 + 4 * i + 1] + z.z * w3s[128 + 4 * i + 2] + z.w * w3s[128 + 4 * i + 3];
;           a3 += z.x * w3s[192 + 4 * i] + z.y * w3s[192 + 4 * i + 1] + z.z * w3s[192 + 4 * i + 2] + z.w * w3s[192 + 4 * i + 3];
;         }
.LBB0_96:
	v_cmp_gt_i32_e32 vcc, s38, v206
	s_and_saveexec_b64 s[16:17], vcc
	s_cbranch_execz .LBB0_95
	s_add_i32 s13, 0, 0x22000
	s_cmp_lg_u32 s13, -1
	s_mov_b64 s[18:19], src_shared_base
	s_cselect_b32 s13, s13, 0
	s_cselect_b32 s18, s19, 0
	v_lshl_add_u64 v[154:155], v[212:213], 0, s[14:15]
	v_mov_b32_e32 v200, s13
	v_mov_b32_e32 v201, s18
	global_load_dword v127, v[208:209], off
	global_load_dword v207, v[208:209], off offset:1024
	global_load_dword v126, v[208:209], off offset:2048
	global_load_dword v228, v[208:209], off offset:3072
	global_load_dwordx4 v[2:5], v[154:155], off offset:48
	global_load_dwordx4 v[6:9], v[154:155], off offset:32
	global_load_dwordx4 v[10:13], v[154:155], off offset:16
	global_load_dwordx4 v[14:17], v[154:155], off
	ds_read_b128 v[128:131], v200
	ds_read_b128 v[18:21], v200 offset:256
	ds_read_b128 v[22:25], v200 offset:512
	s_waitcnt vmcnt(0)
	v_mov_b32_e32 v148, v17
	s_waitcnt lgkmcnt(0)
	v_mov_b32_e32 v27, v129
	v_mov_b32_e32 v26, v22
	v_pk_mul_f32 v[26:27], v[14:15], v[26:27]
	v_pk_mov_b32 v[22:23], v[22:23], v[128:129] op_sel:[1,0]
	s_nop 0
	v_pk_fma_f32 v[22:23], v[14:15], v[22:23], v[26:27] op_sel:[1,0,0] op_sel_hi:[0,1,1]
	v_mov_b32_e32 v26, v24
	v_mov_b32_e32 v27, v130
	v_pk_fma_f32 v[128:129], v[16:17], v[26:27], v[22:23] op_sel_hi:[0,1,1]
	v_mov_b32_e32 v130, v25
	ds_read_b128 v[90:93], v200 offset:768
	ds_read_b128 v[132:135], v200 offset:16
	ds_read_b128 v[22:25], v200 offset:272
	ds_read_b128 v[136:139], v200 offset:528
	ds_read_b128 v[94:97], v200 offset:784
	ds_read_b128 v[140:143], v200 offset:32
	ds_read_b128 v[42:45], v200 offset:288
	ds_read_b128 v[144:147], v200 offset:544
	v_pk_fma_f32 v[128:129], v[148:149], v[130:131], v[128:129] op_sel_hi:[0,1,1]
	v_pk_add_f32 v[126:127], v[126:127], v[128:129]
	v_mov_b32_e32 v130, v13
	s_waitcnt vmcnt(0) lgkmcnt(0)
	v_mov_b32_e32 v27, v133
	v_mov_b32_e32 v151, v141
	v_mov_b32_e32 v26, v136
	v_pk_mul_f32 v[26:27], v[10:11], v[26:27]
	v_pk_mov_b32 v[28:29], v[136:137], v[132:133] op_sel:[1,0]
	v_mov_b32_e32 v136, v138
	v_pk_fma_f32 v[132:133], v[10:11], v[28:29], v[26:27] op_sel:[1,0,0] op_sel_hi:[0,1,1]
	v_mov_b32_e32 v137, v134
	v_mov_b32_e32 v141, v145
	v_pk_fma_f32 v[128:129], v[12:13], v[136:137], v[132:133] op_sel_hi:[0,1,1]
	v_mov_b32_e32 v134, v139
	v_mov_b32_e32 v150, v144
	v_pk_mul_f32 v[140:141], v[6:7], v[140:141]
	v_pk_fma_f32 v[128:129], v[130:131], v[134:135], v[128:129] op_sel_hi:[0,1,1]
	v_pk_add_f32 v[126:127], v[126:127], v[128:129]
	v_pk_fma_f32 v[128:129], v[6:7], v[150:151], v[140:141] op_sel:[0,0,1] op_sel_hi:[1,1,0]
	v_mov_b32_e32 v130, v146
	v_mov_b32_e32 v131, v142
	v_pk_fma_f32 v[128:129], v[8:9], v[130:131], v[128:129] op_sel_hi:[0,1,1]
	v_mov_b32_e32 v130, v9
	v_mov_b32_e32 v142, v147
	v_pk_fma_f32 v[128:129], v[130:131], v[142:143], v[128:129] op_sel_hi:[0,1,1]
	ds_read_b128 v[118:121], v200 offset:800
	ds_read_b128 v[86:89], v200 offset:304
	ds_read_b128 v[106:109], v200 offset:816
	global_load_dwordx4 v[62:65], v[154:155], off offset:80
	global_load_dwordx4 v[74:77], v[154:155], off offset:64
	global_load_dwordx4 v[54:57], v[154:155], off offset:112
	global_load_dwordx4 v[58:61], v[154:155], off offset:96
	ds_read_b128 v[82:85], v200 offset:320
	ds_read_b128 v[102:105], v200 offset:832
	ds_read_b128 v[78:81], v200 offset:336
	ds_read_b128 v[98:101], v200 offset:848
	ds_read_b128 v[122:125], v200 offset:864
	ds_read_b128 v[66:69], v200 offset:368
	ds_read_b128 v[70:73], v200 offset:352
	ds_read_b128 v[114:117], v200 offset:880
	ds_read_b128 v[110:113], v200 offset:896
	global_load_dwordx4 v[26:29], v[154:155], off offset:176
	global_load_dwordx4 v[30:33], v[154:155], off offset:160
	global_load_dwordx4 v[34:37], v[154:155], off offset:144
	global_load_dwordx4 v[38:41], v[154:155], off offset:128
	ds_read_b128 v[46:49], v200 offset:400
	ds_read_b128 v[50:53], v200 offset:384
	v_pk_add_f32 v[134:135], v[126:127], v[128:129]
	ds_read_b128 v[126:129], v200 offset:48
	ds_read_b128 v[130:133], v200 offset:560
	s_waitcnt vmcnt(0)
	v_mov_b32_e32 v202, v29
	s_waitcnt lgkmcnt(0)
	v_mov_b32_e32 v137, v127
	v_mov_b32_e32 v136, v130
	v_pk_mul_f32 v[136:137], v[2:3], v[136:137]
	v_pk_mov_b32 v[126:127], v[130:131], v[126:127] op_sel:[1,0]
	v_mov_b32_e32 v130, v132
	v_pk_fma_f32 v[126:127], v[2:3], v[126:127], v[136:137] op_sel:[1,0,0] op_sel_hi:[0,1,1]
	v_mov_b32_e32 v131, v128
	v_pk_fma_f32 v[126:127], v[4:5], v[130:131], v[126:127] op_sel_hi:[0,1,1]
	v_mov_b32_e32 v130, v5
	v_mov_b32_e32 v128, v133
	v_pk_fma_f32 v[126:127], v[130:131], v[128:129], v[126:127] op_sel_hi:[0,1,1]
	v_pk_add_f32 v[134:135], v[134:135], v[126:127]
	ds_read_b128 v[126:129], v200 offset:64
	ds_read_b128 v[130:133], v200 offset:576
	s_waitcnt vmcnt(0) lgkmcnt(0)
	v_mov_b32_e32 v137, v127
	v_mov_b32_e32 v136, v130
	v_pk_mul_f32 v[136:137], v[74:75], v[136:137]
	v_pk_mov_b32 v[126:127], v[130:131], v[126:127] op_sel:[1,0]
	v_mov_b32_e32 v130, v132
	v_pk_fma_f32 v[126:127], v[74:75], v[126:127], v[136:137] op_sel:[1,0,0] op_sel_hi:[0,1,1]
	v_mov_b32_e32 v131, v128
	v_pk_fma_f32 v[126:127], v[76:77], v[130:131], v[126:127] op_sel_hi:[0,1,1]
	v_mov_b32_e32 v130, v77
	v_mov_b32_e32 v128, v133
	v_pk_fma_f32 v[126:127], v[130:131], v[128:129], v[126:127] op_sel_hi:[0,1,1]
	v_pk_add_f32 v[134:135], v[134:135], v[126:127]
	ds_read_b128 v[126:129], v200 offset:80
	ds_read_b128 v[130:133], v200 offset:592
	s_waitcnt vmcnt(0) lgkmcnt(0)
; DI void filter_phase(const P& p, unsigned char* lds) {
;     ...
;         for (int i = 0; i < 16; ++i) {
;           float4 z = zr[i];
;           a0 += z.x * w3s[4 * i] + z.y * w3s[4 * i + 1] + z.z * w3s[4 * i + 2] + z.w * w3s[4 * i + 3];
;           a1 += z.x * w3s[64 + 4 * i] + z.y * w3s[64 + 4 * i + 1] + z.z * w3s[64 + 4 * i + 2] + z.w * w3s[64 + 4 * i + 3];
;           a2 += z.x * w3s[128 + 4 * i] + z.y * w3s[128 + 4 * i + 1] + z.z * w3s[128 + 4 * i + 2] + z.w * w3s[128 + 4 * i + 3];
;           a3 += z.x * w3s[192 + 4 * i] + z.y * w3s[192 + 4 * i + 1] + z.z * w3s[192 + 4 * i + 2] + z.w * w3s[192 + 4 * i + 3];
;         }
	v_mov_b32_e32 v137, v127
	v_mov_b32_e32 v136, v130
	v_pk_mul_f32 v[136:137], v[62:63], v[136:137]
	v_pk_mov_b32 v[126:127], v[130:131], v[126:127] op_sel:[1,0]
	v_mov_b32_e32 v130, v132
	v_pk_fma_f32 v[126:127], v[62:63], v[126:127], v[136:137] op_sel:[1,0,0] op_sel_hi:[0,1,1]
	v_mov_b32_e32 v131, v128
	v_pk_fma_f32 v[126:127], v[64:65], v[130:131], v[126:127] op_sel_hi:[0,1,1]
	v_mov_b32_e32 v130, v65
	v_mov_b32_e32 v128, v133
	v_pk_fma_f32 v[126:127], v[130:131], v[128:129], v[126:127] op_sel_hi:[0,1,1]
	v_pk_add_f32 v[138:139], v[134:135], v[126:127]
	ds_read_b128 v[126:129], v200 offset:96
	ds_read_b128 v[130:133], v200 offset:608
	ds_read_b128 v[134:137], v200 offset:112
	s_waitcnt vmcnt(0) lgkmcnt(0)
	v_mov_b32_e32 v141, v127
	v_mov_b32_e32 v140, v130
	v_pk_mul_f32 v[140:141], v[58:59], v[140:141]
	v_pk_mov_b32 v[126:127], v[130:131], v[126:127] op_sel:[1,0]
	v_mov_b32_e32 v130, v132
	v_pk_fma_f32 v[126:127], v[58:59], v[126:127], v[140:141] op_sel:[1,0,0] op_sel_hi:[0,1,1]
	v_mov_b32_e32 v131, v128
	v_pk_fma_f32 v[126:127], v[60:61], v[130:131], v[126:127] op_sel_hi:[0,1,1]
	v_mov_b32_e32 v130, v61
	v_mov_b32_e32 v128, v133
	v_pk_fma_f32 v[126:127], v[130:131], v[128:129], v[126:127] op_sel_hi:[0,1,1]
	v_pk_add_f32 v[130:131], v[138:139], v[126:127]
	ds_read_b128 v[126:129], v200 offset:624
	v_mov_b32_e32 v133, v135
	s_waitcnt vmcnt(0) lgkmcnt(0)
	v_mov_b32_e32 v132, v126
	v_pk_mul_f32 v[132:133], v[54:55], v[132:133]
	v_pk_mov_b32 v[126:127], v[126:127], v[134:135] op_sel:[1,0]
	s_nop 0
	v_pk_fma_f32 v[126:127], v[54:55], v[126:127], v[132:133] op_sel:[1,0,0] op_sel_hi:[0,1,1]
	v_mov_b32_e32 v132, v128
	v_mov_b32_e32 v133, v136
	v_pk_fma_f32 v[126:127], v[56:57], v[132:133], v[126:127] op_sel_hi:[0,1,1]
	v_mov_b32_e32 v128, v57
	v_mov_b32_e32 v136, v129
	v_pk_fma_f32 v[126:127], v[128:129], v[136:137], v[126:127] op_sel_hi:[0,1,1]
	v_pk_add_f32 v[138:139], v[130:131], v[126:127]
	ds_read_b128 v[126:129], v200 offset:128
	ds_read_b128 v[130:133], v200 offset:640
	ds_read_b128 v[134:137], v200 offset:144
	s_waitcnt vmcnt(0) lgkmcnt(0)
	v_mov_b32_e32 v141, v127
	v_mov_b32_e32 v140, v130
	v_pk_mul_f32 v[140:141], v[38:39], v[140:141]
	v_pk_mov_b32 v[126:127], v[130:131], v[126:127] op_sel:[1,0]
	v_mov_b32_e32 v130, v132
	v_pk_fma_f32 v[126:127], v[38:39], v[126:127], v[140:141] op_sel:[1,0,0] op_sel_hi:[0,1,1]
	v_mov_b32_e32 v131, v128
	v_pk_fma_f32 v[126:127], v[40:41], v[130:131], v[126:127] op_sel_hi:[0,1,1]
	v_mov_b32_e32 v130, v41
	v_mov_b32_e32 v128, v133
	v_pk_fma_f32 v[126:127], v[130:131], v[128:129], v[126:127] op_sel_hi:[0,1,1]
	v_pk_add_f32 v[130:131], v[138:139], v[126:127]
	ds_read_b128 v[126:129], v200 offset:656
	v_mov_b32_e32 v133, v135
	s_waitcnt vmcnt(0) lgkmcnt(0)
	v_mov_b32_e32 v132, v126
	v_pk_mul_f32 v[132:133], v[34:35], v[132:133]
	v_pk_mov_b32 v[126:127], v[126:127], v[134:135] op_sel:[1,0]
	s_nop 0
	v_pk_fma_f32 v[126:127], v[34:35], v[126:127], v[132:133] op_sel:[1,0,0] op_sel_hi:[0,1,1]
	v_mov_b32_e32 v132, v128
	v_mov_b32_e32 v133, v136
	v_pk_fma_f32 v[126:127], v[36:37], v[132:133], v[126:127] op_sel_hi:[0,1,1]
	v_mov_b32_e32 v128, v37
	v_mov_b32_e32 v136, v129
	v_pk_fma_f32 v[126:127], v[128:129], v[136:137], v[126:127] op_sel_hi:[0,1,1]
	v_pk_add_f32 v[216:217], v[130:131], v[126:127]
	ds_read_b128 v[138:141], v200 offset:912
	ds_read_b128 v[134:137], v200 offset:928
	ds_read_b128 v[192:195], v200 offset:176
	ds_read_b128 v[126:129], v200 offset:160
	ds_read_b128 v[130:133], v200 offset:672
	s_waitcnt vmcnt(0) lgkmcnt(0)
	v_mov_b32_e32 v147, v193
	v_mov_b32_e32 v143, v127
	v_mov_b32_e32 v142, v130
	v_pk_mul_f32 v[142:143], v[30:31], v[142:143]
	v_pk_mov_b32 v[126:127], v[130:131], v[126:127] op_sel:[1,0]
	v_mov_b32_e32 v130, v132
	v_pk_fma_f32 v[126:127], v[30:31], v[126:127], v[142:143] op_sel:[1,0,0] op_sel_hi:[0,1,1]
	v_mov_b32_e32 v131, v128
	v_pk_fma_f32 v[126:127], v[32:33], v[130:131], v[126:127] op_sel_hi:[0,1,1]
	v_mov_b32_e32 v130, v33
	v_mov_b32_e32 v128, v133
	v_pk_fma_f32 v[218:219], v[130:131], v[128:129], v[126:127] op_sel_hi:[0,1,1]
	ds_read_b128 v[126:129], v200 offset:432
	ds_read_b128 v[130:133], v200 offset:416
	ds_read_b128 v[142:145], v200 offset:688
	v_pk_add_f32 v[216:217], v[216:217], v[218:219]
	s_waitcnt vmcnt(0) lgkmcnt(0)
	v_mov_b32_e32 v146, v142
	v_pk_mul_f32 v[146:147], v[26:27], v[146:147]
	v_pk_mov_b32 v[142:143], v[142:143], v[192:193] op_sel:[1,0]
	s_nop 0
	v_pk_fma_f32 v[142:143], v[26:27], v[142:143], v[146:147] op_sel:[1,0,0] op_sel_hi:[0,1,1]
	v_mov_b32_e32 v146, v144
	v_mov_b32_e32 v147, v194
	v_pk_fma_f32 v[220:221], v[28:29], v[146:147], v[142:143] op_sel_hi:[0,1,1]
	v_mov_b32_e32 v194, v145
	ds_read_b128 v[158:161], v200 offset:944
	ds_read_b128 v[196:199], v200 offset:192
	ds_read_b128 v[232:235], v200 offset:704
	ds_read_b128 v[178:181], v200 offset:960
	ds_read_b128 v[236:239], v200 offset:208
	global_load_dwordx4 v[142:145], v[154:155], off offset:240
	global_load_dwordx4 v[146:149], v[154:155], off offset:224
	global_load_dwordx4 v[150:153], v[154:155], off offset:208
	s_nop 0
	global_load_dwordx4 v[154:157], v[154:155], off offset:192
	v_pk_fma_f32 v[194:195], v[202:203], v[194:195], v[220:221] op_sel_hi:[0,1,1]
	v_pk_add_f32 v[194:195], v[216:217], v[194:195]
	s_waitcnt vmcnt(0) lgkmcnt(0)
; DI void filter_phase(const P& p, unsigned char* lds) {
;     ...
;           a0 += z.x * w3s[4 * i] + z.y * w3s[4 * i + 1] + z.z * w3s[4 * i + 2] + z.w * w3s[4 * i + 3];
;           a1 += z.x * w3s[64 + 4 * i] + z.y * w3s[64 + 4 * i + 1] + z.z * w3s[64 + 4 * i + 2] + z.w * w3s[64 + 4 * i + 3];
;           a2 += z.x * w3s[128 + 4 * i] + z.y * w3s[128 + 4 * i + 1] + z.z * w3s[128 + 4 * i + 2] + z.w * w3s[128 + 4 * i + 3];
;           a3 += z.x * w3s[192 + 4 * i] + z.y * w3s[192 + 4 * i + 1] + z.z * w3s[192 + 4 * i + 2] + z.w * w3s[192 + 4 * i + 3];
;         }
;         float dec = __expf(-((float)t / (float)(Lf - 1)) * delta);
;         a0 *= dec; a1 *= dec; a2 *= dec; a3 *= dec;
;         s[phys(t)] = make_float2(a0, 0.f);
;         lsum0 += fabsf(a0);
;         lsum1 += fabsf(a2);
;         if (t >= 1) { s[phys(2 * Lf - t)] = make_float2(a1, 0.f); lsum0 += fabsf(a1); lsum1 += fabsf(a3); }
;         else s[phys(Lf)] = make_float2(0.f, 0.f);
;         park[t] = make_float2(a2, a3);
	v_mov_b32_e32 v163, v197
	v_mov_b32_e32 v162, v232
	v_pk_mov_b32 v[164:165], v[232:233], v[196:197] op_sel:[1,0]
	v_mov_b32_e32 v233, v198
	v_cvt_f32_i32_e32 v198, v206
	v_mov_b32_e32 v232, v234
	v_mov_b32_e32 v245, v237
	v_pk_mul_f32 v[162:163], v[154:155], v[162:163]
	v_div_scale_f32 v214, s[18:19], v224, v224, v198
	v_pk_fma_f32 v[196:197], v[154:155], v[164:165], v[162:163] op_sel:[1,0,0] op_sel_hi:[0,1,1]
	ds_read_b128 v[162:165], v200 offset:464
	ds_read_b128 v[166:169], v200 offset:448
	ds_read_b128 v[240:243], v200 offset:720
	v_rcp_f32_e32 v229, v214
	v_pk_fma_f32 v[196:197], v[156:157], v[232:233], v[196:197] op_sel_hi:[0,1,1]
	v_mov_b32_e32 v202, v157
	ds_read_b128 v[190:193], v200 offset:976
	ds_read_b128 v[186:189], v200 offset:992
	ds_read_b128 v[170:173], v200 offset:496
	ds_read_b128 v[174:177], v200 offset:480
	ds_read_b128 v[182:185], v200 offset:1008
	v_fma_f32 v234, -v214, v229, 1.0
	v_fmac_f32_e32 v229, v234, v229
	v_div_scale_f32 v234, vcc, v198, v224, v198
	s_waitcnt vmcnt(0) lgkmcnt(0)
	v_mov_b32_e32 v244, v240
	v_mul_f32_e32 v240, v234, v229
	v_mov_b32_e32 v237, v241
	v_fma_f32 v241, -v214, v240, v234
	v_fmac_f32_e32 v240, v241, v229
	v_fma_f32 v214, -v214, v240, v234
	v_div_fmas_f32 v214, v214, v229, v240
	v_div_fixup_f32 v198, v214, v224, v198
	v_mul_f32_e32 v198, v223, v198
	v_mul_f32_e32 v198, 0xbfb8aa3b, v198
	v_exp_f32_e32 v214, v198
	v_ashrrev_i32_e32 v198, 4, v206
	v_lshlrev_b32_e32 v198, 3, v198
	v_add3_u32 v229, 0, v198, v225
	v_mov_b32_e32 v198, v235
	v_pk_mul_f32 v[236:237], v[150:151], v[236:237]
	v_pk_fma_f32 v[196:197], v[202:203], v[198:199], v[196:197] op_sel_hi:[0,1,1]
	v_pk_add_f32 v[194:195], v[194:195], v[196:197]
	v_pk_fma_f32 v[196:197], v[150:151], v[244:245], v[236:237] op_sel:[0,0,1] op_sel_hi:[1,1,0]
	v_mov_b32_e32 v198, v242
	v_mov_b32_e32 v199, v238
	v_pk_fma_f32 v[196:197], v[152:153], v[198:199], v[196:197] op_sel_hi:[0,1,1]
	v_mov_b32_e32 v198, v153
	v_mov_b32_e32 v238, v243
	v_pk_fma_f32 v[196:197], v[198:199], v[238:239], v[196:197] op_sel_hi:[0,1,1]
	v_pk_add_f32 v[194:195], v[194:195], v[196:197]
	ds_read_b128 v[196:199], v200 offset:224
	ds_read_b128 v[216:219], v200 offset:736
	v_mov_b32_e32 v202, v149
	v_cmp_gt_i32_e32 vcc, 1, v206
	s_waitcnt vmcnt(0) lgkmcnt(0)
	v_mov_b32_e32 v221, v197
	v_mov_b32_e32 v220, v216
	v_pk_mul_f32 v[220:221], v[146:147], v[220:221]
	v_pk_mov_b32 v[196:197], v[216:217], v[196:197] op_sel:[1,0]
	v_mov_b32_e32 v216, v218
	v_pk_fma_f32 v[196:197], v[146:147], v[196:197], v[220:221] op_sel:[1,0,0] op_sel_hi:[0,1,1]
	v_mov_b32_e32 v217, v198
	v_pk_fma_f32 v[196:197], v[148:149], v[216:217], v[196:197] op_sel_hi:[0,1,1]
	v_mov_b32_e32 v198, v219
	v_pk_fma_f32 v[196:197], v[202:203], v[198:199], v[196:197] op_sel_hi:[0,1,1]
	v_pk_add_f32 v[216:217], v[194:195], v[196:197]
	ds_read_b128 v[194:197], v200 offset:240
	s_nop 0
	ds_read_b128 v[198:201], v200 offset:752
	s_waitcnt vmcnt(0) lgkmcnt(0)
	v_mov_b32_e32 v219, v195
	v_mov_b32_e32 v218, v198
	v_pk_mul_f32 v[218:219], v[142:143], v[218:219]
	v_pk_mov_b32 v[194:195], v[198:199], v[194:195] op_sel:[1,0]
	v_mov_b32_e32 v198, v200
	v_pk_fma_f32 v[194:195], v[142:143], v[194:195], v[218:219] op_sel:[1,0,0] op_sel_hi:[0,1,1]
	v_mov_b32_e32 v199, v196
	v_pk_fma_f32 v[194:195], v[144:145], v[198:199], v[194:195] op_sel_hi:[0,1,1]
	v_mov_b32_e32 v198, v145
	v_mov_b32_e32 v196, v201
	v_pk_fma_f32 v[194:195], v[198:199], v[196:197], v[194:195] op_sel_hi:[0,1,1]
	v_pk_add_f32 v[194:195], v[216:217], v[194:195]
	s_nop 0
	v_pk_mul_f32 v[194:195], v[214:215], v[194:195] op_sel_hi:[0,1]
	v_mov_b32_e32 v202, v195
	ds_write_b64 v229, v[202:203]
	s_and_saveexec_b64 s[18:19], vcc
	s_xor_b64 s[18:19], exec, s[18:19]
	s_add_i32 s13, s39, s40
	v_mov_b32_e32 v18, s13
	ds_write_b64 v18, v[230:231]
	s_or_saveexec_b64 s[18:19], s[18:19]
	v_mul_f32_e32 v91, v15, v91
	v_fmac_f32_e32 v91, v14, v90
	v_fmac_f32_e32 v91, v16, v92
	v_fmac_f32_e32 v91, v17, v93
	v_add_f32_e32 v90, v228, v91
	v_mul_f32_e32 v91, v11, v95
	v_fmac_f32_e32 v91, v10, v94
	v_fmac_f32_e32 v91, v12, v96
	v_fmac_f32_e32 v91, v13, v97
	v_add_f32_e32 v90, v90, v91
	v_mul_f32_e32 v91, v7, v119
	v_fmac_f32_e32 v91, v6, v118
	v_mul_f32_e32 v94, v3, v107
	v_fmac_f32_e32 v91, v8, v120
	v_fmac_f32_e32 v94, v2, v106
	v_fmac_f32_e32 v91, v9, v121
	v_fmac_f32_e32 v94, v4, v108
	v_add_f32_e32 v90, v90, v91
	v_fmac_f32_e32 v94, v5, v109
	v_add_f32_e32 v90, v90, v94
	v_mul_f32_e32 v94, v75, v103
	v_fmac_f32_e32 v94, v74, v102
	v_fmac_f32_e32 v94, v76, v104
	v_fmac_f32_e32 v94, v77, v105
	v_add_f32_e32 v90, v90, v94
	v_mul_f32_e32 v94, v63, v99
	v_mul_f32_e32 v91, v59, v123
	v_fmac_f32_e32 v94, v62, v98
	v_fmac_f32_e32 v91, v58, v122
	v_fmac_f32_e32 v94, v64, v100
	v_fmac_f32_e32 v91, v60, v124
	v_mul_f32_e32 v92, v55, v115
	v_fmac_f32_e32 v94, v65, v101
	v_fmac_f32_e32 v91, v61, v125
	v_fmac_f32_e32 v92, v54, v114
	v_mul_f32_e32 v93, v39, v111
	v_add_f32_e32 v90, v90, v94
	v_fmac_f32_e32 v92, v56, v116
	v_fmac_f32_e32 v93, v38, v110
	v_add_f32_e32 v90, v90, v91
	v_mul_f32_e32 v91, v35, v139
	v_fmac_f32_e32 v92, v57, v117
	v_fmac_f32_e32 v93, v40, v112
	v_fmac_f32_e32 v91, v34, v138
	v_fmac_f32_e32 v93, v41, v113
	v_add_f32_e32 v90, v90, v92
	v_fmac_f32_e32 v91, v36, v140
	v_add_f32_e32 v90, v90, v93
	v_fmac_f32_e32 v91, v37, v141
	v_add_f32_e32 v90, v90, v91
	v_mul_f32_e32 v91, v31, v135
	v_fmac_f32_e32 v91, v30, v134
	v_fmac_f32_e32 v91, v32, v136
	v_fmac_f32_e32 v91, v33, v137
	v_add_f32_e32 v90, v90, v91
	v_mul_f32_e32 v91, v27, v159
	v_fmac_f32_e32 v91, v26, v158
	v_fmac_f32_e32 v91, v28, v160
	v_fmac_f32_e32 v91, v29, v161
	v_add_f32_e32 v90, v90, v91
	v_mul_f32_e32 v91, v155, v179
	v_fmac_f32_e32 v91, v154, v178
	v_fmac_f32_e32 v91, v156, v180
	v_fmac_f32_e32 v91, v157, v181
	v_add_f32_e32 v90, v90, v91
	v_mul_f32_e32 v91, v151, v191
	v_fmac_f32_e32 v91, v150, v190
	v_fmac_f32_e32 v91, v152, v192
	v_fmac_f32_e32 v91, v153, v193
	v_add_f32_e32 v90, v90, v91
	v_mul_f32_e32 v91, v147, v187
	v_fmac_f32_e32 v91, v146, v186
	v_fmac_f32_e32 v91, v148, v188
	v_fmac_f32_e32 v91, v149, v189
	v_add_f32_e32 v90, v90, v91
	v_mul_f32_e32 v91, v143, v183
	v_fmac_f32_e32 v91, v142, v182
	v_fmac_f32_e32 v91, v144, v184
	v_fmac_f32_e32 v91, v145, v185
	v_add_f32_e32 v90, v90, v91
	v_and_b32_e32 v93, 0x7fffffff, v195
	v_and_b32_e32 v92, 0x7fffffff, v194
	v_mul_f32_e32 v90, v214, v90
	v_pk_add_f32 v[204:205], v[204:205], v[92:93]
	s_xor_b64 exec, exec, s[18:19]
	s_cbranch_execz .LBB0_94
; DI void filter_phase(const P& p, unsigned char* lds) {
;     ...
;           a0 += z.x * w3s[4 * i] + z.y * w3s[4 * i + 1] + z.z * w3s[4 * i + 2] + z.w * w3s[4 * i + 3];
;           a1 += z.x * w3s[64 + 4 * i] + z.y * w3s[64 + 4 * i + 1] + z.z * w3s[64 + 4 * i + 2] + z.w * w3s[64 + 4 * i + 3];
;           a2 += z.x * w3s[128 + 4 * i] + z.y * w3s[128 + 4 * i + 1] + z.z * w3s[128 + 4 * i + 2] + z.w * w3s[128 + 4 * i + 3];
;           a3 += z.x * w3s[192 + 4 * i] + z.y * w3s[192 + 4 * i + 1] + z.z * w3s[192 + 4 * i + 2] + z.w * w3s[192 + 4 * i + 3];
;         }
;         float dec = __expf(-((float)t / (float)(Lf - 1)) * delta);
;         a0 *= dec; a1 *= dec; a2 *= dec; a3 *= dec;
;         s[phys(t)] = make_float2(a0, 0.f);
;         lsum0 += fabsf(a0);
;         lsum1 += fabsf(a2);
;         if (t >= 1) { s[phys(2 * Lf - t)] = make_float2(a1, 0.f); lsum0 += fabsf(a1); lsum1 += fabsf(a3); }
	v_mul_f32_e32 v15, v15, v19
	v_fmac_f32_e32 v15, v14, v18
	v_mul_f32_e32 v11, v11, v23
	v_fmac_f32_e32 v15, v16, v20
	v_fmac_f32_e32 v11, v10, v22
	v_mul_f32_e32 v7, v7, v43
	v_fmac_f32_e32 v15, v17, v21
	v_fmac_f32_e32 v11, v12, v24
	v_fmac_f32_e32 v7, v6, v42
	v_mul_f32_e32 v3, v3, v87
	v_add_f32_e32 v14, v207, v15
	v_fmac_f32_e32 v11, v13, v25
	v_fmac_f32_e32 v7, v8, v44
	v_fmac_f32_e32 v3, v2, v86
	v_add_f32_e32 v10, v14, v11
	v_fmac_f32_e32 v7, v9, v45
	v_fmac_f32_e32 v3, v4, v88
	v_add_f32_e32 v6, v10, v7
	v_fmac_f32_e32 v3, v5, v89
	v_add_f32_e32 v2, v6, v3
	v_mul_f32_e32 v3, v75, v83
	v_fmac_f32_e32 v3, v74, v82
	v_fmac_f32_e32 v3, v76, v84
	v_fmac_f32_e32 v3, v77, v85
	v_add_f32_e32 v2, v2, v3
	v_mul_f32_e32 v3, v63, v79
	v_fmac_f32_e32 v3, v62, v78
	v_fmac_f32_e32 v3, v64, v80
	v_fmac_f32_e32 v3, v65, v81
	v_pk_mul_f32 v[6:7], v[54:55], v[66:67]
	v_pk_mul_f32 v[8:9], v[58:59], v[70:71]
	v_add_f32_e32 v12, v2, v3
	v_pk_mul_f32 v[2:3], v[60:61], v[72:73]
	v_pk_mul_f32 v[4:5], v[56:57], v[68:69]
	v_mov_b32_e32 v10, v8
	v_mov_b32_e32 v11, v6
	v_mov_b32_e32 v6, v9
	v_mov_b32_e32 v8, v2
	v_mov_b32_e32 v9, v4
	v_mov_b32_e32 v4, v3
	v_pk_add_f32 v[2:3], v[10:11], v[6:7]
	v_pk_mul_f32 v[6:7], v[34:35], v[46:47]
	v_pk_add_f32 v[2:3], v[2:3], v[8:9]
	v_pk_mul_f32 v[8:9], v[38:39], v[50:51]
	v_pk_add_f32 v[2:3], v[2:3], v[4:5]
	v_pk_mul_f32 v[4:5], v[36:37], v[48:49]
	v_add_f32_e32 v2, v12, v2
	v_add_f32_e32 v12, v2, v3
	v_pk_mul_f32 v[2:3], v[40:41], v[52:53]
	v_mov_b32_e32 v10, v8
	v_mov_b32_e32 v11, v6
	v_mov_b32_e32 v6, v9
	v_mov_b32_e32 v8, v2
	v_mov_b32_e32 v9, v4
	v_mov_b32_e32 v4, v3
	v_pk_add_f32 v[2:3], v[10:11], v[6:7]
	v_pk_mul_f32 v[6:7], v[26:27], v[126:127]
	v_pk_add_f32 v[2:3], v[2:3], v[8:9]
	v_pk_mul_f32 v[8:9], v[30:31], v[130:131]
	v_pk_add_f32 v[2:3], v[2:3], v[4:5]
	v_pk_mul_f32 v[4:5], v[28:29], v[128:129]
	v_add_f32_e32 v2, v12, v2
	v_add_f32_e32 v12, v2, v3
	v_pk_mul_f32 v[2:3], v[32:33], v[132:133]
	v_mov_b32_e32 v10, v8
	v_mov_b32_e32 v11, v6
	v_mov_b32_e32 v6, v9
	v_mov_b32_e32 v8, v2
	v_mov_b32_e32 v9, v4
	v_mov_b32_e32 v4, v3
	v_pk_add_f32 v[2:3], v[10:11], v[6:7]
	v_pk_mul_f32 v[6:7], v[150:151], v[162:163]
	v_pk_add_f32 v[2:3], v[2:3], v[8:9]
	v_pk_mul_f32 v[8:9], v[154:155], v[166:167]
	v_pk_add_f32 v[2:3], v[2:3], v[4:5]
	v_pk_mul_f32 v[4:5], v[152:153], v[164:165]
	v_add_f32_e32 v2, v12, v2
	v_add_f32_e32 v12, v2, v3
	v_pk_mul_f32 v[2:3], v[156:157], v[168:169]
	v_mov_b32_e32 v10, v8
	v_mov_b32_e32 v11, v6
	v_mov_b32_e32 v6, v9
	v_mov_b32_e32 v8, v2
	v_mov_b32_e32 v9, v4
	v_mov_b32_e32 v4, v3
	v_pk_add_f32 v[2:3], v[10:11], v[6:7]
	v_mov_b32_e32 v7, v142
	v_pk_add_f32 v[2:3], v[2:3], v[8:9]
	v_mov_b32_e32 v9, v170
	v_pk_add_f32 v[2:3], v[2:3], v[4:5]
	v_mov_b32_e32 v142, v147
	v_mov_b32_e32 v170, v175
	v_add_f32_e32 v2, v12, v2
	v_mov_b32_e32 v6, v146
	v_mov_b32_e32 v8, v174
	v_pk_mul_f32 v[10:11], v[142:143], v[170:171]
	v_add_f32_e32 v12, v2, v3
	v_mov_b32_e32 v2, v148
	v_mov_b32_e32 v3, v144
	v_mov_b32_e32 v4, v176
	v_mov_b32_e32 v5, v172
	v_pk_fma_f32 v[6:7], v[6:7], v[8:9], v[10:11]
	v_mov_b32_e32 v144, v149
	v_mov_b32_e32 v172, v177
	v_pk_fma_f32 v[2:3], v[2:3], v[4:5], v[6:7]
	s_nop 0
	v_pk_fma_f32 v[2:3], v[144:145], v[172:173], v[2:3]
	s_nop 0
	v_add_f32_e32 v2, v12, v2
	v_add_f32_e32 v2, v2, v3
	v_mul_f32_e32 v202, v214, v2
	v_ashrrev_i32_e32 v2, 4, v227
	v_lshlrev_b32_e32 v2, 3, v2
	v_add3_u32 v2, 0, v2, v226
	ds_write_b64 v2, v[202:203]
	v_and_b32_e32 v3, 0x7fffffff, v202
	v_and_b32_e32 v2, 0x7fffffff, v90
	v_pk_add_f32 v[204:205], v[204:205], v[2:3]
	s_branch .LBB0_94

; DI void filter_phase(const P& p, unsigned char* lds) {
;     ...
;       float tot = block_sum(o == 0 ? lsum0 : lsum1, red);
;       float inv = 1.f / tot;
;       if (lat) {
;         fft_lds<16384, false>(s);
;         float2* dst = (float2*)(p.ws + O_SPEC) + ((size_t)(l * 2 + o) * 256 + c) * 16384;
; #pragma unroll 8
;         for (int i = tid; i < 16384; i += NT) { float2 v = s[phys(i)]; dst[i] = make_float2(v.x * inv, v.y * inv); }
;       } else {
;         float* dst = (float*)(p.ws + O_FILTC) + (size_t)(o * 256 + c) * 512;
;         dst[tid] = s[phys(tid)].x * inv;
.LBB0_129:
	s_or_b64 exec, exec, s[14:15]
	s_add_i32 s0, 0, 0x22400
	v_mov_b32_e32 v4, s0
	s_waitcnt lgkmcnt(0)
	s_barrier
	ds_read_b128 v[4:7], v4
	v_mov_b32_e32 v8, s34
	ds_read_b128 v[8:11], v8
	s_waitcnt lgkmcnt(1)
	v_add_f32_e32 v4, 0, v4
	v_add_f32_e32 v4, v4, v5
	v_add_f32_e32 v4, v4, v6
	v_add_f32_e32 v4, v4, v7
	s_waitcnt lgkmcnt(0)
	v_add_f32_e32 v4, v4, v8
	v_add_f32_e32 v4, v4, v9
	v_add_f32_e32 v4, v4, v10
	v_add_f32_e32 v4, v4, v11
	v_div_scale_f32 v5, s[14:15], v4, v4, 1.0
	v_rcp_f32_e32 v6, v5
	s_mov_b64 s[14:15], -1
	v_fma_f32 v7, -v5, v6, 1.0
	v_fmac_f32_e32 v6, v7, v6
	v_div_scale_f32 v7, vcc, 1.0, v4, 1.0
	v_mul_f32_e32 v8, v7, v6
	v_fma_f32 v9, -v5, v8, v7
	v_fmac_f32_e32 v8, v9, v6
	v_fma_f32 v5, -v5, v8, v7
	v_div_fmas_f32 v5, v5, v6, v8
	v_div_fixup_f32 v4, v5, v4, 1.0
	s_and_b64 vcc, exec, s[10:11]
	s_cbranch_vccz .LBB0_131
	v_ashrrev_i32_e32 v5, 4, v2
	v_add_lshl_u32 v5, v5, v2, 3
	s_lshl_b32 s0, s51, 17
	ds_read_b32 v5, v5
	s_or_b32 s0, s0, s43
	s_lshl_b64 s[14:15], s[0:1], 2
	s_add_u32 s14, s25, s14
	s_addc_u32 s15, s26, s15
	s_waitcnt lgkmcnt(0)
	v_mul_f32_e32 v5, v4, v5
	v_lshl_add_u64 v[6:7], v[2:3], 2, s[14:15]
	global_store_dword v[6:7], v5, off
	s_mov_b64 s[14:15], 0

; DI float sin_t(float turns) { return __builtin_amdgcn_sinf(__builtin_amdgcn_fractf(turns)); }
; DI float cos_t(float turns) { return __builtin_amdgcn_cosf(__builtin_amdgcn_fractf(turns)); }
; DI float2 cmul(float2 a, float2 b) { return make_float2(a.x * b.x - a.y * b.y, a.x * b.y + a.y * b.x); }
; template <int N, bool INV>
; DI void fft_lds(float2* s) {
;     ...
;     for (int lq = (LG & 1) ? LG - 3 : LG - 2; lq >= 0; lq -= 2) {
;       const int q = 1 << lq;
;       __syncthreads();
;       const float inv4q = 1.0f / (float)(4 * q);
; #pragma unroll 4
;       for (int it = 0; it < N / 4 / NT; ++it) {
;         int idx = tid + it * NT;
;         int j = idx & (q - 1), blk = idx >> lq;
;         int p0 = blk * 4 * q + j;
;         float f = (float)j * inv4q;
;         float2 t1 = make_float2(cos_t(f), -sin_t(f));
;         float2 t2 = cmul(t1, t1);
;         float2 x0 = s[phys(p0)], x1 = s[phys(p0 + q)], x2 = s[phys(p0 + 2 * q)], x3 = s[phys(p0 + 3 * q)];
;         float2 a0 = make_float2(x0.x + x2.x, x0.y + x2.y);
;         float2 a2 = cmul(make_float2(x0.x - x2.x, x0.y - x2.y), t1);
;         float2 a1 = make_float2(x1.x + x3.x, x1.y + x3.y);
;         float2 d3 = make_float2(x1.x - x3.x, x1.y - x3.y);
;         float2 a3 = cmul(make_float2(d3.y, -d3.x), t1);
;         s[phys(p0)] = make_float2(a0.x + a1.x, a0.y + a1.y);
;         s[phys(p0 + q)] = cmul(make_float2(a0.x - a1.x, a0.y - a1.y), t2);
;         s[phys(p0 + 2 * q)] = make_float2(a2.x + a3.x, a2.y + a3.y);
;         s[phys(p0 + 3 * q)] = cmul(make_float2(a2.x - a3.x, a2.y - a3.y), t2);
;       }
.LBB0_134:
	v_add_u32_e32 v6, s16, v3
	v_and_b32_e32 v7, s15, v6
	v_ashrrev_i32_e32 v8, s0, v6
	v_add_u32_e32 v9, 0x200, v6
	v_add_u32_e32 v10, 0x400, v6
	v_add_u32_e32 v6, 0x600, v6
	v_lshlrev_b32_e32 v8, 2, v8
	v_cvt_f32_u32_e32 v11, v7
	v_and_b32_e32 v12, s15, v9
	v_ashrrev_i32_e32 v9, s0, v9
	v_and_b32_e32 v13, s15, v10
	v_ashrrev_i32_e32 v10, s0, v10
	v_and_b32_e32 v14, s15, v6
	v_ashrrev_i32_e32 v6, s0, v6
	v_lshl_add_u32 v15, v8, s0, v7
	v_or_b32_e32 v16, 2, v8
	v_or_b32_e32 v8, 3, v8
	v_lshlrev_b32_e32 v9, 2, v9
	v_cvt_f32_u32_e32 v17, v12
	v_lshlrev_b32_e32 v10, 2, v10
	v_lshlrev_b32_e32 v6, 2, v6
	v_ashrrev_i32_e32 v20, 4, v15
	v_add_lshl_u32 v35, v20, v15, 3
	v_add_u32_e32 v15, s14, v15
	v_lshl_add_u32 v16, v16, s0, v7
	v_lshl_add_u32 v7, v8, s0, v7
	v_lshl_add_u32 v8, v9, s0, v12
	v_or_b32_e32 v22, 2, v9
	v_or_b32_e32 v9, 3, v9
	v_lshl_add_u32 v23, v10, s0, v13
	v_or_b32_e32 v24, 2, v10
	v_or_b32_e32 v10, 3, v10
	v_lshl_add_u32 v25, v6, s0, v14
	v_or_b32_e32 v26, 2, v6
	v_or_b32_e32 v6, 3, v6
	v_ashrrev_i32_e32 v27, 4, v15
	v_cvt_f32_u32_e32 v18, v13
	v_cvt_f32_u32_e32 v19, v14
	v_lshlrev_b32_e32 v15, 3, v15
	v_ashrrev_i32_e32 v28, 4, v16
	v_ashrrev_i32_e32 v29, 4, v7
	v_ashrrev_i32_e32 v30, 4, v8
	v_lshlrev_b32_e32 v31, 3, v8
	v_add_u32_e32 v8, s14, v8
	v_lshl_add_u32 v22, v22, s0, v12
	v_lshl_add_u32 v9, v9, s0, v12
	v_ashrrev_i32_e32 v12, 4, v23
	v_lshlrev_b32_e32 v32, 3, v23
	v_add_u32_e32 v23, s14, v23
	v_lshl_add_u32 v24, v24, s0, v13
	v_lshl_add_u32 v10, v10, s0, v13
	v_ashrrev_i32_e32 v13, 4, v25
	v_lshlrev_b32_e32 v33, 3, v25
	v_add_u32_e32 v25, s14, v25
	v_lshl_add_u32 v26, v26, s0, v14
	v_lshl_add_u32 v6, v6, s0, v14
	v_mul_f32_e32 v11, v5, v11
	v_lshlrev_b32_e32 v14, 3, v27
	v_lshlrev_b32_e32 v16, 3, v16
	v_lshlrev_b32_e32 v7, 3, v7
	v_lshlrev_b32_e32 v20, 3, v28
	v_lshlrev_b32_e32 v21, 3, v29
	v_lshlrev_b32_e32 v27, 3, v30
	v_ashrrev_i32_e32 v28, 4, v8
	v_lshlrev_b32_e32 v29, 3, v8
	v_ashrrev_i32_e32 v8, 4, v22
	v_ashrrev_i32_e32 v30, 4, v9
	v_lshlrev_b32_e32 v34, 3, v9
	v_lshlrev_b32_e32 v9, 3, v12
	v_ashrrev_i32_e32 v12, 4, v23
	v_ashrrev_i32_e32 v37, 4, v10
	v_lshlrev_b32_e32 v38, 3, v10
	v_lshlrev_b32_e32 v10, 3, v13
	v_ashrrev_i32_e32 v13, 4, v25
	v_fract_f32_e32 v11, v11
	v_add3_u32 v45, 0, v14, v15
	v_ashrrev_i32_e32 v36, 4, v24
	v_ashrrev_i32_e32 v40, 4, v6
	v_lshlrev_b32_e32 v41, 3, v6
	v_add3_u32 v47, 0, v20, v16
	v_add3_u32 v50, 0, v21, v7
	ds_read_b64 v[6:7], v35
	v_mul_f32_e32 v16, v5, v17
	v_add3_u32 v51, 0, v27, v31
	v_lshlrev_b32_e32 v20, 3, v8
	v_add3_u32 v52, 0, v9, v32
	v_lshlrev_b32_e32 v27, 3, v12
	v_add3_u32 v53, 0, v10, v33
	v_lshlrev_b32_e32 v31, 3, v13
	v_cos_f32_e32 v8, v11
	v_sin_f32_e32 v9, v11
	ds_read_b64 v[10:11], v45
	ds_read_b64 v[12:13], v47
	ds_read_b64 v[14:15], v50
	v_ashrrev_i32_e32 v39, 4, v26
	v_lshlrev_b32_e32 v17, 3, v28
	v_lshlrev_b32_e32 v28, 3, v36
	v_fract_f32_e32 v36, v16
	v_lshlrev_b32_e32 v32, 3, v39
	v_add3_u32 v39, 0, v17, v29
	v_cos_f32_e32 v16, v36
	v_sin_f32_e32 v17, v36
	v_lshlrev_b32_e32 v24, 3, v24
	v_lshlrev_b32_e32 v25, 3, v25
	v_lshlrev_b32_e32 v21, 3, v30
	v_lshlrev_b32_e32 v30, 3, v37
	v_lshlrev_b32_e32 v22, 3, v22
	v_lshlrev_b32_e32 v23, 3, v23
	v_lshlrev_b32_e32 v26, 3, v26
	v_lshlrev_b32_e32 v33, 3, v40
	v_add3_u32 v57, 0, v28, v24
	v_add3_u32 v58, 0, v30, v38
	v_add3_u32 v59, 0, v31, v25
	v_mul_f32_e64 v25, v8, -v9
	v_mov_b32_e32 v24, v9
	s_waitcnt lgkmcnt(1)
	v_pk_add_f32 v[28:29], v[6:7], v[12:13] neg_lo:[0,1] neg_hi:[0,1]
	s_waitcnt lgkmcnt(0)
	v_pk_add_f32 v[30:31], v[10:11], v[14:15] neg_lo:[0,1] neg_hi:[0,1]
	v_pk_add_f32 v[6:7], v[6:7], v[12:13]
	v_pk_add_f32 v[10:11], v[10:11], v[14:15]
	v_add3_u32 v54, 0, v20, v22
	v_add3_u32 v56, 0, v27, v23
	v_add3_u32 v60, 0, v32, v26
	v_add3_u32 v61, 0, v33, v41
	v_pk_mul_f32 v[22:23], v[8:9], v[8:9]
	v_add_f32_e32 v26, v25, v25
	v_mul_f32_e64 v9, v16, -v17
	v_pk_mul_f32 v[40:41], v[24:25], v[28:29] op_sel_hi:[0,1]
	v_xor_b32_e32 v43, 0x80000000, v30
	v_mov_b32_e32 v42, v31
	v_pk_mul_f32 v[24:25], v[24:25], v[30:31] op_sel_hi:[0,1]
	v_pk_add_f32 v[30:31], v[6:7], v[10:11]
	v_pk_add_f32 v[6:7], v[6:7], v[10:11] neg_lo:[0,1] neg_hi:[0,1]
	v_pk_add_f32 v[12:13], v[22:23], v[22:23] op_sel:[0,1] op_sel_hi:[0,1] neg_lo:[0,1] neg_hi:[0,1]
	v_add_f32_e32 v10, v9, v9
	v_pk_fma_f32 v[48:49], v[28:29], v[8:9], v[40:41] op_sel:[0,0,1] op_sel_hi:[1,1,0]
	v_pk_fma_f32 v[28:29], v[28:29], v[8:9], v[40:41] op_sel:[0,0,1] op_sel_hi:[1,0,0] neg_lo:[0,0,1] neg_hi:[0,0,1]
	v_pk_fma_f32 v[8:9], v[8:9], v[42:43], v[24:25] op_sel_hi:[0,1,1] neg_lo:[0,0,1] neg_hi:[0,0,1]
	v_pk_mul_f32 v[24:25], v[26:27], v[6:7] op_sel_hi:[0,1]
	v_mov_b32_e32 v49, v29
	v_pk_fma_f32 v[28:29], v[12:13], v[6:7], v[24:25] op_sel:[0,0,1] op_sel_hi:[1,1,0] neg_lo:[0,0,1] neg_hi:[0,0,1]
	v_pk_fma_f32 v[6:7], v[12:13], v[6:7], v[24:25] op_sel:[0,0,1] op_sel_hi:[1,1,0]
	ds_write_b64 v35, v[30:31]
	v_mov_b32_e32 v29, v7
	v_pk_add_f32 v[6:7], v[48:49], v[8:9]
	v_pk_add_f32 v[8:9], v[48:49], v[8:9] neg_lo:[0,1] neg_hi:[0,1]
	ds_write_b64 v45, v[28:29]
	ds_write_b64 v47, v[6:7]
	v_pk_mul_f32 v[6:7], v[26:27], v[8:9] op_sel_hi:[0,1]
	v_pk_fma_f32 v[24:25], v[12:13], v[8:9], v[6:7] op_sel:[0,0,1] op_sel_hi:[1,1,0] neg_lo:[0,0,1] neg_hi:[0,0,1]
	v_pk_fma_f32 v[6:7], v[12:13], v[8:9], v[6:7] op_sel:[0,0,1] op_sel_hi:[1,1,0]
	v_mul_f32_e32 v18, v5, v18
	v_mov_b32_e32 v25, v7
	ds_write_b64 v50, v[24:25]
	v_add3_u32 v55, 0, v21, v34
	ds_read_b64 v[6:7], v51
	ds_read_b64 v[8:9], v39
	ds_read_b64 v[12:13], v54
	ds_read_b64 v[24:25], v55
	v_mul_f32_e32 v19, v5, v19
	v_fract_f32_e32 v20, v18
	v_fract_f32_e32 v21, v19
	v_cos_f32_e32 v18, v20
	v_sin_f32_e32 v19, v20
	v_mov_b32_e32 v22, v17
	s_waitcnt lgkmcnt(1)
; DI float sin_t(float turns) { return __builtin_amdgcn_sinf(__builtin_amdgcn_fractf(turns)); }
; DI float cos_t(float turns) { return __builtin_amdgcn_cosf(__builtin_amdgcn_fractf(turns)); }
; DI float2 cmul(float2 a, float2 b) { return make_float2(a.x * b.x - a.y * b.y, a.x * b.y + a.y * b.x); }
; template <int N, bool INV>
; DI void fft_lds(float2* s) {
;     ...
;       for (int it = 0; it < N / 4 / NT; ++it) {
;         int idx = tid + it * NT;
;         int j = idx & (q - 1), blk = idx >> lq;
;         int p0 = blk * 4 * q + j;
;         float f = (float)j * inv4q;
;         float2 t1 = make_float2(cos_t(f), -sin_t(f));
;         float2 t2 = cmul(t1, t1);
;         float2 x0 = s[phys(p0)], x1 = s[phys(p0 + q)], x2 = s[phys(p0 + 2 * q)], x3 = s[phys(p0 + 3 * q)];
;         float2 a0 = make_float2(x0.x + x2.x, x0.y + x2.y);
;         float2 a2 = cmul(make_float2(x0.x - x2.x, x0.y - x2.y), t1);
;         float2 a1 = make_float2(x1.x + x3.x, x1.y + x3.y);
;         float2 d3 = make_float2(x1.x - x3.x, x1.y - x3.y);
;         float2 a3 = cmul(make_float2(d3.y, -d3.x), t1);
;         s[phys(p0)] = make_float2(a0.x + a1.x, a0.y + a1.y);
;         s[phys(p0 + q)] = cmul(make_float2(a0.x - a1.x, a0.y - a1.y), t2);
;         s[phys(p0 + 2 * q)] = make_float2(a2.x + a3.x, a2.y + a3.y);
;         s[phys(p0 + 3 * q)] = cmul(make_float2(a2.x - a3.x, a2.y - a3.y), t2);
;       }
; DI void filter_phase(const P& p, unsigned char* lds) {
;     ...
;         for (int i = tid; i < 16384; i += NT) { float2 v = s[phys(i)]; dst[i] = make_float2(v.x * inv, v.y * inv); }
	v_pk_add_f32 v[26:27], v[6:7], v[12:13] neg_lo:[0,1] neg_hi:[0,1]
	s_waitcnt lgkmcnt(0)
	v_pk_add_f32 v[28:29], v[8:9], v[24:25] neg_lo:[0,1] neg_hi:[0,1]
	v_pk_add_f32 v[6:7], v[6:7], v[12:13]
	v_pk_add_f32 v[8:9], v[8:9], v[24:25]
	v_pk_mul_f32 v[14:15], v[16:17], v[16:17]
	v_mul_f32_e64 v17, v18, -v19
	v_pk_mul_f32 v[12:13], v[22:23], v[26:27] op_sel_hi:[0,1]
	v_xor_b32_e32 v25, 0x80000000, v28
	v_mov_b32_e32 v24, v29
	v_pk_mul_f32 v[22:23], v[22:23], v[28:29] op_sel_hi:[0,1]
	v_pk_add_f32 v[28:29], v[6:7], v[8:9]
	v_pk_add_f32 v[6:7], v[6:7], v[8:9] neg_lo:[0,1] neg_hi:[0,1]
	v_pk_add_f32 v[14:15], v[14:15], v[14:15] op_sel:[0,1] op_sel_hi:[0,1] neg_lo:[0,1] neg_hi:[0,1]
	v_add_f32_e32 v44, v17, v17
	v_pk_fma_f32 v[8:9], v[26:27], v[16:17], v[12:13] op_sel:[0,0,1] op_sel_hi:[1,1,0]
	v_pk_fma_f32 v[12:13], v[26:27], v[16:17], v[12:13] op_sel:[0,0,1] op_sel_hi:[1,0,0] neg_lo:[0,0,1] neg_hi:[0,0,1]
	v_pk_fma_f32 v[16:17], v[16:17], v[24:25], v[22:23] op_sel_hi:[0,1,1] neg_lo:[0,0,1] neg_hi:[0,0,1]
	v_pk_mul_f32 v[22:23], v[10:11], v[6:7] op_sel_hi:[0,1]
	v_mov_b32_e32 v9, v13
	v_pk_fma_f32 v[12:13], v[14:15], v[6:7], v[22:23] op_sel:[0,0,1] op_sel_hi:[1,1,0] neg_lo:[0,0,1] neg_hi:[0,0,1]
	v_pk_fma_f32 v[6:7], v[14:15], v[6:7], v[22:23] op_sel:[0,0,1] op_sel_hi:[1,1,0]
	ds_write_b64 v51, v[28:29]
	v_mov_b32_e32 v13, v7
	v_pk_add_f32 v[6:7], v[8:9], v[16:17]
	v_pk_add_f32 v[8:9], v[8:9], v[16:17] neg_lo:[0,1] neg_hi:[0,1]
	ds_write_b64 v39, v[12:13]
	ds_write_b64 v54, v[6:7]
	v_pk_mul_f32 v[6:7], v[10:11], v[8:9] op_sel_hi:[0,1]
	v_pk_fma_f32 v[10:11], v[14:15], v[8:9], v[6:7] op_sel:[0,0,1] op_sel_hi:[1,1,0] neg_lo:[0,0,1] neg_hi:[0,0,1]
	v_pk_fma_f32 v[6:7], v[14:15], v[8:9], v[6:7] op_sel:[0,0,1] op_sel_hi:[1,1,0]
	v_cos_f32_e32 v20, v21
	v_mov_b32_e32 v11, v7
	ds_write_b64 v55, v[10:11]
	ds_read_b64 v[6:7], v52
	ds_read_b64 v[8:9], v56
	ds_read_b64 v[10:11], v57
	ds_read_b64 v[12:13], v58
	v_sin_f32_e32 v21, v21
	v_mov_b32_e32 v34, v19
	v_pk_mul_f32 v[32:33], v[18:19], v[18:19]
	s_waitcnt lgkmcnt(1)
	v_pk_add_f32 v[14:15], v[6:7], v[10:11] neg_lo:[0,1] neg_hi:[0,1]
	s_waitcnt lgkmcnt(0)
	v_pk_add_f32 v[16:17], v[8:9], v[12:13] neg_lo:[0,1] neg_hi:[0,1]
	v_pk_add_f32 v[6:7], v[6:7], v[10:11]
	v_pk_add_f32 v[8:9], v[8:9], v[12:13]
	v_mul_f32_e64 v19, v20, -v21
	v_pk_mul_f32 v[10:11], v[34:35], v[14:15] op_sel_hi:[0,1]
	v_pk_add_f32 v[22:23], v[6:7], v[8:9]
	v_pk_add_f32 v[6:7], v[6:7], v[8:9] neg_lo:[0,1] neg_hi:[0,1]
	v_pk_add_f32 v[32:33], v[32:33], v[32:33] op_sel:[0,1] op_sel_hi:[0,1] neg_lo:[0,1] neg_hi:[0,1]
	v_xor_b32_e32 v13, 0x80000000, v16
	v_mov_b32_e32 v12, v17
	v_pk_mul_f32 v[16:17], v[34:35], v[16:17] op_sel_hi:[0,1]
	v_pk_fma_f32 v[8:9], v[14:15], v[18:19], v[10:11] op_sel:[0,0,1] op_sel_hi:[1,1,0]
	v_pk_fma_f32 v[10:11], v[14:15], v[18:19], v[10:11] op_sel:[0,0,1] op_sel_hi:[1,0,0] neg_lo:[0,0,1] neg_hi:[0,0,1]
	v_pk_mul_f32 v[14:15], v[44:45], v[6:7] op_sel_hi:[0,1]
	v_pk_fma_f32 v[12:13], v[18:19], v[12:13], v[16:17] op_sel_hi:[0,1,1] neg_lo:[0,0,1] neg_hi:[0,0,1]
	v_mov_b32_e32 v9, v11
	v_pk_fma_f32 v[10:11], v[32:33], v[6:7], v[14:15] op_sel:[0,0,1] op_sel_hi:[1,1,0] neg_lo:[0,0,1] neg_hi:[0,0,1]
	v_pk_fma_f32 v[6:7], v[32:33], v[6:7], v[14:15] op_sel:[0,0,1] op_sel_hi:[1,1,0]
	ds_write_b64 v52, v[22:23]
	v_mov_b32_e32 v11, v7
	v_pk_add_f32 v[6:7], v[8:9], v[12:13]
	v_pk_add_f32 v[8:9], v[8:9], v[12:13] neg_lo:[0,1] neg_hi:[0,1]
	ds_write_b64 v56, v[10:11]
	ds_write_b64 v57, v[6:7]
	v_pk_mul_f32 v[6:7], v[44:45], v[8:9] op_sel_hi:[0,1]
	v_pk_fma_f32 v[10:11], v[32:33], v[8:9], v[6:7] op_sel:[0,0,1] op_sel_hi:[1,1,0] neg_lo:[0,0,1] neg_hi:[0,0,1]
	v_pk_fma_f32 v[6:7], v[32:33], v[8:9], v[6:7] op_sel:[0,0,1] op_sel_hi:[1,1,0]
	v_mov_b32_e32 v38, v21
	v_mov_b32_e32 v11, v7
	ds_write_b64 v58, v[10:11]
	ds_read_b64 v[6:7], v53
	ds_read_b64 v[8:9], v59
	ds_read_b64 v[10:11], v60
	ds_read_b64 v[12:13], v61
	v_pk_mul_f32 v[36:37], v[20:21], v[20:21]
	v_add_f32_e32 v46, v19, v19
	v_pk_add_f32 v[36:37], v[36:37], v[36:37] op_sel:[0,1] op_sel_hi:[0,1] neg_lo:[0,1] neg_hi:[0,1]
	s_waitcnt lgkmcnt(1)
	v_pk_add_f32 v[14:15], v[6:7], v[10:11] neg_lo:[0,1] neg_hi:[0,1]
	s_waitcnt lgkmcnt(0)
	v_pk_add_f32 v[16:17], v[8:9], v[12:13] neg_lo:[0,1] neg_hi:[0,1]
	v_pk_add_f32 v[6:7], v[6:7], v[10:11]
	v_pk_add_f32 v[8:9], v[8:9], v[12:13]
	v_pk_mul_f32 v[10:11], v[38:39], v[14:15] op_sel_hi:[0,1]
	v_pk_add_f32 v[18:19], v[6:7], v[8:9]
	v_pk_add_f32 v[6:7], v[6:7], v[8:9] neg_lo:[0,1] neg_hi:[0,1]
	v_xor_b32_e32 v13, 0x80000000, v16
	v_mov_b32_e32 v12, v17
	v_pk_mul_f32 v[16:17], v[38:39], v[16:17] op_sel_hi:[0,1]
	v_pk_fma_f32 v[8:9], v[14:15], v[20:21], v[10:11] op_sel:[0,0,1] op_sel_hi:[1,1,0]
	v_pk_fma_f32 v[10:11], v[14:15], v[20:21], v[10:11] op_sel:[0,0,1] op_sel_hi:[1,0,0] neg_lo:[0,0,1] neg_hi:[0,0,1]
	v_pk_mul_f32 v[14:15], v[46:47], v[6:7] op_sel_hi:[0,1]
	v_pk_fma_f32 v[12:13], v[20:21], v[12:13], v[16:17] op_sel_hi:[0,1,1] neg_lo:[0,0,1] neg_hi:[0,0,1]
	v_mov_b32_e32 v9, v11
	v_pk_fma_f32 v[10:11], v[36:37], v[6:7], v[14:15] op_sel:[0,0,1] op_sel_hi:[1,1,0] neg_lo:[0,0,1] neg_hi:[0,0,1]
	v_pk_fma_f32 v[6:7], v[36:37], v[6:7], v[14:15] op_sel:[0,0,1] op_sel_hi:[1,1,0]
	ds_write_b64 v53, v[18:19]
	v_mov_b32_e32 v11, v7
	v_pk_add_f32 v[6:7], v[8:9], v[12:13]
	v_pk_add_f32 v[8:9], v[8:9], v[12:13] neg_lo:[0,1] neg_hi:[0,1]
	ds_write_b64 v59, v[10:11]
	ds_write_b64 v60, v[6:7]
	v_pk_mul_f32 v[6:7], v[46:47], v[8:9] op_sel_hi:[0,1]
	s_addk_i32 s16, 0x800
	v_pk_fma_f32 v[10:11], v[36:37], v[8:9], v[6:7] op_sel:[0,0,1] op_sel_hi:[1,1,0] neg_lo:[0,0,1] neg_hi:[0,0,1]
	v_pk_fma_f32 v[6:7], v[36:37], v[8:9], v[6:7] op_sel:[0,0,1] op_sel_hi:[1,1,0]
	s_cmpk_eq_i32 s16, 0x1000
	v_mov_b32_e32 v11, v7
	ds_write_b64 v61, v[10:11]
	s_cbranch_scc0 .LBB0_134
	s_add_i32 s14, s0, -2
	s_cmp_eq_u32 s0, 0
	s_mov_b32 s0, s14
	s_cbranch_scc0 .LBB0_133
	s_movk_i32 s0, 0x4000
	v_cmp_gt_i32_e32 vcc, s0, v2
	s_waitcnt lgkmcnt(0)
	s_barrier
	s_and_saveexec_b64 s[14:15], vcc
	s_cbranch_execz .LBB0_102
	v_max_i32_e32 v3, 0x3e00, v2
	v_sub_u32_e32 v3, v3, v2
	v_add_u32_e32 v9, 0x1ff, v3
	v_lshrrev_b32_e32 v6, 9, v9
	s_movk_i32 s0, 0x1ff
	v_add_u32_e32 v8, 1, v6
	v_cmp_lt_u32_e32 vcc, s0, v9
	s_mov_b64 s[18:19], -1
	s_and_saveexec_b64 s[16:17], vcc
	s_cbranch_execz .LBB0_148
	s_or_b32 s18, s51, s44
	s_ashr_i32 s19, s18, 31
	s_lshl_b64 s[18:19], s[18:19], 25
	v_add_u32_e32 v6, -1, v6
	s_add_u32 s18, s45, s18
	v_add_u32_e32 v3, 0x200, v2
	v_lshrrev_b32_e32 v7, 1, v6
	s_addc_u32 s19, s46, s19
	v_mov_b32_e32 v5, v4
	v_add_u32_e32 v9, 1, v7
	v_cmp_lt_u32_e32 vcc, 13, v6
	v_mov_b32_e32 v12, 0
	v_mov_b64_e32 v[6:7], v[2:3]
	s_and_saveexec_b64 s[20:21], vcc
	s_cbranch_execz .LBB0_142
	v_and_b32_e32 v10, -8, v9
	v_lshl_add_u32 v11, v2, 3, 0
	s_mov_b32 s0, 0
	s_mov_b64 s[22:23], 0
	v_mov_b64_e32 v[6:7], v[2:3]

; DI float sin_t(float turns) { return __builtin_amdgcn_sinf(__builtin_amdgcn_fractf(turns)); }
; DI float cos_t(float turns) { return __builtin_amdgcn_cosf(__builtin_amdgcn_fractf(turns)); }
; DI float2 cmul(float2 a, float2 b) { return make_float2(a.x * b.x - a.y * b.y, a.x * b.y + a.y * b.x); }
; template <int N, bool INV>
; DI void fft_lds(float2* s) {
;     ...
;     for (int lq = (LG & 1) ? LG - 3 : LG - 2; lq >= 0; lq -= 2) {
;       const int q = 1 << lq;
;       __syncthreads();
;       const float inv4q = 1.0f / (float)(4 * q);
; #pragma unroll 4
;       for (int it = 0; it < N / 4 / NT; ++it) {
;         int idx = tid + it * NT;
;         int j = idx & (q - 1), blk = idx >> lq;
;         int p0 = blk * 4 * q + j;
;         float f = (float)j * inv4q;
;         float2 t1 = make_float2(cos_t(f), -sin_t(f));
;         float2 t2 = cmul(t1, t1);
;         float2 x0 = s[phys(p0)], x1 = s[phys(p0 + q)], x2 = s[phys(p0 + 2 * q)], x3 = s[phys(p0 + 3 * q)];
;         float2 a0 = make_float2(x0.x + x2.x, x0.y + x2.y);
;         float2 a2 = cmul(make_float2(x0.x - x2.x, x0.y - x2.y), t1);
;         float2 a1 = make_float2(x1.x + x3.x, x1.y + x3.y);
;         float2 d3 = make_float2(x1.x - x3.x, x1.y - x3.y);
;         float2 a3 = cmul(make_float2(d3.y, -d3.x), t1);
;         s[phys(p0)] = make_float2(a0.x + a1.x, a0.y + a1.y);
;         s[phys(p0 + q)] = cmul(make_float2(a0.x - a1.x, a0.y - a1.y), t2);
;         s[phys(p0 + 2 * q)] = make_float2(a2.x + a3.x, a2.y + a3.y);
;         s[phys(p0 + 3 * q)] = cmul(make_float2(a2.x - a3.x, a2.y - a3.y), t2);
;       }
.LBB0_367:
	s_lshl_b32 s10, 4, s0
	v_cvt_f32_u32_e32 v5, s10
	s_lshl_b32 s1, 1, s0
	s_waitcnt lgkmcnt(0)
	s_barrier
	v_div_scale_f32 v6, s[10:11], v5, v5, 1.0
	v_rcp_f32_e32 v7, v6
	s_bfm_b32 s10, s0, 0
	v_and_b32_e32 v13, s10, v1
	v_fma_f32 v8, -v6, v7, 1.0
	v_fmac_f32_e32 v7, v8, v7
	v_div_scale_f32 v8, vcc, 1.0, v5, 1.0
	v_mul_f32_e32 v9, v8, v7
	v_fma_f32 v12, -v6, v9, v8
	v_fmac_f32_e32 v9, v12, v7
	v_fma_f32 v6, -v6, v9, v8
	v_div_fmas_f32 v6, v6, v7, v9
	v_div_fixup_f32 v5, v6, v5, 1.0
	v_ashrrev_i32_e32 v6, s0, v1
	v_lshlrev_b32_e32 v14, 2, v6
	v_lshl_add_u32 v15, v14, s0, v13
	v_ashrrev_i32_e32 v17, 4, v15
	v_add_lshl_u32 v17, v17, v15, 3
	v_add_u32_e32 v15, s1, v15
	v_cvt_f32_u32_e32 v6, v13
	v_ashrrev_i32_e32 v19, 4, v15
	v_add_lshl_u32 v19, v19, v15, 3
	v_or_b32_e32 v15, 2, v14
	v_or_b32_e32 v14, 3, v14
	v_lshl_add_u32 v15, v15, s0, v13
	v_lshl_add_u32 v13, v14, s0, v13
	v_mul_f32_e32 v6, v5, v6
	v_ashrrev_i32_e32 v20, 4, v15
	v_ashrrev_i32_e32 v14, 4, v13
	v_fract_f32_e32 v7, v6
	v_add_lshl_u32 v23, v20, v15, 3
	v_add_lshl_u32 v29, v14, v13, 3
	v_cos_f32_e32 v6, v7
	v_sin_f32_e32 v7, v7
	ds_read_b64 v[14:15], v17
	ds_read_b64 v[20:21], v19
	ds_read_b64 v[26:27], v23
	ds_read_b64 v[30:31], v29
	v_mov_b32_e32 v34, v7
	v_mul_f32_e64 v12, v6, -v7
	v_pk_mul_f32 v[8:9], v[6:7], v[6:7]
	s_waitcnt lgkmcnt(1)
	v_pk_add_f32 v[32:33], v[14:15], v[26:27] neg_lo:[0,1] neg_hi:[0,1]
	v_pk_add_f32 v[14:15], v[14:15], v[26:27]
	v_pk_mul_f32 v[36:37], v[34:35], v[32:33] op_sel_hi:[0,1]
	v_pk_fma_f32 v[40:41], v[6:7], v[32:33], v[36:37] op_sel:[0,0,1] op_sel_hi:[1,1,0]
	v_pk_fma_f32 v[32:33], v[6:7], v[32:33], v[36:37] op_sel:[0,0,1] op_sel_hi:[0,1,0] neg_lo:[0,0,1] neg_hi:[0,0,1]
	v_mov_b32_e32 v41, v33
	s_waitcnt lgkmcnt(0)
	v_pk_add_f32 v[32:33], v[20:21], v[30:31] neg_lo:[0,1] neg_hi:[0,1]
	v_pk_add_f32 v[20:21], v[20:21], v[30:31]
	v_add_f32_e32 v12, v12, v12
	v_pk_add_f32 v[26:27], v[14:15], v[20:21]
	v_pk_add_f32 v[14:15], v[14:15], v[20:21] neg_lo:[0,1] neg_hi:[0,1]
	v_xor_b32_e32 v37, 0x80000000, v32
	v_mov_b32_e32 v36, v33
	v_pk_mul_f32 v[32:33], v[34:35], v[32:33] op_sel_hi:[0,1]
	v_pk_mul_f32 v[20:21], v[12:13], v[14:15] op_sel_hi:[0,1]
	v_pk_add_f32 v[8:9], v[8:9], v[8:9] op_sel:[0,1] op_sel_hi:[0,1] neg_lo:[0,1] neg_hi:[0,1]
	v_pk_fma_f32 v[6:7], v[6:7], v[36:37], v[32:33] op_sel_hi:[0,1,1] neg_lo:[0,0,1] neg_hi:[0,0,1]
	ds_write_b64 v17, v[26:27]
	v_pk_fma_f32 v[26:27], v[8:9], v[14:15], v[20:21] op_sel:[0,0,1] op_sel_hi:[1,1,0] neg_lo:[0,0,1] neg_hi:[0,0,1]
	v_pk_fma_f32 v[14:15], v[8:9], v[14:15], v[20:21] op_sel:[0,0,1] op_sel_hi:[1,1,0]
	s_nop 0
	v_mov_b32_e32 v27, v15
	v_pk_add_f32 v[14:15], v[40:41], v[6:7]
	v_pk_add_f32 v[6:7], v[40:41], v[6:7] neg_lo:[0,1] neg_hi:[0,1]
	ds_write_b64 v19, v[26:27]
	v_pk_mul_f32 v[12:13], v[12:13], v[6:7] op_sel_hi:[0,1]
	ds_write_b64 v23, v[14:15]
	v_pk_fma_f32 v[14:15], v[8:9], v[6:7], v[12:13] op_sel:[0,0,1] op_sel_hi:[1,1,0] neg_lo:[0,0,1] neg_hi:[0,0,1]
	v_pk_fma_f32 v[6:7], v[8:9], v[6:7], v[12:13] op_sel:[0,0,1] op_sel_hi:[1,1,0]
	v_and_b32_e32 v13, s10, v2
	v_mov_b32_e32 v15, v7
	v_ashrrev_i32_e32 v6, s0, v2
	ds_write_b64 v29, v[14:15]
	v_lshlrev_b32_e32 v14, 2, v6
	v_lshl_add_u32 v15, v14, s0, v13
	v_ashrrev_i32_e32 v17, 4, v15
	v_add_lshl_u32 v17, v17, v15, 3
	v_add_u32_e32 v15, s1, v15
	v_cvt_f32_u32_e32 v6, v13
	v_ashrrev_i32_e32 v19, 4, v15
	v_add_lshl_u32 v19, v19, v15, 3
	v_or_b32_e32 v15, 2, v14
	v_or_b32_e32 v14, 3, v14
	v_lshl_add_u32 v15, v15, s0, v13
	v_lshl_add_u32 v13, v14, s0, v13
	v_mul_f32_e32 v6, v5, v6
	v_ashrrev_i32_e32 v20, 4, v15
	v_ashrrev_i32_e32 v14, 4, v13
	v_fract_f32_e32 v7, v6
	v_add_lshl_u32 v23, v20, v15, 3
	v_add_lshl_u32 v29, v14, v13, 3
	v_cos_f32_e32 v6, v7
	v_sin_f32_e32 v7, v7
	ds_read_b64 v[14:15], v17
	ds_read_b64 v[20:21], v19
	ds_read_b64 v[26:27], v23
	ds_read_b64 v[30:31], v29
	v_mov_b32_e32 v34, v7
	v_mul_f32_e64 v12, v6, -v7
	v_pk_mul_f32 v[8:9], v[6:7], v[6:7]
	s_waitcnt lgkmcnt(1)
	v_pk_add_f32 v[32:33], v[14:15], v[26:27] neg_lo:[0,1] neg_hi:[0,1]
	v_pk_add_f32 v[14:15], v[14:15], v[26:27]
	v_pk_mul_f32 v[36:37], v[34:35], v[32:33] op_sel_hi:[0,1]
	v_pk_fma_f32 v[40:41], v[6:7], v[32:33], v[36:37] op_sel:[0,0,1] op_sel_hi:[1,1,0]
	v_pk_fma_f32 v[32:33], v[6:7], v[32:33], v[36:37] op_sel:[0,0,1] op_sel_hi:[0,1,0] neg_lo:[0,0,1] neg_hi:[0,0,1]
	v_mov_b32_e32 v41, v33
	s_waitcnt lgkmcnt(0)
	v_pk_add_f32 v[32:33], v[20:21], v[30:31] neg_lo:[0,1] neg_hi:[0,1]
	v_pk_add_f32 v[20:21], v[20:21], v[30:31]
	v_add_f32_e32 v12, v12, v12
	v_pk_add_f32 v[26:27], v[14:15], v[20:21]
	v_pk_add_f32 v[14:15], v[14:15], v[20:21] neg_lo:[0,1] neg_hi:[0,1]
	v_xor_b32_e32 v37, 0x80000000, v32
	v_mov_b32_e32 v36, v33
	v_pk_mul_f32 v[32:33], v[34:35], v[32:33] op_sel_hi:[0,1]
	v_pk_mul_f32 v[20:21], v[12:13], v[14:15] op_sel_hi:[0,1]
	v_pk_add_f32 v[8:9], v[8:9], v[8:9] op_sel:[0,1] op_sel_hi:[0,1] neg_lo:[0,1] neg_hi:[0,1]
	v_pk_fma_f32 v[6:7], v[6:7], v[36:37], v[32:33] op_sel_hi:[0,1,1] neg_lo:[0,0,1] neg_hi:[0,0,1]
	ds_write_b64 v17, v[26:27]
	v_pk_fma_f32 v[26:27], v[8:9], v[14:15], v[20:21] op_sel:[0,0,1] op_sel_hi:[1,1,0] neg_lo:[0,0,1] neg_hi:[0,0,1]
	v_pk_fma_f32 v[14:15], v[8:9], v[14:15], v[20:21] op_sel:[0,0,1] op_sel_hi:[1,1,0]
	s_nop 0
	v_mov_b32_e32 v27, v15
	v_pk_add_f32 v[14:15], v[40:41], v[6:7]
	v_pk_add_f32 v[6:7], v[40:41], v[6:7] neg_lo:[0,1] neg_hi:[0,1]
	ds_write_b64 v19, v[26:27]
	v_pk_mul_f32 v[12:13], v[12:13], v[6:7] op_sel_hi:[0,1]
	ds_write_b64 v23, v[14:15]
	v_pk_fma_f32 v[14:15], v[8:9], v[6:7], v[12:13] op_sel:[0,0,1] op_sel_hi:[1,1,0] neg_lo:[0,0,1] neg_hi:[0,0,1]
	v_pk_fma_f32 v[6:7], v[8:9], v[6:7], v[12:13] op_sel:[0,0,1] op_sel_hi:[1,1,0]
	v_and_b32_e32 v13, s10, v3
	v_mov_b32_e32 v15, v7
	v_ashrrev_i32_e32 v6, s0, v3
	ds_write_b64 v29, v[14:15]
	v_lshlrev_b32_e32 v14, 2, v6
	v_lshl_add_u32 v15, v14, s0, v13
	v_ashrrev_i32_e32 v17, 4, v15
	v_add_lshl_u32 v17, v17, v15, 3
	v_add_u32_e32 v15, s1, v15
	v_cvt_f32_u32_e32 v6, v13
	v_ashrrev_i32_e32 v19, 4, v15
	v_add_lshl_u32 v19, v19, v15, 3
	v_or_b32_e32 v15, 2, v14
	v_or_b32_e32 v14, 3, v14
	v_lshl_add_u32 v15, v15, s0, v13
	v_lshl_add_u32 v13, v14, s0, v13
	v_mul_f32_e32 v6, v5, v6
	v_ashrrev_i32_e32 v20, 4, v15
	v_ashrrev_i32_e32 v14, 4, v13
	v_fract_f32_e32 v7, v6
	v_add_lshl_u32 v23, v20, v15, 3
	v_add_lshl_u32 v29, v14, v13, 3
	v_cos_f32_e32 v6, v7
	v_sin_f32_e32 v7, v7
	ds_read_b64 v[14:15], v17
	ds_read_b64 v[20:21], v19
	ds_read_b64 v[26:27], v23
	ds_read_b64 v[30:31], v29
	v_mov_b32_e32 v34, v7
	v_mul_f32_e64 v12, v6, -v7
	v_pk_mul_f32 v[8:9], v[6:7], v[6:7]
	s_waitcnt lgkmcnt(1)
; DI float sin_t(float turns) { return __builtin_amdgcn_sinf(__builtin_amdgcn_fractf(turns)); }
; DI float cos_t(float turns) { return __builtin_amdgcn_cosf(__builtin_amdgcn_fractf(turns)); }
; DI float2 cmul(float2 a, float2 b) { return make_float2(a.x * b.x - a.y * b.y, a.x * b.y + a.y * b.x); }
; template <int N, bool INV>
; DI void fft_lds(float2* s) {
;     ...
;       __syncthreads();
;       constexpr int h = N / 2;
; #pragma unroll 4
;       for (int j = tid; j < h; j += NT) {
;         float f = (float)j * (1.0f / N);
;         float2 w = make_float2(cos_t(f), -sin_t(f));
;         float2 a = s[phys(j)], b = s[phys(j + h)];
;         s[phys(j)] = make_float2(a.x + b.x, a.y + b.y);
;         s[phys(j + h)] = cmul(make_float2(a.x - b.x, a.y - b.y), w);
;       }
;     ...
;       for (int it = 0; it < N / 4 / NT; ++it) {
;         int idx = tid + it * NT;
;         int j = idx & (q - 1), blk = idx >> lq;
;         int p0 = blk * 4 * q + j;
;         float f = (float)j * inv4q;
;         float2 t1 = make_float2(cos_t(f), -sin_t(f));
;         float2 t2 = cmul(t1, t1);
;         float2 x0 = s[phys(p0)], x1 = s[phys(p0 + q)], x2 = s[phys(p0 + 2 * q)], x3 = s[phys(p0 + 3 * q)];
;         float2 a0 = make_float2(x0.x + x2.x, x0.y + x2.y);
;         float2 a2 = cmul(make_float2(x0.x - x2.x, x0.y - x2.y), t1);
;         float2 a1 = make_float2(x1.x + x3.x, x1.y + x3.y);
;         float2 d3 = make_float2(x1.x - x3.x, x1.y - x3.y);
;         float2 a3 = cmul(make_float2(d3.y, -d3.x), t1);
;         s[phys(p0)] = make_float2(a0.x + a1.x, a0.y + a1.y);
;         s[phys(p0 + q)] = cmul(make_float2(a0.x - a1.x, a0.y - a1.y), t2);
;         s[phys(p0 + 2 * q)] = make_float2(a2.x + a3.x, a2.y + a3.y);
;         s[phys(p0 + 3 * q)] = cmul(make_float2(a2.x - a3.x, a2.y - a3.y), t2);
;       }
	v_pk_add_f32 v[32:33], v[14:15], v[26:27] neg_lo:[0,1] neg_hi:[0,1]
	v_pk_add_f32 v[14:15], v[14:15], v[26:27]
	v_pk_mul_f32 v[36:37], v[34:35], v[32:33] op_sel_hi:[0,1]
	v_pk_fma_f32 v[40:41], v[6:7], v[32:33], v[36:37] op_sel:[0,0,1] op_sel_hi:[1,1,0]
	v_pk_fma_f32 v[32:33], v[6:7], v[32:33], v[36:37] op_sel:[0,0,1] op_sel_hi:[0,1,0] neg_lo:[0,0,1] neg_hi:[0,0,1]
	v_mov_b32_e32 v41, v33
	s_waitcnt lgkmcnt(0)
	v_pk_add_f32 v[32:33], v[20:21], v[30:31] neg_lo:[0,1] neg_hi:[0,1]
	v_pk_add_f32 v[20:21], v[20:21], v[30:31]
	v_add_f32_e32 v12, v12, v12
	v_pk_add_f32 v[26:27], v[14:15], v[20:21]
	v_pk_add_f32 v[14:15], v[14:15], v[20:21] neg_lo:[0,1] neg_hi:[0,1]
	v_xor_b32_e32 v37, 0x80000000, v32
	v_mov_b32_e32 v36, v33
	v_pk_mul_f32 v[32:33], v[34:35], v[32:33] op_sel_hi:[0,1]
	v_pk_mul_f32 v[20:21], v[12:13], v[14:15] op_sel_hi:[0,1]
	v_pk_add_f32 v[8:9], v[8:9], v[8:9] op_sel:[0,1] op_sel_hi:[0,1] neg_lo:[0,1] neg_hi:[0,1]
	v_pk_fma_f32 v[6:7], v[6:7], v[36:37], v[32:33] op_sel_hi:[0,1,1] neg_lo:[0,0,1] neg_hi:[0,0,1]
	ds_write_b64 v17, v[26:27]
	v_pk_fma_f32 v[26:27], v[8:9], v[14:15], v[20:21] op_sel:[0,0,1] op_sel_hi:[1,1,0] neg_lo:[0,0,1] neg_hi:[0,0,1]
	v_pk_fma_f32 v[14:15], v[8:9], v[14:15], v[20:21] op_sel:[0,0,1] op_sel_hi:[1,1,0]
	s_nop 0
	v_mov_b32_e32 v27, v15
	v_pk_add_f32 v[14:15], v[40:41], v[6:7]
	v_pk_add_f32 v[6:7], v[40:41], v[6:7] neg_lo:[0,1] neg_hi:[0,1]
	ds_write_b64 v19, v[26:27]
	v_pk_mul_f32 v[12:13], v[12:13], v[6:7] op_sel_hi:[0,1]
	ds_write_b64 v23, v[14:15]
	v_pk_fma_f32 v[14:15], v[8:9], v[6:7], v[12:13] op_sel:[0,0,1] op_sel_hi:[1,1,0] neg_lo:[0,0,1] neg_hi:[0,0,1]
	v_pk_fma_f32 v[6:7], v[8:9], v[6:7], v[12:13] op_sel:[0,0,1] op_sel_hi:[1,1,0]
	s_nop 0
	v_and_b32_e32 v6, s10, v4
	v_cvt_f32_u32_e32 v8, v6
	v_mov_b32_e32 v15, v7
	v_ashrrev_i32_e32 v7, s0, v4
	v_lshlrev_b32_e32 v7, 2, v7
	v_mul_f32_e32 v5, v5, v8
	v_fract_f32_e32 v5, v5
	v_cos_f32_e32 v8, v5
	v_sin_f32_e32 v9, v5
	ds_write_b64 v29, v[14:15]
	v_lshl_add_u32 v15, v7, s0, v6
	v_mul_f32_e64 v5, v8, -v9
	v_add_f32_e32 v14, v5, v5
	v_ashrrev_i32_e32 v5, 4, v15
	v_add_lshl_u32 v5, v5, v15, 3
	v_add_u32_e32 v15, s1, v15
	v_ashrrev_i32_e32 v17, 4, v15
	v_lshlrev_b32_e32 v17, 3, v17
	v_lshlrev_b32_e32 v15, 3, v15
	v_add3_u32 v15, 0, v17, v15
	v_or_b32_e32 v17, 2, v7
	v_or_b32_e32 v7, 3, v7
	v_lshl_add_u32 v17, v17, s0, v6
	v_lshl_add_u32 v6, v7, s0, v6
	v_ashrrev_i32_e32 v19, 4, v17
	v_ashrrev_i32_e32 v7, 4, v6
	v_lshlrev_b32_e32 v19, 3, v19
	v_lshlrev_b32_e32 v17, 3, v17
	v_lshlrev_b32_e32 v7, 3, v7
	v_lshlrev_b32_e32 v6, 3, v6
	v_add3_u32 v17, 0, v19, v17
	v_add3_u32 v19, 0, v7, v6
	ds_read_b64 v[6:7], v5
	ds_read_b64 v[20:21], v15
	ds_read_b64 v[26:27], v17
	ds_read_b64 v[30:31], v19
	v_mov_b32_e32 v34, v9
	v_pk_mul_f32 v[12:13], v[8:9], v[8:9]
	s_add_i32 s0, s0, -2
	s_waitcnt lgkmcnt(1)
	v_pk_add_f32 v[32:33], v[6:7], v[26:27] neg_lo:[0,1] neg_hi:[0,1]
	v_pk_add_f32 v[6:7], v[6:7], v[26:27]
	v_pk_mul_f32 v[36:37], v[34:35], v[32:33] op_sel_hi:[0,1]
	v_pk_fma_f32 v[40:41], v[8:9], v[32:33], v[36:37] op_sel:[0,0,1] op_sel_hi:[1,1,0]
	v_pk_fma_f32 v[32:33], v[8:9], v[32:33], v[36:37] op_sel:[0,0,1] op_sel_hi:[0,1,0] neg_lo:[0,0,1] neg_hi:[0,0,1]
	v_mov_b32_e32 v41, v33
	s_waitcnt lgkmcnt(0)
	v_pk_add_f32 v[32:33], v[20:21], v[30:31] neg_lo:[0,1] neg_hi:[0,1]
	v_pk_add_f32 v[20:21], v[20:21], v[30:31]
	v_xor_b32_e32 v37, 0x80000000, v32
	v_pk_add_f32 v[26:27], v[6:7], v[20:21]
	v_pk_add_f32 v[6:7], v[6:7], v[20:21] neg_lo:[0,1] neg_hi:[0,1]
	v_mov_b32_e32 v36, v33
	v_pk_mul_f32 v[32:33], v[34:35], v[32:33] op_sel_hi:[0,1]
	v_pk_mul_f32 v[20:21], v[14:15], v[6:7] op_sel_hi:[0,1]
	v_pk_add_f32 v[12:13], v[12:13], v[12:13] op_sel:[0,1] op_sel_hi:[0,1] neg_lo:[0,1] neg_hi:[0,1]
	v_pk_fma_f32 v[8:9], v[8:9], v[36:37], v[32:33] op_sel_hi:[0,1,1] neg_lo:[0,0,1] neg_hi:[0,0,1]
	ds_write_b64 v5, v[26:27]
	v_pk_fma_f32 v[26:27], v[12:13], v[6:7], v[20:21] op_sel:[0,0,1] op_sel_hi:[1,1,0] neg_lo:[0,0,1] neg_hi:[0,0,1]
	v_pk_fma_f32 v[6:7], v[12:13], v[6:7], v[20:21] op_sel:[0,0,1] op_sel_hi:[1,1,0]
	s_cmp_lg_u32 s0, -2
	v_mov_b32_e32 v27, v7
	v_pk_add_f32 v[6:7], v[40:41], v[8:9]
	ds_write_b64 v15, v[26:27]
	ds_write_b64 v17, v[6:7]
	v_pk_add_f32 v[6:7], v[40:41], v[8:9] neg_lo:[0,1] neg_hi:[0,1]
	s_nop 0
	v_pk_mul_f32 v[8:9], v[14:15], v[6:7] op_sel_hi:[0,1]
	v_pk_fma_f32 v[14:15], v[12:13], v[6:7], v[8:9] op_sel:[0,0,1] op_sel_hi:[1,1,0] neg_lo:[0,0,1] neg_hi:[0,0,1]
	v_pk_fma_f32 v[6:7], v[12:13], v[6:7], v[8:9] op_sel:[0,0,1] op_sel_hi:[1,1,0]
	s_nop 0
	v_mov_b32_e32 v15, v7
	ds_write_b64 v19, v[14:15]
	s_cbranch_scc1 .LBB0_367
	v_mov_b32_e32 v1, v215
	s_waitcnt lgkmcnt(0)
	s_barrier
	s_nop 0
	v_cmp_gt_i32_e32 vcc, s46, v1
	s_barrier
	s_and_saveexec_b64 s[0:1], vcc
	s_cbranch_execz .LBB0_376
	v_max_i32_e32 v2, 0xe00, v1
	v_sub_u32_e32 v2, v2, v1
	v_add_u32_e32 v3, 0x1ff, v2
	v_and_b32_e32 v2, 0x600, v3
	s_movk_i32 s10, 0x600
	v_cmp_ne_u32_e32 vcc, s10, v2
	v_mov_b32_e32 v2, v1
	s_and_saveexec_b64 s[10:11], vcc
	s_cbranch_execz .LBB0_373
	v_lshrrev_b32_e32 v2, 9, v3
	v_add_u32_e32 v2, 1, v2
	v_and_b32_e32 v2, 3, v2
	v_readlane_b32 s12, v254, 39
	v_sub_u32_e32 v5, 0, v2
	v_mov_b32_e32 v2, v1
	v_lshl_add_u32 v4, v1, 3, s12
	s_mov_b64 s[12:13], 0

; DI float sin_t(float turns) { return __builtin_amdgcn_sinf(__builtin_amdgcn_fractf(turns)); }
; DI float cos_t(float turns) { return __builtin_amdgcn_cosf(__builtin_amdgcn_fractf(turns)); }
; DI float2 cmul(float2 a, float2 b) { return make_float2(a.x * b.x - a.y * b.y, a.x * b.y + a.y * b.x); }
; template <int N, bool INV>
; DI void fft_lds(float2* s) {
;     ...
;     for (int lq = (LG & 1) ? LG - 3 : LG - 2; lq >= 0; lq -= 2) {
;       const int q = 1 << lq;
;       __syncthreads();
;       const float inv4q = 1.0f / (float)(4 * q);
; #pragma unroll 4
;       for (int it = 0; it < N / 4 / NT; ++it) {
;         int idx = tid + it * NT;
;         int j = idx & (q - 1), blk = idx >> lq;
;         int p0 = blk * 4 * q + j;
;         float f = (float)j * inv4q;
;         float2 t1 = make_float2(cos_t(f), -sin_t(f));
;         float2 t2 = cmul(t1, t1);
;         float2 x0 = s[phys(p0)], x1 = s[phys(p0 + q)], x2 = s[phys(p0 + 2 * q)], x3 = s[phys(p0 + 3 * q)];
;         float2 a0 = make_float2(x0.x + x2.x, x0.y + x2.y);
;         float2 a2 = cmul(make_float2(x0.x - x2.x, x0.y - x2.y), t1);
;         float2 a1 = make_float2(x1.x + x3.x, x1.y + x3.y);
;         float2 d3 = make_float2(x1.x - x3.x, x1.y - x3.y);
;         float2 a3 = cmul(make_float2(d3.y, -d3.x), t1);
;         s[phys(p0)] = make_float2(a0.x + a1.x, a0.y + a1.y);
;         s[phys(p0 + q)] = cmul(make_float2(a0.x - a1.x, a0.y - a1.y), t2);
;         s[phys(p0 + 2 * q)] = make_float2(a2.x + a3.x, a2.y + a3.y);
;         s[phys(p0 + 3 * q)] = cmul(make_float2(a2.x - a3.x, a2.y - a3.y), t2);
;       }
.LBB0_473:
	v_add_u32_e32 v3, s5, v1
	v_ashrrev_i32_e32 v4, s0, v3
	v_and_b32_e32 v9, s4, v3
	v_lshlrev_b32_e32 v10, 2, v4
	v_lshl_add_u32 v11, v10, s0, v9
	v_ashrrev_i32_e32 v12, 4, v11
	v_add_lshl_u32 v21, v12, v11, 3
	v_add_u32_e32 v11, s1, v11
	v_cvt_f32_u32_e32 v4, v9
	v_ashrrev_i32_e32 v12, 4, v11
	v_add_lshl_u32 v26, v12, v11, 3
	v_or_b32_e32 v11, 2, v10
	v_or_b32_e32 v10, 3, v10
	v_lshl_add_u32 v11, v11, s0, v9
	v_lshl_add_u32 v9, v10, s0, v9
	v_mul_f32_e32 v4, v2, v4
	v_ashrrev_i32_e32 v12, 4, v11
	v_ashrrev_i32_e32 v10, 4, v9
	v_fract_f32_e32 v5, v4
	v_add_lshl_u32 v27, v12, v11, 3
	v_add_lshl_u32 v28, v10, v9, 3
	v_cos_f32_e32 v4, v5
	v_sin_f32_e32 v5, v5
	ds_read_b64 v[10:11], v21
	ds_read_b64 v[12:13], v26
	ds_read_b64 v[14:15], v27
	ds_read_b64 v[16:17], v28
	v_mov_b32_e32 v20, v5
	v_mul_f32_e64 v8, v4, -v5
	v_pk_mul_f32 v[6:7], v[4:5], v[4:5]
	s_waitcnt lgkmcnt(1)
	v_pk_add_f32 v[18:19], v[10:11], v[14:15] neg_lo:[0,1] neg_hi:[0,1]
	v_pk_add_f32 v[10:11], v[10:11], v[14:15]
	v_pk_mul_f32 v[22:23], v[20:21], v[18:19] op_sel_hi:[0,1]
	v_pk_fma_f32 v[24:25], v[18:19], v[4:5], v[22:23] op_sel:[0,0,1] op_sel_hi:[1,1,0]
	v_pk_fma_f32 v[18:19], v[18:19], v[4:5], v[22:23] op_sel:[0,0,1] op_sel_hi:[1,0,0] neg_lo:[0,0,1] neg_hi:[0,0,1]
	v_add_f32_e32 v8, v8, v8
	v_mov_b32_e32 v25, v19
	s_waitcnt lgkmcnt(0)
	v_pk_add_f32 v[18:19], v[12:13], v[16:17] neg_lo:[0,1] neg_hi:[0,1]
	v_pk_add_f32 v[12:13], v[12:13], v[16:17]
	v_xor_b32_e32 v23, 0x80000000, v18
	v_pk_add_f32 v[14:15], v[10:11], v[12:13]
	v_pk_add_f32 v[10:11], v[10:11], v[12:13] neg_lo:[0,1] neg_hi:[0,1]
	v_mov_b32_e32 v22, v19
	v_pk_mul_f32 v[18:19], v[20:21], v[18:19] op_sel_hi:[0,1]
	v_pk_mul_f32 v[12:13], v[8:9], v[10:11] op_sel_hi:[0,1]
	v_pk_add_f32 v[6:7], v[6:7], v[6:7] op_sel:[0,1] op_sel_hi:[0,1] neg_lo:[0,1] neg_hi:[0,1]
	v_pk_fma_f32 v[4:5], v[4:5], v[22:23], v[18:19] op_sel_hi:[0,1,1] neg_lo:[0,0,1] neg_hi:[0,0,1]
	ds_write_b64 v21, v[14:15]
	v_pk_fma_f32 v[14:15], v[6:7], v[10:11], v[12:13] op_sel:[0,0,1] op_sel_hi:[1,1,0] neg_lo:[0,0,1] neg_hi:[0,0,1]
	v_pk_fma_f32 v[10:11], v[6:7], v[10:11], v[12:13] op_sel:[0,0,1] op_sel_hi:[1,1,0]
	s_addk_i32 s5, 0x800
	v_mov_b32_e32 v15, v11
	v_pk_add_f32 v[10:11], v[24:25], v[4:5]
	v_pk_add_f32 v[4:5], v[24:25], v[4:5] neg_lo:[0,1] neg_hi:[0,1]
	ds_write_b64 v26, v[14:15]
	v_pk_mul_f32 v[8:9], v[8:9], v[4:5] op_sel_hi:[0,1]
	ds_write_b64 v27, v[10:11]
	v_pk_fma_f32 v[10:11], v[6:7], v[4:5], v[8:9] op_sel:[0,0,1] op_sel_hi:[1,1,0] neg_lo:[0,0,1] neg_hi:[0,0,1]
	v_pk_fma_f32 v[4:5], v[6:7], v[4:5], v[8:9] op_sel:[0,0,1] op_sel_hi:[1,1,0]
	s_cmpk_eq_i32 s5, 0x1000
	v_add_u32_e32 v4, 0x200, v3
	v_mov_b32_e32 v11, v5
	v_and_b32_e32 v9, s4, v4
	v_ashrrev_i32_e32 v4, s0, v4
	ds_write_b64 v28, v[10:11]
	v_lshlrev_b32_e32 v10, 2, v4
	v_lshl_add_u32 v11, v10, s0, v9
	v_ashrrev_i32_e32 v12, 4, v11
	v_add_lshl_u32 v21, v12, v11, 3
	v_add_u32_e32 v11, s1, v11
	v_cvt_f32_u32_e32 v4, v9
	v_ashrrev_i32_e32 v12, 4, v11
	v_add_lshl_u32 v26, v12, v11, 3
	v_or_b32_e32 v11, 2, v10
	v_or_b32_e32 v10, 3, v10
	v_lshl_add_u32 v11, v11, s0, v9
	v_lshl_add_u32 v9, v10, s0, v9
	v_mul_f32_e32 v4, v2, v4
	v_ashrrev_i32_e32 v12, 4, v11
	v_ashrrev_i32_e32 v10, 4, v9
	v_fract_f32_e32 v5, v4
	v_add_lshl_u32 v27, v12, v11, 3
	v_add_lshl_u32 v28, v10, v9, 3
	v_cos_f32_e32 v4, v5
	v_sin_f32_e32 v5, v5
	ds_read_b64 v[10:11], v21
	ds_read_b64 v[12:13], v26
	ds_read_b64 v[14:15], v27
	ds_read_b64 v[16:17], v28
	v_mov_b32_e32 v20, v5
	v_mul_f32_e64 v8, v4, -v5
	v_pk_mul_f32 v[6:7], v[4:5], v[4:5]
	s_waitcnt lgkmcnt(1)
	v_pk_add_f32 v[18:19], v[10:11], v[14:15] neg_lo:[0,1] neg_hi:[0,1]
	v_pk_add_f32 v[10:11], v[10:11], v[14:15]
	v_pk_mul_f32 v[22:23], v[20:21], v[18:19] op_sel_hi:[0,1]
	v_pk_fma_f32 v[24:25], v[18:19], v[4:5], v[22:23] op_sel:[0,0,1] op_sel_hi:[1,1,0]
	v_pk_fma_f32 v[18:19], v[18:19], v[4:5], v[22:23] op_sel:[0,0,1] op_sel_hi:[1,0,0] neg_lo:[0,0,1] neg_hi:[0,0,1]
	v_add_f32_e32 v8, v8, v8
	v_mov_b32_e32 v25, v19
	s_waitcnt lgkmcnt(0)
	v_pk_add_f32 v[18:19], v[12:13], v[16:17] neg_lo:[0,1] neg_hi:[0,1]
	v_pk_add_f32 v[12:13], v[12:13], v[16:17]
	v_xor_b32_e32 v23, 0x80000000, v18
	v_pk_add_f32 v[14:15], v[10:11], v[12:13]
	v_pk_add_f32 v[10:11], v[10:11], v[12:13] neg_lo:[0,1] neg_hi:[0,1]
	v_mov_b32_e32 v22, v19
	v_pk_mul_f32 v[18:19], v[20:21], v[18:19] op_sel_hi:[0,1]
	v_pk_mul_f32 v[12:13], v[8:9], v[10:11] op_sel_hi:[0,1]
	v_pk_add_f32 v[6:7], v[6:7], v[6:7] op_sel:[0,1] op_sel_hi:[0,1] neg_lo:[0,1] neg_hi:[0,1]
	v_pk_fma_f32 v[4:5], v[4:5], v[22:23], v[18:19] op_sel_hi:[0,1,1] neg_lo:[0,0,1] neg_hi:[0,0,1]
	ds_write_b64 v21, v[14:15]
	v_pk_fma_f32 v[14:15], v[6:7], v[10:11], v[12:13] op_sel:[0,0,1] op_sel_hi:[1,1,0] neg_lo:[0,0,1] neg_hi:[0,0,1]
	v_pk_fma_f32 v[10:11], v[6:7], v[10:11], v[12:13] op_sel:[0,0,1] op_sel_hi:[1,1,0]
	s_nop 0
	v_mov_b32_e32 v15, v11
	v_pk_add_f32 v[10:11], v[24:25], v[4:5]
	v_pk_add_f32 v[4:5], v[24:25], v[4:5] neg_lo:[0,1] neg_hi:[0,1]
	ds_write_b64 v26, v[14:15]
	v_pk_mul_f32 v[8:9], v[8:9], v[4:5] op_sel_hi:[0,1]
	ds_write_b64 v27, v[10:11]
	v_pk_fma_f32 v[10:11], v[6:7], v[4:5], v[8:9] op_sel:[0,0,1] op_sel_hi:[1,1,0] neg_lo:[0,0,1] neg_hi:[0,0,1]
	v_pk_fma_f32 v[4:5], v[6:7], v[4:5], v[8:9] op_sel:[0,0,1] op_sel_hi:[1,1,0]
	s_nop 0
	v_add_u32_e32 v4, 0x400, v3
	v_mov_b32_e32 v11, v5
	v_and_b32_e32 v9, s4, v4
	v_ashrrev_i32_e32 v4, s0, v4
	ds_write_b64 v28, v[10:11]
	v_lshlrev_b32_e32 v10, 2, v4
	v_lshl_add_u32 v11, v10, s0, v9
	v_ashrrev_i32_e32 v12, 4, v11
	v_add_lshl_u32 v21, v12, v11, 3
	v_add_u32_e32 v11, s1, v11
	v_cvt_f32_u32_e32 v4, v9
	v_ashrrev_i32_e32 v12, 4, v11
	v_add_lshl_u32 v26, v12, v11, 3
	v_or_b32_e32 v11, 2, v10
	v_or_b32_e32 v10, 3, v10
	v_lshl_add_u32 v11, v11, s0, v9
	v_lshl_add_u32 v9, v10, s0, v9
	v_mul_f32_e32 v4, v2, v4
	v_ashrrev_i32_e32 v12, 4, v11
	v_ashrrev_i32_e32 v10, 4, v9
	v_fract_f32_e32 v5, v4
	v_add_lshl_u32 v27, v12, v11, 3
	v_add_lshl_u32 v28, v10, v9, 3
	v_cos_f32_e32 v4, v5
	v_sin_f32_e32 v5, v5
	ds_read_b64 v[10:11], v21
	ds_read_b64 v[12:13], v26
	ds_read_b64 v[14:15], v27
	ds_read_b64 v[16:17], v28
	v_mov_b32_e32 v20, v5
	v_mul_f32_e64 v8, v4, -v5
	v_pk_mul_f32 v[6:7], v[4:5], v[4:5]
	s_waitcnt lgkmcnt(1)
; DI float sin_t(float turns) { return __builtin_amdgcn_sinf(__builtin_amdgcn_fractf(turns)); }
; DI float cos_t(float turns) { return __builtin_amdgcn_cosf(__builtin_amdgcn_fractf(turns)); }
; DI float2 cmul(float2 a, float2 b) { return make_float2(a.x * b.x - a.y * b.y, a.x * b.y + a.y * b.x); }
; template <int N, bool INV>
; DI void fft_lds(float2* s) {
;     ...
;       for (int it = 0; it < N / 4 / NT; ++it) {
;         int idx = tid + it * NT;
;         int j = idx & (q - 1), blk = idx >> lq;
;         int p0 = blk * 4 * q + j;
;         float f = (float)j * inv4q;
;         float2 t1 = make_float2(cos_t(f), -sin_t(f));
;         float2 t2 = cmul(t1, t1);
;         float2 x0 = s[phys(p0)], x1 = s[phys(p0 + q)], x2 = s[phys(p0 + 2 * q)], x3 = s[phys(p0 + 3 * q)];
;         float2 a0 = make_float2(x0.x + x2.x, x0.y + x2.y);
;         float2 a2 = cmul(make_float2(x0.x - x2.x, x0.y - x2.y), t1);
;         float2 a1 = make_float2(x1.x + x3.x, x1.y + x3.y);
;         float2 d3 = make_float2(x1.x - x3.x, x1.y - x3.y);
;         float2 a3 = cmul(make_float2(d3.y, -d3.x), t1);
;         s[phys(p0)] = make_float2(a0.x + a1.x, a0.y + a1.y);
;         s[phys(p0 + q)] = cmul(make_float2(a0.x - a1.x, a0.y - a1.y), t2);
;         s[phys(p0 + 2 * q)] = make_float2(a2.x + a3.x, a2.y + a3.y);
;         s[phys(p0 + 3 * q)] = cmul(make_float2(a2.x - a3.x, a2.y - a3.y), t2);
;       }
; DI void hyena_lat_item(const P& p, int l, int c, int bp, unsigned char* lds) {
;     ...
;     for (int i = tid; i < 16384; i += NT) { s[phys(i)] = cmul(s[phys(i)], H[i]); }
	v_pk_add_f32 v[18:19], v[10:11], v[14:15] neg_lo:[0,1] neg_hi:[0,1]
	v_pk_add_f32 v[10:11], v[10:11], v[14:15]
	v_pk_mul_f32 v[22:23], v[20:21], v[18:19] op_sel_hi:[0,1]
	v_pk_fma_f32 v[24:25], v[18:19], v[4:5], v[22:23] op_sel:[0,0,1] op_sel_hi:[1,1,0]
	v_pk_fma_f32 v[18:19], v[18:19], v[4:5], v[22:23] op_sel:[0,0,1] op_sel_hi:[1,0,0] neg_lo:[0,0,1] neg_hi:[0,0,1]
	v_add_f32_e32 v8, v8, v8
	v_mov_b32_e32 v25, v19
	s_waitcnt lgkmcnt(0)
	v_pk_add_f32 v[18:19], v[12:13], v[16:17] neg_lo:[0,1] neg_hi:[0,1]
	v_pk_add_f32 v[12:13], v[12:13], v[16:17]
	v_xor_b32_e32 v23, 0x80000000, v18
	v_pk_add_f32 v[14:15], v[10:11], v[12:13]
	v_pk_add_f32 v[10:11], v[10:11], v[12:13] neg_lo:[0,1] neg_hi:[0,1]
	v_mov_b32_e32 v22, v19
	v_pk_mul_f32 v[18:19], v[20:21], v[18:19] op_sel_hi:[0,1]
	v_pk_mul_f32 v[12:13], v[8:9], v[10:11] op_sel_hi:[0,1]
	v_pk_add_f32 v[6:7], v[6:7], v[6:7] op_sel:[0,1] op_sel_hi:[0,1] neg_lo:[0,1] neg_hi:[0,1]
	v_pk_fma_f32 v[4:5], v[4:5], v[22:23], v[18:19] op_sel_hi:[0,1,1] neg_lo:[0,0,1] neg_hi:[0,0,1]
	ds_write_b64 v21, v[14:15]
	v_pk_fma_f32 v[14:15], v[6:7], v[10:11], v[12:13] op_sel:[0,0,1] op_sel_hi:[1,1,0] neg_lo:[0,0,1] neg_hi:[0,0,1]
	v_pk_fma_f32 v[10:11], v[6:7], v[10:11], v[12:13] op_sel:[0,0,1] op_sel_hi:[1,1,0]
	v_add_u32_e32 v3, 0x600, v3
	v_mov_b32_e32 v15, v11
	v_pk_add_f32 v[10:11], v[24:25], v[4:5]
	v_pk_add_f32 v[4:5], v[24:25], v[4:5] neg_lo:[0,1] neg_hi:[0,1]
	ds_write_b64 v26, v[14:15]
	v_pk_mul_f32 v[8:9], v[8:9], v[4:5] op_sel_hi:[0,1]
	ds_write_b64 v27, v[10:11]
	v_pk_fma_f32 v[10:11], v[6:7], v[4:5], v[8:9] op_sel:[0,0,1] op_sel_hi:[1,1,0] neg_lo:[0,0,1] neg_hi:[0,0,1]
	v_pk_fma_f32 v[4:5], v[6:7], v[4:5], v[8:9] op_sel:[0,0,1] op_sel_hi:[1,1,0]
	v_and_b32_e32 v9, s4, v3
	v_ashrrev_i32_e32 v3, s0, v3
	v_mov_b32_e32 v11, v5
	v_lshlrev_b32_e32 v3, 2, v3
	ds_write_b64 v28, v[10:11]
	v_lshl_add_u32 v10, v3, s0, v9
	v_ashrrev_i32_e32 v11, 4, v10
	v_add_lshl_u32 v21, v11, v10, 3
	v_add_u32_e32 v10, s1, v10
	v_cvt_f32_u32_e32 v4, v9
	v_ashrrev_i32_e32 v11, 4, v10
	v_add_lshl_u32 v26, v11, v10, 3
	v_or_b32_e32 v10, 2, v3
	v_or_b32_e32 v3, 3, v3
	v_lshl_add_u32 v10, v10, s0, v9
	v_lshl_add_u32 v3, v3, s0, v9
	v_mul_f32_e32 v4, v2, v4
	v_ashrrev_i32_e32 v11, 4, v10
	v_ashrrev_i32_e32 v9, 4, v3
	v_fract_f32_e32 v5, v4
	v_add_lshl_u32 v27, v11, v10, 3
	v_lshlrev_b32_e32 v9, 3, v9
	v_lshlrev_b32_e32 v3, 3, v3
	v_cos_f32_e32 v4, v5
	v_sin_f32_e32 v5, v5
	v_add3_u32 v3, 0, v9, v3
	ds_read_b64 v[10:11], v21
	ds_read_b64 v[12:13], v26
	ds_read_b64 v[14:15], v27
	ds_read_b64 v[16:17], v3
	v_mov_b32_e32 v20, v5
	v_mul_f32_e64 v8, v4, -v5
	v_pk_mul_f32 v[6:7], v[4:5], v[4:5]
	s_waitcnt lgkmcnt(1)
	v_pk_add_f32 v[18:19], v[10:11], v[14:15] neg_lo:[0,1] neg_hi:[0,1]
	v_pk_add_f32 v[10:11], v[10:11], v[14:15]
	v_pk_mul_f32 v[22:23], v[20:21], v[18:19] op_sel_hi:[0,1]
	v_pk_fma_f32 v[24:25], v[18:19], v[4:5], v[22:23] op_sel:[0,0,1] op_sel_hi:[1,1,0]
	v_pk_fma_f32 v[18:19], v[18:19], v[4:5], v[22:23] op_sel:[0,0,1] op_sel_hi:[1,0,0] neg_lo:[0,0,1] neg_hi:[0,0,1]
	v_add_f32_e32 v8, v8, v8
	v_mov_b32_e32 v25, v19
	s_waitcnt lgkmcnt(0)
	v_pk_add_f32 v[18:19], v[12:13], v[16:17] neg_lo:[0,1] neg_hi:[0,1]
	v_pk_add_f32 v[12:13], v[12:13], v[16:17]
	v_xor_b32_e32 v23, 0x80000000, v18
	v_pk_add_f32 v[14:15], v[10:11], v[12:13]
	v_pk_add_f32 v[10:11], v[10:11], v[12:13] neg_lo:[0,1] neg_hi:[0,1]
	v_mov_b32_e32 v22, v19
	v_pk_mul_f32 v[18:19], v[20:21], v[18:19] op_sel_hi:[0,1]
	v_pk_mul_f32 v[12:13], v[8:9], v[10:11] op_sel_hi:[0,1]
	v_pk_add_f32 v[6:7], v[6:7], v[6:7] op_sel:[0,1] op_sel_hi:[0,1] neg_lo:[0,1] neg_hi:[0,1]
	v_pk_fma_f32 v[4:5], v[4:5], v[22:23], v[18:19] op_sel_hi:[0,1,1] neg_lo:[0,0,1] neg_hi:[0,0,1]
	ds_write_b64 v21, v[14:15]
	v_pk_fma_f32 v[14:15], v[6:7], v[10:11], v[12:13] op_sel:[0,0,1] op_sel_hi:[1,1,0] neg_lo:[0,0,1] neg_hi:[0,0,1]
	v_pk_fma_f32 v[10:11], v[6:7], v[10:11], v[12:13] op_sel:[0,0,1] op_sel_hi:[1,1,0]
	s_nop 0
	v_mov_b32_e32 v15, v11
	v_pk_add_f32 v[10:11], v[24:25], v[4:5]
	v_pk_add_f32 v[4:5], v[24:25], v[4:5] neg_lo:[0,1] neg_hi:[0,1]
	ds_write_b64 v26, v[14:15]
	v_pk_mul_f32 v[8:9], v[8:9], v[4:5] op_sel_hi:[0,1]
	ds_write_b64 v27, v[10:11]
	v_pk_fma_f32 v[10:11], v[6:7], v[4:5], v[8:9] op_sel:[0,0,1] op_sel_hi:[1,1,0] neg_lo:[0,0,1] neg_hi:[0,0,1]
	v_pk_fma_f32 v[4:5], v[6:7], v[4:5], v[8:9] op_sel:[0,0,1] op_sel_hi:[1,1,0]
	s_nop 0
	v_mov_b32_e32 v11, v5
	ds_write_b64 v3, v[10:11]
	s_cbranch_scc0 .LBB0_473
	s_add_i32 s1, s0, -2
	s_cmp_eq_u32 s0, 0
	s_mov_b32 s0, s1
	s_cbranch_scc0 .LBB0_472
	s_movk_i32 s0, 0x4000
	v_max_i32_e32 v1, 0x3e00, v52
	v_cmp_gt_i32_e64 s[4:5], s0, v52
	v_sub_u32_e32 v70, v1, v52
	s_waitcnt lgkmcnt(0)
	s_barrier
	s_and_saveexec_b64 s[0:1], s[4:5]
	s_cbranch_execz .LBB0_483
	v_add_u32_e32 v1, 0x1ff, v70
	v_and_b32_e32 v2, 0xe00, v1
	s_movk_i32 s10, 0xe00
	v_cmp_ne_u32_e32 vcc, s10, v2
	v_mov_b32_e32 v2, v52
	s_and_saveexec_b64 s[10:11], vcc
	s_cbranch_execz .LBB0_480
	v_lshrrev_b32_e32 v2, 9, v1
	s_lshl_b64 s[12:13], s[6:7], 17
	v_readlane_b32 s16, v254, 60
	v_add_u32_e32 v2, 1, v2
	s_add_u32 s12, s16, s12
	v_readlane_b32 s16, v254, 61
	v_and_b32_e32 v2, 7, v2
	v_ashrrev_i32_e32 v53, 31, v52
	s_addc_u32 s13, s16, s13
	v_lshl_add_u64 v[4:5], v[52:53], 3, s[12:13]
	v_add_u32_e32 v3, 0, v50
	v_sub_u32_e32 v6, 0, v2
	s_mov_b64 s[12:13], 0
	v_mov_b32_e32 v2, v52
	s_mov_b64 s[16:17], 0x1000

; DI float sin_t(float turns) { return __builtin_amdgcn_sinf(__builtin_amdgcn_fractf(turns)); }
; DI float cos_t(float turns) { return __builtin_amdgcn_cosf(__builtin_amdgcn_fractf(turns)); }
; DI float2 cmul(float2 a, float2 b) { return make_float2(a.x * b.x - a.y * b.y, a.x * b.y + a.y * b.x); }
; template <int N, bool INV>
; DI void fft_lds(float2* s) {
;     ...
;     for (int lq = 0; (1 << lq) <= top; lq += 2) {
;       const int q = 1 << lq;
;       __syncthreads();
;       const float inv4q = 1.0f / (float)(4 * q);
; #pragma unroll 4
;       for (int it = 0; it < N / 4 / NT; ++it) {
;         int idx = tid + it * NT;
;         int j = idx & (q - 1), blk = idx >> lq;
;         int p0 = blk * 4 * q + j;
;         float f = (float)j * inv4q;
;         float2 t1 = make_float2(cos_t(f), sin_t(f));
;         float2 t2 = cmul(t1, t1);
;         float2 x0 = s[phys(p0)], x1 = s[phys(p0 + q)], x2 = s[phys(p0 + 2 * q)], x3 = s[phys(p0 + 3 * q)];
;         float2 b = cmul(x1, t2);
;         float2 a0 = make_float2(x0.x + b.x, x0.y + b.y), a1 = make_float2(x0.x - b.x, x0.y - b.y);
;         b = cmul(x3, t2);
;         float2 a2 = make_float2(x2.x + b.x, x2.y + b.y), a3 = make_float2(x2.x - b.x, x2.y - b.y);
;         b = cmul(a2, t1);
;         s[phys(p0)] = make_float2(a0.x + b.x, a0.y + b.y);
;         s[phys(p0 + 2 * q)] = make_float2(a0.x - b.x, a0.y - b.y);
;         float2 c3 = cmul(a3, t1);
;         b = make_float2(-c3.y, c3.x);
;         s[phys(p0 + q)] = make_float2(a1.x + b.x, a1.y + b.y);
;         s[phys(p0 + 3 * q)] = make_float2(a1.x - b.x, a1.y - b.y);
;       }
.LBB0_485:
	v_add_u32_e32 v20, s13, v1
	v_ashrrev_i32_e32 v2, s0, v20
	v_and_b32_e32 v7, s12, v20
	v_lshlrev_b32_e32 v8, 2, v2
	v_lshl_add_u32 v9, v8, s0, v7
	v_cvt_f32_u32_e32 v2, v7
	v_ashrrev_i32_e32 v10, 4, v9
	v_add_lshl_u32 v21, v10, v9, 3
	v_add_u32_e32 v9, s1, v9
	v_ashrrev_i32_e32 v10, 4, v9
	v_add_lshl_u32 v22, v10, v9, 3
	v_mul_f32_e32 v2, s11, v2
	v_or_b32_e32 v9, 2, v8
	v_or_b32_e32 v8, 3, v8
	v_fract_f32_e32 v3, v2
	v_lshl_add_u32 v9, v9, s0, v7
	v_lshl_add_u32 v7, v8, s0, v7
	v_cos_f32_e32 v2, v3
	v_sin_f32_e32 v3, v3
	v_ashrrev_i32_e32 v10, 4, v9
	v_ashrrev_i32_e32 v8, 4, v7
	v_add_lshl_u32 v23, v10, v9, 3
	v_lshlrev_b32_e32 v8, 3, v8
	v_lshlrev_b32_e32 v7, 3, v7
	v_add3_u32 v24, 0, v8, v7
	ds_read_b64 v[8:9], v21
	ds_read_b64 v[10:11], v22
	ds_read_b64 v[12:13], v23
	ds_read_b64 v[14:15], v24
	v_mul_f32_e32 v6, v2, v3
	v_pk_mul_f32 v[4:5], v[2:3], v[2:3]
	v_add_f32_e32 v6, v6, v6
	s_waitcnt lgkmcnt(2)
	v_pk_mul_f32 v[16:17], v[10:11], v[6:7] op_sel_hi:[1,0]
	v_pk_add_f32 v[4:5], v[4:5], v[4:5] op_sel:[0,1] op_sel_hi:[0,1] neg_lo:[0,1] neg_hi:[0,1]
	v_pk_fma_f32 v[18:19], v[10:11], v[4:5], v[16:17] op_sel:[0,0,1] op_sel_hi:[1,1,0] neg_lo:[0,0,1] neg_hi:[0,0,1]
	v_pk_fma_f32 v[10:11], v[10:11], v[4:5], v[16:17] op_sel:[0,0,1] op_sel_hi:[1,1,0]
	s_waitcnt lgkmcnt(0)
	v_pk_mul_f32 v[4:5], v[14:15], v[4:5]
	v_mov_b32_e32 v19, v11
	v_pk_fma_f32 v[16:17], v[14:15], v[6:7], v[4:5] op_sel:[0,0,1] op_sel_hi:[1,1,0]
	v_pk_fma_f32 v[4:5], v[14:15], v[6:7], v[4:5] op_sel:[0,0,1] op_sel_hi:[1,0,0] neg_lo:[1,0,0] neg_hi:[1,0,0]
	v_pk_add_f32 v[10:11], v[8:9], v[18:19] neg_lo:[0,1] neg_hi:[0,1]
	v_mov_b32_e32 v17, v5
	v_pk_add_f32 v[6:7], v[8:9], v[18:19]
	v_pk_add_f32 v[8:9], v[12:13], v[16:17] op_sel:[1,0] op_sel_hi:[0,1]
	v_pk_add_f32 v[4:5], v[12:13], v[16:17] op_sel:[1,0] op_sel_hi:[0,1] neg_lo:[0,1] neg_hi:[0,1]
	v_mov_b32_e32 v12, v3
	v_mov_b32_e32 v14, v3
	v_pk_mul_f32 v[16:17], v[2:3], v[8:9] op_sel_hi:[0,1]
	v_pk_fma_f32 v[12:13], v[12:13], v[8:9], v[16:17] op_sel:[0,0,1] op_sel_hi:[1,1,0] neg_lo:[1,0,0] neg_hi:[1,0,0]
	v_pk_fma_f32 v[8:9], v[14:15], v[8:9], v[16:17] op_sel:[0,0,1] op_sel_hi:[0,1,0]
	v_mov_b32_e32 v13, v9
	v_pk_add_f32 v[8:9], v[6:7], v[12:13]
	v_pk_add_f32 v[6:7], v[6:7], v[12:13] neg_lo:[0,1] neg_hi:[0,1]
	ds_write_b64 v21, v[8:9]
	ds_write_b64 v23, v[6:7]
	v_pk_mul_f32 v[6:7], v[14:15], v[4:5] op_sel_hi:[0,1]
	v_pk_fma_f32 v[8:9], v[2:3], v[4:5], v[6:7] op_sel:[0,0,1] op_sel_hi:[1,1,0]
	v_pk_fma_f32 v[2:3], v[2:3], v[4:5], v[6:7] op_sel:[0,0,1] op_sel_hi:[0,1,0] neg_lo:[0,0,1] neg_hi:[0,0,1]
	v_mov_b32_e32 v9, v3
	v_pk_add_f32 v[2:3], v[10:11], v[8:9] neg_lo:[0,1] neg_hi:[0,1]
	v_pk_add_f32 v[4:5], v[10:11], v[8:9]
	v_mov_b32_e32 v6, v2
	v_mov_b32_e32 v7, v5
	v_add_u32_e32 v2, 0x200, v20
	ds_write_b64 v22, v[6:7]
	v_and_b32_e32 v7, s12, v2
	v_ashrrev_i32_e32 v2, s0, v2
	v_lshlrev_b32_e32 v8, 2, v2
	v_lshl_add_u32 v9, v8, s0, v7
	v_cvt_f32_u32_e32 v2, v7
	v_ashrrev_i32_e32 v10, 4, v9
	v_add_lshl_u32 v21, v10, v9, 3
	v_add_u32_e32 v9, s1, v9
	v_ashrrev_i32_e32 v10, 4, v9
	v_add_lshl_u32 v22, v10, v9, 3
	v_mul_f32_e32 v2, s11, v2
	v_or_b32_e32 v9, 2, v8
	v_or_b32_e32 v8, 3, v8
	v_mov_b32_e32 v5, v3
	v_fract_f32_e32 v3, v2
	v_lshl_add_u32 v9, v9, s0, v7
	v_lshl_add_u32 v7, v8, s0, v7
	v_cos_f32_e32 v2, v3
	v_sin_f32_e32 v3, v3
	v_ashrrev_i32_e32 v10, 4, v9
	v_ashrrev_i32_e32 v8, 4, v7
	ds_write_b64 v24, v[4:5]
	v_add_lshl_u32 v23, v10, v9, 3
	v_lshlrev_b32_e32 v8, 3, v8
	v_lshlrev_b32_e32 v7, 3, v7
	v_add3_u32 v24, 0, v8, v7
	ds_read_b64 v[8:9], v21
	ds_read_b64 v[10:11], v22
	ds_read_b64 v[12:13], v23
	ds_read_b64 v[14:15], v24
	v_mul_f32_e32 v6, v2, v3
	v_pk_mul_f32 v[4:5], v[2:3], v[2:3]
	v_add_f32_e32 v6, v6, v6
	s_waitcnt lgkmcnt(2)
	v_pk_mul_f32 v[16:17], v[10:11], v[6:7] op_sel_hi:[1,0]
	v_pk_add_f32 v[4:5], v[4:5], v[4:5] op_sel:[0,1] op_sel_hi:[0,1] neg_lo:[0,1] neg_hi:[0,1]
	v_pk_fma_f32 v[18:19], v[10:11], v[4:5], v[16:17] op_sel:[0,0,1] op_sel_hi:[1,1,0] neg_lo:[0,0,1] neg_hi:[0,0,1]
	v_pk_fma_f32 v[10:11], v[10:11], v[4:5], v[16:17] op_sel:[0,0,1] op_sel_hi:[1,1,0]
	s_waitcnt lgkmcnt(0)
	v_pk_mul_f32 v[4:5], v[14:15], v[4:5]
	v_mov_b32_e32 v19, v11
	v_pk_fma_f32 v[16:17], v[14:15], v[6:7], v[4:5] op_sel:[0,0,1] op_sel_hi:[1,1,0]
	v_pk_fma_f32 v[4:5], v[14:15], v[6:7], v[4:5] op_sel:[0,0,1] op_sel_hi:[1,0,0] neg_lo:[1,0,0] neg_hi:[1,0,0]
	v_pk_add_f32 v[10:11], v[8:9], v[18:19] neg_lo:[0,1] neg_hi:[0,1]
	v_mov_b32_e32 v17, v5
	v_pk_add_f32 v[6:7], v[8:9], v[18:19]
	v_pk_add_f32 v[8:9], v[12:13], v[16:17] op_sel:[1,0] op_sel_hi:[0,1]
	v_pk_add_f32 v[4:5], v[12:13], v[16:17] op_sel:[1,0] op_sel_hi:[0,1] neg_lo:[0,1] neg_hi:[0,1]
	v_mov_b32_e32 v12, v3
	v_mov_b32_e32 v14, v3
	v_pk_mul_f32 v[16:17], v[2:3], v[8:9] op_sel_hi:[0,1]
	v_pk_fma_f32 v[12:13], v[12:13], v[8:9], v[16:17] op_sel:[0,0,1] op_sel_hi:[1,1,0] neg_lo:[1,0,0] neg_hi:[1,0,0]
	v_pk_fma_f32 v[8:9], v[14:15], v[8:9], v[16:17] op_sel:[0,0,1] op_sel_hi:[0,1,0]
	v_mov_b32_e32 v13, v9
	v_pk_add_f32 v[8:9], v[6:7], v[12:13]
	v_pk_add_f32 v[6:7], v[6:7], v[12:13] neg_lo:[0,1] neg_hi:[0,1]
	ds_write_b64 v21, v[8:9]
	ds_write_b64 v23, v[6:7]
	v_pk_mul_f32 v[6:7], v[14:15], v[4:5] op_sel_hi:[0,1]
	v_pk_fma_f32 v[8:9], v[2:3], v[4:5], v[6:7] op_sel:[0,0,1] op_sel_hi:[1,1,0]
	v_pk_fma_f32 v[2:3], v[2:3], v[4:5], v[6:7] op_sel:[0,0,1] op_sel_hi:[0,1,0] neg_lo:[0,0,1] neg_hi:[0,0,1]
	v_mov_b32_e32 v9, v3
	v_pk_add_f32 v[2:3], v[10:11], v[8:9] neg_lo:[0,1] neg_hi:[0,1]
	v_pk_add_f32 v[4:5], v[10:11], v[8:9]
	v_mov_b32_e32 v6, v2
	v_mov_b32_e32 v7, v5
	v_add_u32_e32 v2, 0x400, v20
	ds_write_b64 v22, v[6:7]
	v_and_b32_e32 v7, s12, v2
	v_ashrrev_i32_e32 v2, s0, v2
	v_lshlrev_b32_e32 v8, 2, v2
	v_lshl_add_u32 v9, v8, s0, v7
	v_cvt_f32_u32_e32 v2, v7
	v_ashrrev_i32_e32 v10, 4, v9
	v_add_lshl_u32 v21, v10, v9, 3
	v_add_u32_e32 v9, s1, v9
	v_ashrrev_i32_e32 v10, 4, v9
	v_add_lshl_u32 v22, v10, v9, 3
	v_mul_f32_e32 v2, s11, v2
	v_or_b32_e32 v9, 2, v8
	v_or_b32_e32 v8, 3, v8
	v_mov_b32_e32 v5, v3
	v_fract_f32_e32 v3, v2
	v_lshl_add_u32 v9, v9, s0, v7
	v_lshl_add_u32 v7, v8, s0, v7
	v_cos_f32_e32 v2, v3
	v_sin_f32_e32 v3, v3
	v_ashrrev_i32_e32 v10, 4, v9
	v_ashrrev_i32_e32 v8, 4, v7
	ds_write_b64 v24, v[4:5]
	v_add_lshl_u32 v23, v10, v9, 3
	v_lshlrev_b32_e32 v8, 3, v8
	v_lshlrev_b32_e32 v7, 3, v7
	v_add3_u32 v24, 0, v8, v7
	ds_read_b64 v[8:9], v21
	ds_read_b64 v[10:11], v22
	ds_read_b64 v[12:13], v23
	ds_read_b64 v[14:15], v24
	v_mul_f32_e32 v6, v2, v3
	v_pk_mul_f32 v[4:5], v[2:3], v[2:3]
	v_add_f32_e32 v6, v6, v6
	s_waitcnt lgkmcnt(2)
; DI float sin_t(float turns) { return __builtin_amdgcn_sinf(__builtin_amdgcn_fractf(turns)); }
; DI float cos_t(float turns) { return __builtin_amdgcn_cosf(__builtin_amdgcn_fractf(turns)); }
; DI float2 cmul(float2 a, float2 b) { return make_float2(a.x * b.x - a.y * b.y, a.x * b.y + a.y * b.x); }
; template <int N, bool INV>
; DI void fft_lds(float2* s) {
;     ...
;       for (int it = 0; it < N / 4 / NT; ++it) {
;         int idx = tid + it * NT;
;         int j = idx & (q - 1), blk = idx >> lq;
;         int p0 = blk * 4 * q + j;
;         float f = (float)j * inv4q;
;         float2 t1 = make_float2(cos_t(f), sin_t(f));
;         float2 t2 = cmul(t1, t1);
;         float2 x0 = s[phys(p0)], x1 = s[phys(p0 + q)], x2 = s[phys(p0 + 2 * q)], x3 = s[phys(p0 + 3 * q)];
;         float2 b = cmul(x1, t2);
;         float2 a0 = make_float2(x0.x + b.x, x0.y + b.y), a1 = make_float2(x0.x - b.x, x0.y - b.y);
;         b = cmul(x3, t2);
;         float2 a2 = make_float2(x2.x + b.x, x2.y + b.y), a3 = make_float2(x2.x - b.x, x2.y - b.y);
;         b = cmul(a2, t1);
;         s[phys(p0)] = make_float2(a0.x + b.x, a0.y + b.y);
;         s[phys(p0 + 2 * q)] = make_float2(a0.x - b.x, a0.y - b.y);
;         float2 c3 = cmul(a3, t1);
;         b = make_float2(-c3.y, c3.x);
;         s[phys(p0 + q)] = make_float2(a1.x + b.x, a1.y + b.y);
;         s[phys(p0 + 3 * q)] = make_float2(a1.x - b.x, a1.y - b.y);
;       }
; DI void hyena_lat_item(const P& p, int l, int c, int bp, unsigned char* lds) {
;     ...
;       float2 y1v[16];
; #pragma unroll
;       for (int i = 0; i < 16; ++i) {
;         int n = (i >> 3) * 4096 + tid * 8 + (i & 7);
;         float2 cv = s[phys(n)], v = scr[n], x1 = scr[8192 + n];
;         y1v[i] = make_float2(x1.x * (cv.x * invN + v.x * bias), x1.y * (cv.y * invN + v.y * bias));
;         scr[24576 + n] = y1v[i];
;       }
	v_pk_mul_f32 v[16:17], v[10:11], v[6:7] op_sel_hi:[1,0]
	v_pk_add_f32 v[4:5], v[4:5], v[4:5] op_sel:[0,1] op_sel_hi:[0,1] neg_lo:[0,1] neg_hi:[0,1]
	v_pk_fma_f32 v[18:19], v[10:11], v[4:5], v[16:17] op_sel:[0,0,1] op_sel_hi:[1,1,0] neg_lo:[0,0,1] neg_hi:[0,0,1]
	v_pk_fma_f32 v[10:11], v[10:11], v[4:5], v[16:17] op_sel:[0,0,1] op_sel_hi:[1,1,0]
	s_waitcnt lgkmcnt(0)
	v_pk_mul_f32 v[4:5], v[14:15], v[4:5]
	v_mov_b32_e32 v19, v11
	v_pk_fma_f32 v[16:17], v[14:15], v[6:7], v[4:5] op_sel:[0,0,1] op_sel_hi:[1,1,0]
	v_pk_fma_f32 v[4:5], v[14:15], v[6:7], v[4:5] op_sel:[0,0,1] op_sel_hi:[1,0,0] neg_lo:[1,0,0] neg_hi:[1,0,0]
	v_pk_add_f32 v[10:11], v[8:9], v[18:19] neg_lo:[0,1] neg_hi:[0,1]
	v_mov_b32_e32 v17, v5
	v_pk_add_f32 v[6:7], v[8:9], v[18:19]
	v_pk_add_f32 v[8:9], v[12:13], v[16:17] op_sel:[1,0] op_sel_hi:[0,1]
	v_pk_add_f32 v[4:5], v[12:13], v[16:17] op_sel:[1,0] op_sel_hi:[0,1] neg_lo:[0,1] neg_hi:[0,1]
	v_mov_b32_e32 v12, v3
	v_mov_b32_e32 v14, v3
	v_pk_mul_f32 v[16:17], v[2:3], v[8:9] op_sel_hi:[0,1]
	v_pk_fma_f32 v[12:13], v[12:13], v[8:9], v[16:17] op_sel:[0,0,1] op_sel_hi:[1,1,0] neg_lo:[1,0,0] neg_hi:[1,0,0]
	v_pk_fma_f32 v[8:9], v[14:15], v[8:9], v[16:17] op_sel:[0,0,1] op_sel_hi:[0,1,0]
	v_mov_b32_e32 v13, v9
	v_pk_add_f32 v[8:9], v[6:7], v[12:13]
	v_pk_add_f32 v[6:7], v[6:7], v[12:13] neg_lo:[0,1] neg_hi:[0,1]
	ds_write_b64 v21, v[8:9]
	ds_write_b64 v23, v[6:7]
	v_pk_mul_f32 v[6:7], v[14:15], v[4:5] op_sel_hi:[0,1]
	v_pk_fma_f32 v[8:9], v[2:3], v[4:5], v[6:7] op_sel:[0,0,1] op_sel_hi:[1,1,0]
	v_pk_fma_f32 v[2:3], v[2:3], v[4:5], v[6:7] op_sel:[0,0,1] op_sel_hi:[0,1,0] neg_lo:[0,0,1] neg_hi:[0,0,1]
	v_mov_b32_e32 v9, v3
	v_pk_add_f32 v[2:3], v[10:11], v[8:9] neg_lo:[0,1] neg_hi:[0,1]
	v_pk_add_f32 v[4:5], v[10:11], v[8:9]
	v_mov_b32_e32 v6, v2
	v_mov_b32_e32 v7, v5
	v_add_u32_e32 v2, 0x600, v20
	ds_write_b64 v22, v[6:7]
	v_and_b32_e32 v7, s12, v2
	v_ashrrev_i32_e32 v2, s0, v2
	v_lshlrev_b32_e32 v8, 2, v2
	v_lshl_add_u32 v9, v8, s0, v7
	v_cvt_f32_u32_e32 v2, v7
	v_ashrrev_i32_e32 v10, 4, v9
	v_add_lshl_u32 v20, v10, v9, 3
	v_add_u32_e32 v9, s1, v9
	v_ashrrev_i32_e32 v10, 4, v9
	v_add_lshl_u32 v21, v10, v9, 3
	v_mul_f32_e32 v2, s11, v2
	v_or_b32_e32 v9, 2, v8
	v_or_b32_e32 v8, 3, v8
	v_mov_b32_e32 v5, v3
	v_fract_f32_e32 v3, v2
	v_lshl_add_u32 v9, v9, s0, v7
	v_lshl_add_u32 v7, v8, s0, v7
	v_cos_f32_e32 v2, v3
	v_sin_f32_e32 v3, v3
	v_ashrrev_i32_e32 v10, 4, v9
	v_ashrrev_i32_e32 v8, 4, v7
	ds_write_b64 v24, v[4:5]
	v_add_lshl_u32 v22, v10, v9, 3
	v_lshlrev_b32_e32 v8, 3, v8
	v_lshlrev_b32_e32 v7, 3, v7
	v_add3_u32 v23, 0, v8, v7
	ds_read_b64 v[8:9], v20
	ds_read_b64 v[10:11], v21
	ds_read_b64 v[12:13], v22
	ds_read_b64 v[14:15], v23
	v_mul_f32_e32 v6, v2, v3
	v_pk_mul_f32 v[4:5], v[2:3], v[2:3]
	v_add_f32_e32 v6, v6, v6
	s_waitcnt lgkmcnt(2)
	v_pk_mul_f32 v[16:17], v[10:11], v[6:7] op_sel_hi:[1,0]
	v_pk_add_f32 v[4:5], v[4:5], v[4:5] op_sel:[0,1] op_sel_hi:[0,1] neg_lo:[0,1] neg_hi:[0,1]
	v_pk_fma_f32 v[18:19], v[10:11], v[4:5], v[16:17] op_sel:[0,0,1] op_sel_hi:[1,1,0] neg_lo:[0,0,1] neg_hi:[0,0,1]
	v_pk_fma_f32 v[10:11], v[10:11], v[4:5], v[16:17] op_sel:[0,0,1] op_sel_hi:[1,1,0]
	s_waitcnt lgkmcnt(0)
	v_pk_mul_f32 v[4:5], v[14:15], v[4:5]
	v_mov_b32_e32 v19, v11
	v_pk_fma_f32 v[16:17], v[14:15], v[6:7], v[4:5] op_sel:[0,0,1] op_sel_hi:[1,1,0]
	v_pk_fma_f32 v[4:5], v[14:15], v[6:7], v[4:5] op_sel:[0,0,1] op_sel_hi:[1,0,0] neg_lo:[1,0,0] neg_hi:[1,0,0]
	v_pk_add_f32 v[10:11], v[8:9], v[18:19] neg_lo:[0,1] neg_hi:[0,1]
	v_mov_b32_e32 v17, v5
	v_pk_add_f32 v[6:7], v[8:9], v[18:19]
	v_pk_add_f32 v[8:9], v[12:13], v[16:17] op_sel:[1,0] op_sel_hi:[0,1]
	v_pk_add_f32 v[4:5], v[12:13], v[16:17] op_sel:[1,0] op_sel_hi:[0,1] neg_lo:[0,1] neg_hi:[0,1]
	v_mov_b32_e32 v12, v3
	v_mov_b32_e32 v14, v3
	v_pk_mul_f32 v[16:17], v[2:3], v[8:9] op_sel_hi:[0,1]
	v_pk_fma_f32 v[12:13], v[12:13], v[8:9], v[16:17] op_sel:[0,0,1] op_sel_hi:[1,1,0] neg_lo:[1,0,0] neg_hi:[1,0,0]
	v_pk_fma_f32 v[8:9], v[14:15], v[8:9], v[16:17] op_sel:[0,0,1] op_sel_hi:[0,1,0]
	v_mov_b32_e32 v13, v9
	v_pk_add_f32 v[8:9], v[6:7], v[12:13]
	v_pk_add_f32 v[6:7], v[6:7], v[12:13] neg_lo:[0,1] neg_hi:[0,1]
	ds_write_b64 v20, v[8:9]
	ds_write_b64 v22, v[6:7]
	v_pk_mul_f32 v[6:7], v[14:15], v[4:5] op_sel_hi:[0,1]
	v_pk_fma_f32 v[8:9], v[2:3], v[4:5], v[6:7] op_sel:[0,0,1] op_sel_hi:[1,1,0]
	v_pk_fma_f32 v[2:3], v[2:3], v[4:5], v[6:7] op_sel:[0,0,1] op_sel_hi:[0,1,0] neg_lo:[0,0,1] neg_hi:[0,0,1]
	v_mov_b32_e32 v9, v3
	v_pk_add_f32 v[2:3], v[10:11], v[8:9] neg_lo:[0,1] neg_hi:[0,1]
	v_pk_add_f32 v[4:5], v[10:11], v[8:9]
	s_addk_i32 s13, 0x800
	v_mov_b32_e32 v6, v2
	v_mov_b32_e32 v7, v5
	v_mov_b32_e32 v5, v3
	s_cmpk_eq_i32 s13, 0x1000
	ds_write_b64 v21, v[6:7]
	ds_write_b64 v23, v[4:5]
	s_cbranch_scc0 .LBB0_485
	s_add_i32 s11, s0, 2
	s_cmp_gt_u32 s0, 10
	s_mov_b32 s1, s10
	s_mov_b32 s0, s11
	s_cbranch_scc0 .LBB0_484
	v_readlane_b32 s0, v254, 55
	s_add_i32 s0, s6, s0
	s_ashr_i32 s1, s0, 31
	v_readlane_b32 s16, v252, 46
	s_lshl_b64 s[0:1], s[0:1], 2
	v_readlane_b32 s22, v252, 52
	v_lshlrev_b32_e32 v1, 2, v52
	v_ashrrev_i32_e32 v51, 31, v50
	v_readlane_b32 s23, v252, 53
	s_add_u32 s0, s22, s0
	v_and_b32_e32 v1, -8, v1
	v_lshlrev_b32_e32 v38, 3, v50
	s_addc_u32 s1, s23, s1
	v_add3_u32 v63, 0, v1, v38
	v_lshl_add_u64 v[58:59], v[50:51], 3, s[56:57]
	s_waitcnt lgkmcnt(0)
	s_barrier
; DI void hyena_lat_item(const P& p, int l, int c, int bp, unsigned char* lds) {
;     ...
;       float2 y1v[16];
; #pragma unroll
;       for (int i = 0; i < 16; ++i) {
;         int n = (i >> 3) * 4096 + tid * 8 + (i & 7);
;         float2 cv = s[phys(n)], v = scr[n], x1 = scr[8192 + n];
;         y1v[i] = make_float2(x1.x * (cv.x * invN + v.x * bias), x1.y * (cv.y * invN + v.y * bias));
;         scr[24576 + n] = y1v[i];
;       }
	global_load_dword v62, v179, s[0:1]
	ds_read2_b64 v[2:5], v63 offset1:1
	global_load_dwordx4 v[18:21], v[58:59], off offset:48
	global_load_dwordx4 v[6:9], v[58:59], off offset:32
	global_load_dwordx4 v[10:13], v[58:59], off offset:16
	global_load_dwordx4 v[14:17], v[58:59], off
	s_mov_b64 s[12:13], 0x10000
	v_add_co_u32_e32 v22, vcc, s65, v58
	v_lshl_add_u64 v[34:35], v[58:59], 0, s[12:13]
	s_nop 0
	v_addc_co_u32_e32 v23, vcc, 0, v59, vcc
	global_load_dwordx4 v[22:25], v[22:23], off
	s_nop 0
	global_load_dwordx4 v[26:29], v[34:35], off offset:48
	global_load_dwordx4 v[30:33], v[34:35], off offset:32
	s_nop 0
	global_load_dwordx4 v[34:37], v[34:35], off offset:16
	v_readlane_b32 s18, v252, 48
	v_readlane_b32 s19, v252, 49
	s_mov_b32 s18, 0x38800000
	s_mov_b32 s10, 0x30000
	s_mov_b64 s[0:1], 0x38000
	v_lshl_add_u64 v[48:49], v[58:59], 0, s[0:1]
	s_mov_b32 s0, 0x18000
	v_add_u32_e32 v1, 0x1000, v50
	v_ashrrev_i32_e32 v1, 4, v1
	v_lshlrev_b32_e32 v1, 3, v1
	v_add3_u32 v53, 0, v1, v38
	v_add_u32_e32 v1, 0x8000, v53
	v_readlane_b32 s17, v252, 47
	s_mov_b64 s[16:17], 0x30000
	v_lshl_add_u64 v[46:47], v[58:59], 0, s[78:79]
	v_lshl_add_u64 v[60:61], v[58:59], 0, s[16:17]
	v_readlane_b32 s20, v252, 50
	v_readlane_b32 s21, v252, 51
	v_readlane_b32 s24, v252, 54
	v_readlane_b32 s25, v252, 55
	v_readlane_b32 s26, v252, 56
	v_readlane_b32 s27, v252, 57
	v_readlane_b32 s28, v252, 58
	v_readlane_b32 s29, v252, 59
	v_readlane_b32 s30, v252, 60
	v_readlane_b32 s31, v252, 61
	s_waitcnt vmcnt(6)
	v_pk_mul_f32 v[6:7], v[62:63], v[6:7] op_sel_hi:[0,1]
	s_waitcnt vmcnt(5)
	v_pk_mul_f32 v[10:11], v[62:63], v[10:11] op_sel_hi:[0,1]
	s_waitcnt vmcnt(4)
	v_pk_mul_f32 v[14:15], v[62:63], v[14:15] op_sel_hi:[0,1]
	s_waitcnt lgkmcnt(0)
	v_pk_fma_f32 v[2:3], v[2:3], s[18:19], v[14:15] op_sel_hi:[1,0,1]
	v_pk_mul_f32 v[18:19], v[62:63], v[18:19] op_sel_hi:[0,1]
	s_waitcnt vmcnt(3)
	v_pk_mul_f32 v[14:15], v[22:23], v[2:3]
	v_pk_mul_f32 v[2:3], v[62:63], v[16:17] op_sel_hi:[0,1]
	v_pk_fma_f32 v[2:3], v[4:5], s[18:19], v[2:3] op_sel_hi:[1,0,1]
	v_add_co_u32_e32 v22, vcc, s10, v58
	v_pk_mul_f32 v[16:17], v[24:25], v[2:3]
	ds_read2_b64 v[2:5], v63 offset0:2 offset1:3
	v_addc_co_u32_e32 v23, vcc, 0, v59, vcc
	global_store_dwordx4 v[22:23], v[14:17], off
	s_waitcnt lgkmcnt(0)
	v_pk_fma_f32 v[2:3], v[2:3], s[18:19], v[10:11] op_sel_hi:[1,0,1]
	s_waitcnt vmcnt(1)
	v_pk_mul_f32 v[10:11], v[34:35], v[2:3]
	v_pk_mul_f32 v[2:3], v[62:63], v[12:13] op_sel_hi:[0,1]
	v_pk_fma_f32 v[2:3], v[4:5], s[18:19], v[2:3] op_sel_hi:[1,0,1]
	s_nop 0
	v_pk_mul_f32 v[12:13], v[36:37], v[2:3]
	ds_read2_b64 v[2:5], v63 offset0:4 offset1:5
	global_store_dwordx4 v[22:23], v[10:13], off offset:16
	s_waitcnt lgkmcnt(0)
	v_pk_fma_f32 v[2:3], v[2:3], s[18:19], v[6:7] op_sel_hi:[1,0,1]
	s_nop 0
	v_pk_mul_f32 v[6:7], v[30:31], v[2:3]
	v_pk_mul_f32 v[2:3], v[62:63], v[8:9] op_sel_hi:[0,1]
	v_pk_fma_f32 v[2:3], v[4:5], s[18:19], v[2:3] op_sel_hi:[1,0,1]
	s_nop 0
	v_pk_mul_f32 v[8:9], v[32:33], v[2:3]
	ds_read2_b64 v[2:5], v63 offset0:6 offset1:7
	global_store_dwordx4 v[22:23], v[6:9], off offset:32
	s_waitcnt lgkmcnt(0)
	v_pk_fma_f32 v[2:3], v[2:3], s[18:19], v[18:19] op_sel_hi:[1,0,1]
	v_pk_mul_f32 v[18:19], v[62:63], v[20:21] op_sel_hi:[0,1]
	v_pk_fma_f32 v[4:5], v[4:5], s[18:19], v[18:19] op_sel_hi:[1,0,1]
	v_pk_mul_f32 v[2:3], v[26:27], v[2:3]
	v_pk_mul_f32 v[4:5], v[28:29], v[4:5]
	global_store_dwordx4 v[22:23], v[2:5], off offset:48
	v_add_co_u32_e32 v22, vcc, s2, v58
	ds_read2_b64 v[18:21], v1 offset1:1
	s_nop 0
	v_addc_co_u32_e32 v23, vcc, 0, v59, vcc
	global_load_dwordx2 v[22:23], v[22:23], off
	v_add_co_u32_e32 v24, vcc, s0, v58
	s_mov_b32 s0, 0x38000
	s_nop 0
	v_addc_co_u32_e32 v25, vcc, 0, v59, vcc
	global_load_dwordx2 v[24:25], v[24:25], off
	s_waitcnt vmcnt(1)
	v_pk_mul_f32 v[22:23], v[62:63], v[22:23] op_sel_hi:[0,1]
	s_waitcnt lgkmcnt(0)
	v_pk_fma_f32 v[18:19], v[18:19], s[18:19], v[22:23] op_sel_hi:[1,0,1]
	s_waitcnt vmcnt(0)
	v_pk_mul_f32 v[64:65], v[24:25], v[18:19]
	v_add_co_u32_e32 v18, vcc, s0, v58
	s_mov_b32 s0, 12
	s_nop 0
	v_addc_co_u32_e32 v19, vcc, 0, v59, vcc
	global_store_dwordx2 v[18:19], v[64:65], off
	v_add_u32_e32 v18, 0x1001, v50
	v_ashrrev_i32_e32 v19, 31, v18
	v_lshl_add_u64 v[54:55], v[18:19], 3, s[56:57]
	global_load_dwordx4 v[22:25], v[54:55], off offset:32
	global_load_dwordx4 v[30:33], v[54:55], off offset:16
	global_load_dwordx4 v[38:41], v[54:55], off
	global_load_dwordx2 v[66:67], v[54:55], off offset:48
	v_add_co_u32_e32 v26, vcc, s65, v54
	v_lshl_add_u64 v[18:19], v[54:55], 0, s[12:13]
	s_nop 0
	v_addc_co_u32_e32 v27, vcc, 0, v55, vcc
	global_load_dwordx4 v[42:45], v[26:27], off
	s_nop 0
	global_load_dwordx4 v[26:29], v[18:19], off offset:32
	global_load_dwordx4 v[34:37], v[18:19], off offset:16
	global_load_dwordx2 v[68:69], v[18:19], off offset:48
	v_lshl_add_u64 v[56:57], v[54:55], 0, s[16:17]
	s_waitcnt vmcnt(7)
	v_pk_mul_f32 v[22:23], v[62:63], v[22:23] op_sel_hi:[0,1]
	s_waitcnt vmcnt(6)
	v_pk_mul_f32 v[30:31], v[62:63], v[30:31] op_sel_hi:[0,1]
	s_waitcnt vmcnt(5)
	v_pk_mul_f32 v[18:19], v[62:63], v[38:39] op_sel_hi:[0,1]
	v_add_u32_e32 v38, 0x8010, v53
	ds_read2_b64 v[72:75], v38 offset1:1
	v_pk_fma_f32 v[18:19], v[20:21], s[18:19], v[18:19] op_sel_hi:[1,0,1]
	v_pk_mul_f32 v[20:21], v[62:63], v[40:41] op_sel_hi:[0,1]
	v_add_co_u32_e32 v40, vcc, s10, v54
	s_waitcnt lgkmcnt(0)
; DI void hyena_lat_item(const P& p, int l, int c, int bp, unsigned char* lds) {
;     ...
;       for (int i = 0; i < 16; ++i) {
;         int n = (i >> 3) * 4096 + tid * 8 + (i & 7);
;         float2 cv = s[phys(n)], v = scr[n], x1 = scr[8192 + n];
;         y1v[i] = make_float2(x1.x * (cv.x * invN + v.x * bias), x1.y * (cv.y * invN + v.y * bias));
;         scr[24576 + n] = y1v[i];
;       }
;       __syncthreads();
; #pragma unroll
;       for (int i = 0; i < 16; ++i) { int n = (i >> 3) * 4096 + tid * 8 + (i & 7); s[phys(n)] = y1v[i]; s[phys(n + L)] = make_float2(0.f, 0.f); }
	v_pk_fma_f32 v[20:21], v[72:73], s[18:19], v[20:21] op_sel_hi:[1,0,1]
	s_waitcnt vmcnt(3)
	v_pk_mul_f32 v[18:19], v[42:43], v[18:19]
	v_pk_mul_f32 v[20:21], v[44:45], v[20:21]
	v_addc_co_u32_e32 v41, vcc, 0, v55, vcc
	global_store_dwordx4 v[40:41], v[18:21], off
	v_add_u32_e32 v40, 0x1003, v50
	v_pk_fma_f32 v[30:31], v[74:75], s[18:19], v[30:31] op_sel_hi:[1,0,1]
	v_ashrrev_i32_e32 v41, 31, v40
	s_waitcnt vmcnt(2)
	v_pk_mul_f32 v[34:35], v[34:35], v[30:31]
	v_add_u32_e32 v30, 0x8020, v53
	v_lshl_add_u64 v[44:45], v[40:41], 3, s[56:57]
	ds_read2_b64 v[40:43], v30 offset1:1
	v_pk_mul_f32 v[32:33], v[62:63], v[32:33] op_sel_hi:[0,1]
	v_pk_mul_f32 v[24:25], v[62:63], v[24:25] op_sel_hi:[0,1]
	s_waitcnt lgkmcnt(0)
	v_pk_fma_f32 v[32:33], v[40:41], s[18:19], v[32:33] op_sel_hi:[1,0,1]
	s_nop 0
	v_pk_mul_f32 v[36:37], v[36:37], v[32:33]
	v_add_co_u32_e32 v32, vcc, s10, v44
	v_pk_fma_f32 v[22:23], v[42:43], s[18:19], v[22:23] op_sel_hi:[1,0,1]
	s_nop 0
	v_addc_co_u32_e32 v33, vcc, 0, v45, vcc
	global_store_dwordx4 v[32:33], v[34:37], off
	v_add_u32_e32 v32, 0x1005, v50
	v_ashrrev_i32_e32 v33, 31, v32
	v_lshl_add_u64 v[44:45], v[32:33], 3, s[56:57]
	v_add_u32_e32 v32, 0x8030, v53
	ds_read2_b64 v[40:43], v32 offset1:1
	v_pk_mul_f32 v[22:23], v[26:27], v[22:23]
	v_add_co_u32_e32 v26, vcc, s10, v44
	s_waitcnt lgkmcnt(0)
	v_pk_fma_f32 v[24:25], v[40:41], s[18:19], v[24:25] op_sel_hi:[1,0,1]
	s_nop 0
	v_pk_mul_f32 v[24:25], v[28:29], v[24:25]
	v_addc_co_u32_e32 v27, vcc, 0, v45, vcc
	global_store_dwordx4 v[26:27], v[22:25], off
	v_add_u32_e32 v26, 0x1007, v50
	v_ashrrev_i32_e32 v27, 31, v26
	v_lshl_add_u64 v[26:27], v[26:27], 3, s[56:57]
	v_pk_mul_f32 v[28:29], v[62:63], v[66:67] op_sel_hi:[0,1]
	v_pk_fma_f32 v[28:29], v[42:43], s[18:19], v[28:29] op_sel_hi:[1,0,1]
	v_add_co_u32_e32 v26, vcc, s10, v26
	s_waitcnt vmcnt(3)
	v_pk_mul_f32 v[28:29], v[68:69], v[28:29]
	v_addc_co_u32_e32 v27, vcc, 0, v27, vcc
	global_store_dwordx2 v[26:27], v[28:29], off
	s_barrier
	ds_write_b64 v63, v[14:15]
	v_add_u32_e32 v14, 0x2000, v50
	v_ashrrev_i32_e32 v15, 4, v14
	v_lshlrev_b32_e32 v15, 3, v15
	v_lshlrev_b32_e32 v14, 3, v14
	v_add3_u32 v14, 0, v15, v14
	ds_write_b64 v14, v[230:231]
	ds_write_b64 v63, v[16:17] offset:8
	v_add_u32_e32 v14, 0x2001, v50
	v_ashrrev_i32_e32 v15, 4, v14
	v_lshlrev_b32_e32 v15, 3, v15
	v_lshlrev_b32_e32 v14, 3, v14
	v_add3_u32 v14, 0, v15, v14
	ds_write_b64 v14, v[230:231]
	ds_write_b64 v63, v[10:11] offset:16
	v_add_u32_e32 v10, 0x2002, v50
	v_ashrrev_i32_e32 v11, 4, v10
	v_lshlrev_b32_e32 v11, 3, v11
	v_lshlrev_b32_e32 v10, 3, v10
	v_add3_u32 v10, 0, v11, v10
	ds_write_b64 v10, v[230:231]
	ds_write_b64 v63, v[12:13] offset:24
	v_add_u32_e32 v10, 0x2003, v50
	v_ashrrev_i32_e32 v11, 4, v10
	v_lshlrev_b32_e32 v11, 3, v11
	v_lshlrev_b32_e32 v10, 3, v10
	v_add3_u32 v10, 0, v11, v10
	ds_write_b64 v10, v[230:231]
	ds_write_b64 v63, v[6:7] offset:32
	v_add_u32_e32 v6, 0x2004, v50
	v_ashrrev_i32_e32 v7, 4, v6
	v_lshlrev_b32_e32 v7, 3, v7
	v_lshlrev_b32_e32 v6, 3, v6
	v_add3_u32 v6, 0, v7, v6
	ds_write_b64 v6, v[230:231]
	ds_write_b64 v63, v[8:9] offset:40
	v_add_u32_e32 v6, 0x2005, v50
	v_ashrrev_i32_e32 v7, 4, v6
	v_lshlrev_b32_e32 v7, 3, v7
	v_lshlrev_b32_e32 v6, 3, v6
	v_add3_u32 v6, 0, v7, v6
	ds_write_b64 v6, v[230:231]
	ds_write_b64 v63, v[2:3] offset:48
	v_add_u32_e32 v2, 0x2006, v50
	v_ashrrev_i32_e32 v3, 4, v2
	v_lshlrev_b32_e32 v3, 3, v3
	v_lshlrev_b32_e32 v2, 3, v2
	v_add3_u32 v2, 0, v3, v2
	ds_write_b64 v2, v[230:231]
	ds_write_b64 v63, v[4:5] offset:56
	v_add_u32_e32 v2, 0x2007, v50
	v_ashrrev_i32_e32 v3, 4, v2
	v_lshlrev_b32_e32 v3, 3, v3
	v_lshlrev_b32_e32 v2, 3, v2
	v_add3_u32 v2, 0, v3, v2
	ds_write_b64 v2, v[230:231]
	ds_write_b64 v53, v[64:65] offset:32768
	v_add_u32_e32 v2, 0x3000, v50
	v_ashrrev_i32_e32 v3, 4, v2
	v_lshlrev_b32_e32 v3, 3, v3
	v_lshlrev_b32_e32 v2, 3, v2
	v_add3_u32 v2, 0, v3, v2
	ds_write_b64 v2, v[230:231]
	ds_write_b64 v53, v[18:19] offset:32776
	v_add_u32_e32 v2, 0x3001, v50
	v_ashrrev_i32_e32 v3, 4, v2
	v_lshlrev_b32_e32 v3, 3, v3
	v_lshlrev_b32_e32 v2, 3, v2
	v_add3_u32 v2, 0, v3, v2
	ds_write_b64 v2, v[230:231]
	ds_write_b64 v53, v[20:21] offset:32784
	v_add_u32_e32 v2, 0x3002, v50
	v_ashrrev_i32_e32 v3, 4, v2
	v_lshlrev_b32_e32 v3, 3, v3
	v_lshlrev_b32_e32 v2, 3, v2
	v_add3_u32 v2, 0, v3, v2
	ds_write_b64 v2, v[230:231]
	ds_write_b64 v53, v[34:35] offset:32792
	v_add_u32_e32 v2, 0x3003, v50
	v_ashrrev_i32_e32 v3, 4, v2
	v_lshlrev_b32_e32 v3, 3, v3
	v_lshlrev_b32_e32 v2, 3, v2
	v_add3_u32 v2, 0, v3, v2
	ds_write_b64 v2, v[230:231]
	ds_write_b64 v53, v[36:37] offset:32800
	v_add_u32_e32 v2, 0x3004, v50
	v_ashrrev_i32_e32 v3, 4, v2
	v_lshlrev_b32_e32 v3, 3, v3
	v_lshlrev_b32_e32 v2, 3, v2
	v_add3_u32 v2, 0, v3, v2
	ds_write_b64 v2, v[230:231]
	ds_write_b64 v53, v[22:23] offset:32808
	v_add_u32_e32 v2, 0x3005, v50
	v_ashrrev_i32_e32 v3, 4, v2
	v_lshlrev_b32_e32 v3, 3, v3
	v_lshlrev_b32_e32 v2, 3, v2
	v_add3_u32 v2, 0, v3, v2
	ds_write_b64 v2, v[230:231]
	ds_write_b64 v53, v[24:25] offset:32816
	v_add_u32_e32 v2, 0x3006, v50
	v_ashrrev_i32_e32 v3, 4, v2
	v_lshlrev_b32_e32 v3, 3, v3
	v_lshlrev_b32_e32 v2, 3, v2
	v_add3_u32 v2, 0, v3, v2
	ds_write_b64 v2, v[230:231]
	ds_write_b64 v53, v[28:29] offset:32824
	v_add_u32_e32 v2, 0x3007, v50
	v_ashrrev_i32_e32 v3, 4, v2
	v_lshlrev_b32_e32 v3, 3, v3
	v_lshlrev_b32_e32 v2, 3, v2
	v_add3_u32 v2, 0, v3, v2
	ds_write_b64 v2, v[230:231]
	v_mov_b32_e32 v2, v215

; DI float sin_t(float turns) { return __builtin_amdgcn_sinf(__builtin_amdgcn_fractf(turns)); }
; DI float cos_t(float turns) { return __builtin_amdgcn_cosf(__builtin_amdgcn_fractf(turns)); }
; DI float2 cmul(float2 a, float2 b) { return make_float2(a.x * b.x - a.y * b.y, a.x * b.y + a.y * b.x); }
; template <int N, bool INV>
; DI void fft_lds(float2* s) {
;     ...
;     for (int lq = (LG & 1) ? LG - 3 : LG - 2; lq >= 0; lq -= 2) {
;       const int q = 1 << lq;
;       __syncthreads();
;       const float inv4q = 1.0f / (float)(4 * q);
; #pragma unroll 4
;       for (int it = 0; it < N / 4 / NT; ++it) {
;         int idx = tid + it * NT;
;         int j = idx & (q - 1), blk = idx >> lq;
;         int p0 = blk * 4 * q + j;
;         float f = (float)j * inv4q;
;         float2 t1 = make_float2(cos_t(f), -sin_t(f));
;         float2 t2 = cmul(t1, t1);
;         float2 x0 = s[phys(p0)], x1 = s[phys(p0 + q)], x2 = s[phys(p0 + 2 * q)], x3 = s[phys(p0 + 3 * q)];
;         float2 a0 = make_float2(x0.x + x2.x, x0.y + x2.y);
;         float2 a2 = cmul(make_float2(x0.x - x2.x, x0.y - x2.y), t1);
;         float2 a1 = make_float2(x1.x + x3.x, x1.y + x3.y);
;         float2 d3 = make_float2(x1.x - x3.x, x1.y - x3.y);
;         float2 a3 = cmul(make_float2(d3.y, -d3.x), t1);
;         s[phys(p0)] = make_float2(a0.x + a1.x, a0.y + a1.y);
;         s[phys(p0 + q)] = cmul(make_float2(a0.x - a1.x, a0.y - a1.y), t2);
;         s[phys(p0 + 2 * q)] = make_float2(a2.x + a3.x, a2.y + a3.y);
;         s[phys(p0 + 3 * q)] = cmul(make_float2(a2.x - a3.x, a2.y - a3.y), t2);
;       }
.LBB0_489:
	v_add_u32_e32 v21, s11, v2
	v_ashrrev_i32_e32 v4, s0, v21
	v_and_b32_e32 v9, s10, v21
	v_lshlrev_b32_e32 v10, 2, v4
	v_lshl_add_u32 v11, v10, s0, v9
	v_ashrrev_i32_e32 v12, 4, v11
	v_add_lshl_u32 v26, v12, v11, 3
	v_add_u32_e32 v11, s1, v11
	v_cvt_f32_u32_e32 v4, v9
	v_ashrrev_i32_e32 v12, 4, v11
	v_add_lshl_u32 v27, v12, v11, 3
	v_or_b32_e32 v11, 2, v10
	v_or_b32_e32 v10, 3, v10
	v_lshl_add_u32 v11, v11, s0, v9
	v_lshl_add_u32 v9, v10, s0, v9
	v_mul_f32_e32 v4, v3, v4
	v_ashrrev_i32_e32 v12, 4, v11
	v_ashrrev_i32_e32 v10, 4, v9
	v_fract_f32_e32 v5, v4
	v_add_lshl_u32 v28, v12, v11, 3
	v_add_lshl_u32 v29, v10, v9, 3
	v_cos_f32_e32 v4, v5
	v_sin_f32_e32 v5, v5
	ds_read_b64 v[10:11], v26
	ds_read_b64 v[12:13], v27
	ds_read_b64 v[14:15], v28
	ds_read_b64 v[16:17], v29
	v_mov_b32_e32 v20, v5
	v_mul_f32_e64 v8, v4, -v5
	v_pk_mul_f32 v[6:7], v[4:5], v[4:5]
	s_waitcnt lgkmcnt(1)
	v_pk_add_f32 v[18:19], v[10:11], v[14:15] neg_lo:[0,1] neg_hi:[0,1]
	v_pk_add_f32 v[10:11], v[10:11], v[14:15]
	v_pk_mul_f32 v[22:23], v[20:21], v[18:19] op_sel_hi:[0,1]
	v_pk_fma_f32 v[24:25], v[18:19], v[4:5], v[22:23] op_sel:[0,0,1] op_sel_hi:[1,1,0]
	v_pk_fma_f32 v[18:19], v[18:19], v[4:5], v[22:23] op_sel:[0,0,1] op_sel_hi:[1,0,0] neg_lo:[0,0,1] neg_hi:[0,0,1]
	v_add_f32_e32 v8, v8, v8
	v_mov_b32_e32 v25, v19
	s_waitcnt lgkmcnt(0)
	v_pk_add_f32 v[18:19], v[12:13], v[16:17] neg_lo:[0,1] neg_hi:[0,1]
	v_pk_add_f32 v[12:13], v[12:13], v[16:17]
	v_xor_b32_e32 v23, 0x80000000, v18
	v_pk_add_f32 v[14:15], v[10:11], v[12:13]
	v_pk_add_f32 v[10:11], v[10:11], v[12:13] neg_lo:[0,1] neg_hi:[0,1]
	v_mov_b32_e32 v22, v19
	v_pk_mul_f32 v[18:19], v[20:21], v[18:19] op_sel_hi:[0,1]
	v_pk_mul_f32 v[12:13], v[8:9], v[10:11] op_sel_hi:[0,1]
	v_pk_add_f32 v[6:7], v[6:7], v[6:7] op_sel:[0,1] op_sel_hi:[0,1] neg_lo:[0,1] neg_hi:[0,1]
	v_pk_fma_f32 v[4:5], v[4:5], v[22:23], v[18:19] op_sel_hi:[0,1,1] neg_lo:[0,0,1] neg_hi:[0,0,1]
	ds_write_b64 v26, v[14:15]
	v_pk_fma_f32 v[14:15], v[6:7], v[10:11], v[12:13] op_sel:[0,0,1] op_sel_hi:[1,1,0] neg_lo:[0,0,1] neg_hi:[0,0,1]
	v_pk_fma_f32 v[10:11], v[6:7], v[10:11], v[12:13] op_sel:[0,0,1] op_sel_hi:[1,1,0]
	s_addk_i32 s11, 0x800
	v_mov_b32_e32 v15, v11
	v_pk_add_f32 v[10:11], v[24:25], v[4:5]
	v_pk_add_f32 v[4:5], v[24:25], v[4:5] neg_lo:[0,1] neg_hi:[0,1]
	ds_write_b64 v27, v[14:15]
	v_pk_mul_f32 v[8:9], v[8:9], v[4:5] op_sel_hi:[0,1]
	ds_write_b64 v28, v[10:11]
	v_pk_fma_f32 v[10:11], v[6:7], v[4:5], v[8:9] op_sel:[0,0,1] op_sel_hi:[1,1,0] neg_lo:[0,0,1] neg_hi:[0,0,1]
	v_pk_fma_f32 v[4:5], v[6:7], v[4:5], v[8:9] op_sel:[0,0,1] op_sel_hi:[1,1,0]
	s_cmpk_lg_i32 s11, 0x1000
	v_add_u32_e32 v4, 0x200, v21
	v_mov_b32_e32 v11, v5
	v_and_b32_e32 v9, s10, v4
	v_ashrrev_i32_e32 v4, s0, v4
	ds_write_b64 v29, v[10:11]
	v_lshlrev_b32_e32 v10, 2, v4
	v_lshl_add_u32 v11, v10, s0, v9
	v_ashrrev_i32_e32 v12, 4, v11
	v_add_lshl_u32 v26, v12, v11, 3
	v_add_u32_e32 v11, s1, v11
	v_cvt_f32_u32_e32 v4, v9
	v_ashrrev_i32_e32 v12, 4, v11
	v_add_lshl_u32 v27, v12, v11, 3
	v_or_b32_e32 v11, 2, v10
	v_or_b32_e32 v10, 3, v10
	v_lshl_add_u32 v11, v11, s0, v9
	v_lshl_add_u32 v9, v10, s0, v9
	v_mul_f32_e32 v4, v3, v4
	v_ashrrev_i32_e32 v12, 4, v11
	v_ashrrev_i32_e32 v10, 4, v9
	v_fract_f32_e32 v5, v4
	v_add_lshl_u32 v28, v12, v11, 3
	v_add_lshl_u32 v29, v10, v9, 3
	v_cos_f32_e32 v4, v5
	v_sin_f32_e32 v5, v5
	ds_read_b64 v[10:11], v26
	ds_read_b64 v[12:13], v27
	ds_read_b64 v[14:15], v28
	ds_read_b64 v[16:17], v29
	v_mov_b32_e32 v20, v5
	v_mul_f32_e64 v8, v4, -v5
	v_pk_mul_f32 v[6:7], v[4:5], v[4:5]
	s_waitcnt lgkmcnt(1)
	v_pk_add_f32 v[18:19], v[10:11], v[14:15] neg_lo:[0,1] neg_hi:[0,1]
	v_pk_add_f32 v[10:11], v[10:11], v[14:15]
	v_pk_mul_f32 v[22:23], v[20:21], v[18:19] op_sel_hi:[0,1]
	v_pk_fma_f32 v[24:25], v[18:19], v[4:5], v[22:23] op_sel:[0,0,1] op_sel_hi:[1,1,0]
	v_pk_fma_f32 v[18:19], v[18:19], v[4:5], v[22:23] op_sel:[0,0,1] op_sel_hi:[1,0,0] neg_lo:[0,0,1] neg_hi:[0,0,1]
	v_add_f32_e32 v8, v8, v8
	v_mov_b32_e32 v25, v19
	s_waitcnt lgkmcnt(0)
	v_pk_add_f32 v[18:19], v[12:13], v[16:17] neg_lo:[0,1] neg_hi:[0,1]
	v_pk_add_f32 v[12:13], v[12:13], v[16:17]
	v_xor_b32_e32 v23, 0x80000000, v18
	v_pk_add_f32 v[14:15], v[10:11], v[12:13]
	v_pk_add_f32 v[10:11], v[10:11], v[12:13] neg_lo:[0,1] neg_hi:[0,1]
	v_mov_b32_e32 v22, v19
	v_pk_mul_f32 v[18:19], v[20:21], v[18:19] op_sel_hi:[0,1]
	v_pk_mul_f32 v[12:13], v[8:9], v[10:11] op_sel_hi:[0,1]
	v_pk_add_f32 v[6:7], v[6:7], v[6:7] op_sel:[0,1] op_sel_hi:[0,1] neg_lo:[0,1] neg_hi:[0,1]
	v_pk_fma_f32 v[4:5], v[4:5], v[22:23], v[18:19] op_sel_hi:[0,1,1] neg_lo:[0,0,1] neg_hi:[0,0,1]
	ds_write_b64 v26, v[14:15]
	v_pk_fma_f32 v[14:15], v[6:7], v[10:11], v[12:13] op_sel:[0,0,1] op_sel_hi:[1,1,0] neg_lo:[0,0,1] neg_hi:[0,0,1]
	v_pk_fma_f32 v[10:11], v[6:7], v[10:11], v[12:13] op_sel:[0,0,1] op_sel_hi:[1,1,0]
	s_nop 0
	v_mov_b32_e32 v15, v11
	v_pk_add_f32 v[10:11], v[24:25], v[4:5]
	v_pk_add_f32 v[4:5], v[24:25], v[4:5] neg_lo:[0,1] neg_hi:[0,1]
	ds_write_b64 v27, v[14:15]
	v_pk_mul_f32 v[8:9], v[8:9], v[4:5] op_sel_hi:[0,1]
	ds_write_b64 v28, v[10:11]
	v_pk_fma_f32 v[10:11], v[6:7], v[4:5], v[8:9] op_sel:[0,0,1] op_sel_hi:[1,1,0] neg_lo:[0,0,1] neg_hi:[0,0,1]
	v_pk_fma_f32 v[4:5], v[6:7], v[4:5], v[8:9] op_sel:[0,0,1] op_sel_hi:[1,1,0]
	s_nop 0
	v_add_u32_e32 v4, 0x400, v21
	v_mov_b32_e32 v11, v5
	v_and_b32_e32 v9, s10, v4
	v_ashrrev_i32_e32 v4, s0, v4
	ds_write_b64 v29, v[10:11]
	v_lshlrev_b32_e32 v10, 2, v4
	v_lshl_add_u32 v11, v10, s0, v9
	v_ashrrev_i32_e32 v12, 4, v11
	v_add_lshl_u32 v26, v12, v11, 3
	v_add_u32_e32 v11, s1, v11
	v_cvt_f32_u32_e32 v4, v9
	v_ashrrev_i32_e32 v12, 4, v11
	v_add_lshl_u32 v27, v12, v11, 3
	v_or_b32_e32 v11, 2, v10
	v_or_b32_e32 v10, 3, v10
	v_lshl_add_u32 v11, v11, s0, v9
	v_lshl_add_u32 v9, v10, s0, v9
	v_mul_f32_e32 v4, v3, v4
	v_ashrrev_i32_e32 v12, 4, v11
	v_ashrrev_i32_e32 v10, 4, v9
	v_fract_f32_e32 v5, v4
	v_add_lshl_u32 v28, v12, v11, 3
	v_add_lshl_u32 v29, v10, v9, 3
	v_cos_f32_e32 v4, v5
	v_sin_f32_e32 v5, v5
	ds_read_b64 v[10:11], v26
	ds_read_b64 v[12:13], v27
	ds_read_b64 v[14:15], v28
	ds_read_b64 v[16:17], v29
	v_mov_b32_e32 v20, v5
	v_mul_f32_e64 v8, v4, -v5
	v_pk_mul_f32 v[6:7], v[4:5], v[4:5]
	s_waitcnt lgkmcnt(1)
; DI float sin_t(float turns) { return __builtin_amdgcn_sinf(__builtin_amdgcn_fractf(turns)); }
; DI float cos_t(float turns) { return __builtin_amdgcn_cosf(__builtin_amdgcn_fractf(turns)); }
; DI float2 cmul(float2 a, float2 b) { return make_float2(a.x * b.x - a.y * b.y, a.x * b.y + a.y * b.x); }
; template <int N, bool INV>
; DI void fft_lds(float2* s) {
;     ...
;       for (int it = 0; it < N / 4 / NT; ++it) {
;         int idx = tid + it * NT;
;         int j = idx & (q - 1), blk = idx >> lq;
;         int p0 = blk * 4 * q + j;
;         float f = (float)j * inv4q;
;         float2 t1 = make_float2(cos_t(f), -sin_t(f));
;         float2 t2 = cmul(t1, t1);
;         float2 x0 = s[phys(p0)], x1 = s[phys(p0 + q)], x2 = s[phys(p0 + 2 * q)], x3 = s[phys(p0 + 3 * q)];
;         float2 a0 = make_float2(x0.x + x2.x, x0.y + x2.y);
;         float2 a2 = cmul(make_float2(x0.x - x2.x, x0.y - x2.y), t1);
;         float2 a1 = make_float2(x1.x + x3.x, x1.y + x3.y);
;         float2 d3 = make_float2(x1.x - x3.x, x1.y - x3.y);
;         float2 a3 = cmul(make_float2(d3.y, -d3.x), t1);
;         s[phys(p0)] = make_float2(a0.x + a1.x, a0.y + a1.y);
;         s[phys(p0 + q)] = cmul(make_float2(a0.x - a1.x, a0.y - a1.y), t2);
;         s[phys(p0 + 2 * q)] = make_float2(a2.x + a3.x, a2.y + a3.y);
;         s[phys(p0 + 3 * q)] = cmul(make_float2(a2.x - a3.x, a2.y - a3.y), t2);
;       }
; DI void hyena_lat_item(const P& p, int l, int c, int bp, unsigned char* lds) {
;     ...
;     for (int i = tid; i < 16384; i += NT) { s[phys(i)] = cmul(s[phys(i)], H[i]); }
	v_pk_add_f32 v[18:19], v[10:11], v[14:15] neg_lo:[0,1] neg_hi:[0,1]
	v_pk_add_f32 v[10:11], v[10:11], v[14:15]
	v_pk_mul_f32 v[22:23], v[20:21], v[18:19] op_sel_hi:[0,1]
	v_pk_fma_f32 v[24:25], v[18:19], v[4:5], v[22:23] op_sel:[0,0,1] op_sel_hi:[1,1,0]
	v_pk_fma_f32 v[18:19], v[18:19], v[4:5], v[22:23] op_sel:[0,0,1] op_sel_hi:[1,0,0] neg_lo:[0,0,1] neg_hi:[0,0,1]
	v_add_f32_e32 v8, v8, v8
	v_mov_b32_e32 v25, v19
	s_waitcnt lgkmcnt(0)
	v_pk_add_f32 v[18:19], v[12:13], v[16:17] neg_lo:[0,1] neg_hi:[0,1]
	v_pk_add_f32 v[12:13], v[12:13], v[16:17]
	v_xor_b32_e32 v23, 0x80000000, v18
	v_pk_add_f32 v[14:15], v[10:11], v[12:13]
	v_pk_add_f32 v[10:11], v[10:11], v[12:13] neg_lo:[0,1] neg_hi:[0,1]
	v_mov_b32_e32 v22, v19
	v_pk_mul_f32 v[18:19], v[20:21], v[18:19] op_sel_hi:[0,1]
	v_pk_mul_f32 v[12:13], v[8:9], v[10:11] op_sel_hi:[0,1]
	v_pk_add_f32 v[6:7], v[6:7], v[6:7] op_sel:[0,1] op_sel_hi:[0,1] neg_lo:[0,1] neg_hi:[0,1]
	v_pk_fma_f32 v[4:5], v[4:5], v[22:23], v[18:19] op_sel_hi:[0,1,1] neg_lo:[0,0,1] neg_hi:[0,0,1]
	ds_write_b64 v26, v[14:15]
	v_pk_fma_f32 v[14:15], v[6:7], v[10:11], v[12:13] op_sel:[0,0,1] op_sel_hi:[1,1,0] neg_lo:[0,0,1] neg_hi:[0,0,1]
	v_pk_fma_f32 v[10:11], v[6:7], v[10:11], v[12:13] op_sel:[0,0,1] op_sel_hi:[1,1,0]
	s_nop 0
	v_mov_b32_e32 v15, v11
	v_pk_add_f32 v[10:11], v[24:25], v[4:5]
	v_pk_add_f32 v[4:5], v[24:25], v[4:5] neg_lo:[0,1] neg_hi:[0,1]
	ds_write_b64 v27, v[14:15]
	v_pk_mul_f32 v[8:9], v[8:9], v[4:5] op_sel_hi:[0,1]
	ds_write_b64 v28, v[10:11]
	v_pk_fma_f32 v[10:11], v[6:7], v[4:5], v[8:9] op_sel:[0,0,1] op_sel_hi:[1,1,0] neg_lo:[0,0,1] neg_hi:[0,0,1]
	v_pk_fma_f32 v[4:5], v[6:7], v[4:5], v[8:9] op_sel:[0,0,1] op_sel_hi:[1,1,0]
	s_nop 0
	v_add_u32_e32 v4, 0x600, v21
	v_mov_b32_e32 v11, v5
	v_and_b32_e32 v9, s10, v4
	v_ashrrev_i32_e32 v4, s0, v4
	ds_write_b64 v29, v[10:11]
	v_lshlrev_b32_e32 v10, 2, v4
	v_lshl_add_u32 v11, v10, s0, v9
	v_ashrrev_i32_e32 v12, 4, v11
	v_add_lshl_u32 v21, v12, v11, 3
	v_add_u32_e32 v11, s1, v11
	v_cvt_f32_u32_e32 v4, v9
	v_ashrrev_i32_e32 v12, 4, v11
	v_add_lshl_u32 v26, v12, v11, 3
	v_or_b32_e32 v11, 2, v10
	v_or_b32_e32 v10, 3, v10
	v_lshl_add_u32 v11, v11, s0, v9
	v_lshl_add_u32 v9, v10, s0, v9
	v_mul_f32_e32 v4, v3, v4
	v_ashrrev_i32_e32 v12, 4, v11
	v_ashrrev_i32_e32 v10, 4, v9
	v_fract_f32_e32 v5, v4
	v_add_lshl_u32 v27, v12, v11, 3
	v_add_lshl_u32 v28, v10, v9, 3
	v_cos_f32_e32 v4, v5
	v_sin_f32_e32 v5, v5
	ds_read_b64 v[10:11], v21
	ds_read_b64 v[12:13], v26
	ds_read_b64 v[14:15], v27
	ds_read_b64 v[16:17], v28
	v_mov_b32_e32 v20, v5
	v_mul_f32_e64 v8, v4, -v5
	v_pk_mul_f32 v[6:7], v[4:5], v[4:5]
	s_waitcnt lgkmcnt(1)
	v_pk_add_f32 v[18:19], v[10:11], v[14:15] neg_lo:[0,1] neg_hi:[0,1]
	v_pk_add_f32 v[10:11], v[10:11], v[14:15]
	v_pk_mul_f32 v[22:23], v[20:21], v[18:19] op_sel_hi:[0,1]
	v_pk_fma_f32 v[24:25], v[18:19], v[4:5], v[22:23] op_sel:[0,0,1] op_sel_hi:[1,1,0]
	v_pk_fma_f32 v[18:19], v[18:19], v[4:5], v[22:23] op_sel:[0,0,1] op_sel_hi:[1,0,0] neg_lo:[0,0,1] neg_hi:[0,0,1]
	v_add_f32_e32 v8, v8, v8
	v_mov_b32_e32 v25, v19
	s_waitcnt lgkmcnt(0)
	v_pk_add_f32 v[18:19], v[12:13], v[16:17] neg_lo:[0,1] neg_hi:[0,1]
	v_pk_add_f32 v[12:13], v[12:13], v[16:17]
	v_xor_b32_e32 v23, 0x80000000, v18
	v_pk_add_f32 v[14:15], v[10:11], v[12:13]
	v_pk_add_f32 v[10:11], v[10:11], v[12:13] neg_lo:[0,1] neg_hi:[0,1]
	v_mov_b32_e32 v22, v19
	v_pk_mul_f32 v[18:19], v[20:21], v[18:19] op_sel_hi:[0,1]
	v_pk_mul_f32 v[12:13], v[8:9], v[10:11] op_sel_hi:[0,1]
	v_pk_add_f32 v[6:7], v[6:7], v[6:7] op_sel:[0,1] op_sel_hi:[0,1] neg_lo:[0,1] neg_hi:[0,1]
	v_pk_fma_f32 v[4:5], v[4:5], v[22:23], v[18:19] op_sel_hi:[0,1,1] neg_lo:[0,0,1] neg_hi:[0,0,1]
	ds_write_b64 v21, v[14:15]
	v_pk_fma_f32 v[14:15], v[6:7], v[10:11], v[12:13] op_sel:[0,0,1] op_sel_hi:[1,1,0] neg_lo:[0,0,1] neg_hi:[0,0,1]
	v_pk_fma_f32 v[10:11], v[6:7], v[10:11], v[12:13] op_sel:[0,0,1] op_sel_hi:[1,1,0]
	s_nop 0
	v_mov_b32_e32 v15, v11
	v_pk_add_f32 v[10:11], v[24:25], v[4:5]
	v_pk_add_f32 v[4:5], v[24:25], v[4:5] neg_lo:[0,1] neg_hi:[0,1]
	ds_write_b64 v26, v[14:15]
	v_pk_mul_f32 v[8:9], v[8:9], v[4:5] op_sel_hi:[0,1]
	ds_write_b64 v27, v[10:11]
	v_pk_fma_f32 v[10:11], v[6:7], v[4:5], v[8:9] op_sel:[0,0,1] op_sel_hi:[1,1,0] neg_lo:[0,0,1] neg_hi:[0,0,1]
	v_pk_fma_f32 v[4:5], v[6:7], v[4:5], v[8:9] op_sel:[0,0,1] op_sel_hi:[1,1,0]
	s_nop 0
	v_mov_b32_e32 v11, v5
	ds_write_b64 v28, v[10:11]
	s_cbranch_scc1 .LBB0_489
	s_add_i32 s1, s0, -2
	s_cmp_lg_u32 s0, 0
	s_mov_b32 s0, s1
	s_cbranch_scc1 .LBB0_488
	s_waitcnt lgkmcnt(0)
	s_barrier
	s_and_saveexec_b64 s[0:1], s[4:5]
	s_cbranch_execz .LBB0_499
	v_add_u32_e32 v4, 0x1ff, v70
	v_and_b32_e32 v2, 0xe00, v4
	s_movk_i32 s4, 0xe00
	v_cmp_ne_u32_e32 vcc, s4, v2
	s_and_saveexec_b64 s[4:5], vcc
	s_cbranch_execz .LBB0_496
	v_lshrrev_b32_e32 v2, 9, v4
	s_lshl_b64 s[10:11], s[6:7], 17
	v_readlane_b32 s12, v251, 0
	v_add_u32_e32 v2, 1, v2
	s_add_u32 s10, s12, s10
	v_readlane_b32 s12, v251, 1
	v_and_b32_e32 v6, 7, v2
	v_ashrrev_i32_e32 v53, 31, v52
	s_addc_u32 s11, s12, s11
	v_lshl_add_u64 v[2:3], v[52:53], 3, s[10:11]
	v_add_u32_e32 v5, 0, v50
	v_sub_u32_e32 v6, 0, v6
	s_mov_b64 s[10:11], 0
	s_mov_b64 s[12:13], 0x1000

; DI float sin_t(float turns) { return __builtin_amdgcn_sinf(__builtin_amdgcn_fractf(turns)); }
; DI float cos_t(float turns) { return __builtin_amdgcn_cosf(__builtin_amdgcn_fractf(turns)); }
; DI float2 cmul(float2 a, float2 b) { return make_float2(a.x * b.x - a.y * b.y, a.x * b.y + a.y * b.x); }
; template <int N, bool INV>
; DI void fft_lds(float2* s) {
;     ...
;     for (int lq = 0; (1 << lq) <= top; lq += 2) {
;       const int q = 1 << lq;
;       __syncthreads();
;       const float inv4q = 1.0f / (float)(4 * q);
; #pragma unroll 4
;       for (int it = 0; it < N / 4 / NT; ++it) {
;         int idx = tid + it * NT;
;         int j = idx & (q - 1), blk = idx >> lq;
;         int p0 = blk * 4 * q + j;
;         float f = (float)j * inv4q;
;         float2 t1 = make_float2(cos_t(f), sin_t(f));
;         float2 t2 = cmul(t1, t1);
;         float2 x0 = s[phys(p0)], x1 = s[phys(p0 + q)], x2 = s[phys(p0 + 2 * q)], x3 = s[phys(p0 + 3 * q)];
;         float2 b = cmul(x1, t2);
;         float2 a0 = make_float2(x0.x + b.x, x0.y + b.y), a1 = make_float2(x0.x - b.x, x0.y - b.y);
;         b = cmul(x3, t2);
;         float2 a2 = make_float2(x2.x + b.x, x2.y + b.y), a3 = make_float2(x2.x - b.x, x2.y - b.y);
;         b = cmul(a2, t1);
;         s[phys(p0)] = make_float2(a0.x + b.x, a0.y + b.y);
;         s[phys(p0 + 2 * q)] = make_float2(a0.x - b.x, a0.y - b.y);
;         float2 c3 = cmul(a3, t1);
;         b = make_float2(-c3.y, c3.x);
;         s[phys(p0 + q)] = make_float2(a1.x + b.x, a1.y + b.y);
;         s[phys(p0 + 3 * q)] = make_float2(a1.x - b.x, a1.y - b.y);
;       }
.LBB0_501:
	v_add_u32_e32 v3, s11, v2
	v_ashrrev_i32_e32 v4, s0, v3
	v_and_b32_e32 v9, s10, v3
	v_lshlrev_b32_e32 v10, 2, v4
	v_lshl_add_u32 v11, v10, s0, v9
	v_cvt_f32_u32_e32 v4, v9
	v_ashrrev_i32_e32 v12, 4, v11
	v_add_lshl_u32 v22, v12, v11, 3
	v_add_u32_e32 v11, s1, v11
	v_ashrrev_i32_e32 v12, 4, v11
	v_add_lshl_u32 v23, v12, v11, 3
	v_mul_f32_e32 v4, s5, v4
	v_or_b32_e32 v11, 2, v10
	v_or_b32_e32 v10, 3, v10
	v_fract_f32_e32 v5, v4
	v_lshl_add_u32 v11, v11, s0, v9
	v_lshl_add_u32 v9, v10, s0, v9
	v_cos_f32_e32 v4, v5
	v_sin_f32_e32 v5, v5
	v_ashrrev_i32_e32 v12, 4, v11
	v_ashrrev_i32_e32 v10, 4, v9
	v_add_lshl_u32 v24, v12, v11, 3
	v_lshlrev_b32_e32 v10, 3, v10
	v_lshlrev_b32_e32 v9, 3, v9
	v_add3_u32 v25, 0, v10, v9
	ds_read_b64 v[10:11], v22
	ds_read_b64 v[12:13], v23
	ds_read_b64 v[14:15], v24
	ds_read_b64 v[16:17], v25
	v_mul_f32_e32 v8, v4, v5
	v_pk_mul_f32 v[6:7], v[4:5], v[4:5]
	v_add_f32_e32 v8, v8, v8
	s_waitcnt lgkmcnt(2)
	v_pk_mul_f32 v[18:19], v[12:13], v[8:9] op_sel_hi:[1,0]
	v_pk_add_f32 v[6:7], v[6:7], v[6:7] op_sel:[0,1] op_sel_hi:[0,1] neg_lo:[0,1] neg_hi:[0,1]
	v_pk_fma_f32 v[20:21], v[12:13], v[6:7], v[18:19] op_sel:[0,0,1] op_sel_hi:[1,1,0] neg_lo:[0,0,1] neg_hi:[0,0,1]
	v_pk_fma_f32 v[12:13], v[12:13], v[6:7], v[18:19] op_sel:[0,0,1] op_sel_hi:[1,1,0]
	s_waitcnt lgkmcnt(0)
	v_pk_mul_f32 v[6:7], v[16:17], v[6:7]
	v_mov_b32_e32 v21, v13
	v_pk_fma_f32 v[18:19], v[16:17], v[8:9], v[6:7] op_sel:[0,0,1] op_sel_hi:[1,1,0]
	v_pk_fma_f32 v[6:7], v[16:17], v[8:9], v[6:7] op_sel:[0,0,1] op_sel_hi:[1,0,0] neg_lo:[1,0,0] neg_hi:[1,0,0]
	v_pk_add_f32 v[12:13], v[10:11], v[20:21] neg_lo:[0,1] neg_hi:[0,1]
	v_mov_b32_e32 v19, v7
	v_pk_add_f32 v[8:9], v[10:11], v[20:21]
	v_pk_add_f32 v[10:11], v[14:15], v[18:19] op_sel:[1,0] op_sel_hi:[0,1]
	v_pk_add_f32 v[6:7], v[14:15], v[18:19] op_sel:[1,0] op_sel_hi:[0,1] neg_lo:[0,1] neg_hi:[0,1]
	v_mov_b32_e32 v14, v5
	v_mov_b32_e32 v16, v5
	v_pk_mul_f32 v[18:19], v[4:5], v[10:11] op_sel_hi:[0,1]
	v_pk_fma_f32 v[14:15], v[14:15], v[10:11], v[18:19] op_sel:[0,0,1] op_sel_hi:[1,1,0] neg_lo:[1,0,0] neg_hi:[1,0,0]
	v_pk_fma_f32 v[10:11], v[16:17], v[10:11], v[18:19] op_sel:[0,0,1] op_sel_hi:[0,1,0]
	v_mov_b32_e32 v15, v11
	v_pk_add_f32 v[10:11], v[8:9], v[14:15]
	v_pk_add_f32 v[8:9], v[8:9], v[14:15] neg_lo:[0,1] neg_hi:[0,1]
	ds_write_b64 v22, v[10:11]
	ds_write_b64 v24, v[8:9]
	v_pk_mul_f32 v[8:9], v[16:17], v[6:7] op_sel_hi:[0,1]
	v_pk_fma_f32 v[10:11], v[4:5], v[6:7], v[8:9] op_sel:[0,0,1] op_sel_hi:[1,1,0]
	v_pk_fma_f32 v[4:5], v[4:5], v[6:7], v[8:9] op_sel:[0,0,1] op_sel_hi:[0,1,0] neg_lo:[0,0,1] neg_hi:[0,0,1]
	v_mov_b32_e32 v11, v5
	v_pk_add_f32 v[4:5], v[12:13], v[10:11] neg_lo:[0,1] neg_hi:[0,1]
	v_pk_add_f32 v[6:7], v[12:13], v[10:11]
	v_mov_b32_e32 v8, v4
	v_mov_b32_e32 v9, v7
	v_add_u32_e32 v4, 0x200, v3
	ds_write_b64 v23, v[8:9]
	v_and_b32_e32 v9, s10, v4
	v_ashrrev_i32_e32 v4, s0, v4
	v_lshlrev_b32_e32 v10, 2, v4
	v_lshl_add_u32 v11, v10, s0, v9
	v_cvt_f32_u32_e32 v4, v9
	v_ashrrev_i32_e32 v12, 4, v11
	v_add_lshl_u32 v22, v12, v11, 3
	v_add_u32_e32 v11, s1, v11
	v_ashrrev_i32_e32 v12, 4, v11
	v_add_lshl_u32 v23, v12, v11, 3
	v_mul_f32_e32 v4, s5, v4
	v_or_b32_e32 v11, 2, v10
	v_or_b32_e32 v10, 3, v10
	v_mov_b32_e32 v7, v5
	v_fract_f32_e32 v5, v4
	v_lshl_add_u32 v11, v11, s0, v9
	v_lshl_add_u32 v9, v10, s0, v9
	v_cos_f32_e32 v4, v5
	v_sin_f32_e32 v5, v5
	v_ashrrev_i32_e32 v12, 4, v11
	v_ashrrev_i32_e32 v10, 4, v9
	ds_write_b64 v25, v[6:7]
	v_add_lshl_u32 v24, v12, v11, 3
	v_lshlrev_b32_e32 v10, 3, v10
	v_lshlrev_b32_e32 v9, 3, v9
	v_add3_u32 v25, 0, v10, v9
	ds_read_b64 v[10:11], v22
	ds_read_b64 v[12:13], v23
	ds_read_b64 v[14:15], v24
	ds_read_b64 v[16:17], v25
	v_mul_f32_e32 v8, v4, v5
	v_pk_mul_f32 v[6:7], v[4:5], v[4:5]
	v_add_f32_e32 v8, v8, v8
	s_waitcnt lgkmcnt(2)
	v_pk_mul_f32 v[18:19], v[12:13], v[8:9] op_sel_hi:[1,0]
	v_pk_add_f32 v[6:7], v[6:7], v[6:7] op_sel:[0,1] op_sel_hi:[0,1] neg_lo:[0,1] neg_hi:[0,1]
	v_pk_fma_f32 v[20:21], v[12:13], v[6:7], v[18:19] op_sel:[0,0,1] op_sel_hi:[1,1,0] neg_lo:[0,0,1] neg_hi:[0,0,1]
	v_pk_fma_f32 v[12:13], v[12:13], v[6:7], v[18:19] op_sel:[0,0,1] op_sel_hi:[1,1,0]
	s_waitcnt lgkmcnt(0)
	v_pk_mul_f32 v[6:7], v[16:17], v[6:7]
	v_mov_b32_e32 v21, v13
	v_pk_fma_f32 v[18:19], v[16:17], v[8:9], v[6:7] op_sel:[0,0,1] op_sel_hi:[1,1,0]
	v_pk_fma_f32 v[6:7], v[16:17], v[8:9], v[6:7] op_sel:[0,0,1] op_sel_hi:[1,0,0] neg_lo:[1,0,0] neg_hi:[1,0,0]
	v_pk_add_f32 v[12:13], v[10:11], v[20:21] neg_lo:[0,1] neg_hi:[0,1]
	v_mov_b32_e32 v19, v7
	v_pk_add_f32 v[8:9], v[10:11], v[20:21]
	v_pk_add_f32 v[10:11], v[14:15], v[18:19] op_sel:[1,0] op_sel_hi:[0,1]
	v_pk_add_f32 v[6:7], v[14:15], v[18:19] op_sel:[1,0] op_sel_hi:[0,1] neg_lo:[0,1] neg_hi:[0,1]
	v_mov_b32_e32 v14, v5
	v_mov_b32_e32 v16, v5
	v_pk_mul_f32 v[18:19], v[4:5], v[10:11] op_sel_hi:[0,1]
	v_pk_fma_f32 v[14:15], v[14:15], v[10:11], v[18:19] op_sel:[0,0,1] op_sel_hi:[1,1,0] neg_lo:[1,0,0] neg_hi:[1,0,0]
	v_pk_fma_f32 v[10:11], v[16:17], v[10:11], v[18:19] op_sel:[0,0,1] op_sel_hi:[0,1,0]
	v_mov_b32_e32 v15, v11
	v_pk_add_f32 v[10:11], v[8:9], v[14:15]
	v_pk_add_f32 v[8:9], v[8:9], v[14:15] neg_lo:[0,1] neg_hi:[0,1]
	ds_write_b64 v22, v[10:11]
	ds_write_b64 v24, v[8:9]
	v_pk_mul_f32 v[8:9], v[16:17], v[6:7] op_sel_hi:[0,1]
	v_pk_fma_f32 v[10:11], v[4:5], v[6:7], v[8:9] op_sel:[0,0,1] op_sel_hi:[1,1,0]
	v_pk_fma_f32 v[4:5], v[4:5], v[6:7], v[8:9] op_sel:[0,0,1] op_sel_hi:[0,1,0] neg_lo:[0,0,1] neg_hi:[0,0,1]
	v_mov_b32_e32 v11, v5
	v_pk_add_f32 v[4:5], v[12:13], v[10:11] neg_lo:[0,1] neg_hi:[0,1]
	v_pk_add_f32 v[6:7], v[12:13], v[10:11]
	v_mov_b32_e32 v8, v4
	v_mov_b32_e32 v9, v7
	v_add_u32_e32 v4, 0x400, v3
	ds_write_b64 v23, v[8:9]
	v_and_b32_e32 v9, s10, v4
	v_ashrrev_i32_e32 v4, s0, v4
	v_lshlrev_b32_e32 v10, 2, v4
	v_lshl_add_u32 v11, v10, s0, v9
	v_cvt_f32_u32_e32 v4, v9
	v_ashrrev_i32_e32 v12, 4, v11
	v_add_lshl_u32 v22, v12, v11, 3
	v_add_u32_e32 v11, s1, v11
	v_ashrrev_i32_e32 v12, 4, v11
	v_add_lshl_u32 v23, v12, v11, 3
	v_mul_f32_e32 v4, s5, v4
	v_or_b32_e32 v11, 2, v10
	v_or_b32_e32 v10, 3, v10
	v_mov_b32_e32 v7, v5
	v_fract_f32_e32 v5, v4
	v_lshl_add_u32 v11, v11, s0, v9
	v_lshl_add_u32 v9, v10, s0, v9
	v_cos_f32_e32 v4, v5
	v_sin_f32_e32 v5, v5
	v_ashrrev_i32_e32 v12, 4, v11
	v_ashrrev_i32_e32 v10, 4, v9
	ds_write_b64 v25, v[6:7]
	v_add_lshl_u32 v24, v12, v11, 3
	v_lshlrev_b32_e32 v10, 3, v10
	v_lshlrev_b32_e32 v9, 3, v9
	v_add3_u32 v25, 0, v10, v9
	ds_read_b64 v[10:11], v22
	ds_read_b64 v[12:13], v23
	ds_read_b64 v[14:15], v24
	ds_read_b64 v[16:17], v25
	v_mul_f32_e32 v8, v4, v5
	v_pk_mul_f32 v[6:7], v[4:5], v[4:5]
	v_add_f32_e32 v8, v8, v8
	s_waitcnt lgkmcnt(2)
; DI unsigned pack2(float a, float b) { fl2_t f = {a, b}; bf2_t r = __builtin_convertvector(f, bf2_t); return __builtin_bit_cast(unsigned, r); }
; DI float sin_t(float turns) { return __builtin_amdgcn_sinf(__builtin_amdgcn_fractf(turns)); }
; DI float cos_t(float turns) { return __builtin_amdgcn_cosf(__builtin_amdgcn_fractf(turns)); }
; DI float2 cmul(float2 a, float2 b) { return make_float2(a.x * b.x - a.y * b.y, a.x * b.y + a.y * b.x); }
; template <int N, bool INV>
; DI void fft_lds(float2* s) {
;     ...
;       for (int it = 0; it < N / 4 / NT; ++it) {
;         int idx = tid + it * NT;
;         int j = idx & (q - 1), blk = idx >> lq;
;         int p0 = blk * 4 * q + j;
;         float f = (float)j * inv4q;
;         float2 t1 = make_float2(cos_t(f), sin_t(f));
;         float2 t2 = cmul(t1, t1);
;         float2 x0 = s[phys(p0)], x1 = s[phys(p0 + q)], x2 = s[phys(p0 + 2 * q)], x3 = s[phys(p0 + 3 * q)];
;         float2 b = cmul(x1, t2);
;         float2 a0 = make_float2(x0.x + b.x, x0.y + b.y), a1 = make_float2(x0.x - b.x, x0.y - b.y);
;         b = cmul(x3, t2);
;         float2 a2 = make_float2(x2.x + b.x, x2.y + b.y), a3 = make_float2(x2.x - b.x, x2.y - b.y);
;         b = cmul(a2, t1);
;         s[phys(p0)] = make_float2(a0.x + b.x, a0.y + b.y);
;         s[phys(p0 + 2 * q)] = make_float2(a0.x - b.x, a0.y - b.y);
;         float2 c3 = cmul(a3, t1);
;         b = make_float2(-c3.y, c3.x);
;         s[phys(p0 + q)] = make_float2(a1.x + b.x, a1.y + b.y);
;         s[phys(p0 + 3 * q)] = make_float2(a1.x - b.x, a1.y - b.y);
;       }
; DI void hyena_lat_item(const P& p, int l, int c, int bp, unsigned char* lds) {
;     ...
;         float r0[8], r1[8];
; #pragma unroll
;         for (int e = 0; e < 8; ++e) {
;           int n = ch * 4096 + tid * 8 + e;
;           float2 cv = s[phys(n)], y1 = scr[24576 + n], x2 = scr[16384 + n];
;           r0[e] = x2.x * (cv.x * invN + y1.x * bias);
;           r1[e] = x2.y * (cv.y * invN + y1.y * bias);
;         }
;         *(uint4*)(HYT + ((size_t)(2 * bp) * 256 + c) * L + ch * 4096 + tid * 8) = make_uint4(pack2(r0[0], r0[1]), pack2(r0[2], r0[3]), pack2(r0[4], r0[5]), pack2(r0[6], r0[7]));
;         *(uint4*)(HYT + ((size_t)(2 * bp + 1) * 256 + c) * L + ch * 4096 + tid * 8) = make_uint4(pack2(r1[0], r1[1]), pack2(r1[2], r1[3]), pack2(r1[4], r1[5]), pack2(r1[6], r1[7]));
	v_pk_mul_f32 v[18:19], v[12:13], v[8:9] op_sel_hi:[1,0]
	v_pk_add_f32 v[6:7], v[6:7], v[6:7] op_sel:[0,1] op_sel_hi:[0,1] neg_lo:[0,1] neg_hi:[0,1]
	v_pk_fma_f32 v[20:21], v[12:13], v[6:7], v[18:19] op_sel:[0,0,1] op_sel_hi:[1,1,0] neg_lo:[0,0,1] neg_hi:[0,0,1]
	v_pk_fma_f32 v[12:13], v[12:13], v[6:7], v[18:19] op_sel:[0,0,1] op_sel_hi:[1,1,0]
	s_waitcnt lgkmcnt(0)
	v_pk_mul_f32 v[6:7], v[16:17], v[6:7]
	v_mov_b32_e32 v21, v13
	v_pk_fma_f32 v[18:19], v[16:17], v[8:9], v[6:7] op_sel:[0,0,1] op_sel_hi:[1,1,0]
	v_pk_fma_f32 v[6:7], v[16:17], v[8:9], v[6:7] op_sel:[0,0,1] op_sel_hi:[1,0,0] neg_lo:[1,0,0] neg_hi:[1,0,0]
	v_pk_add_f32 v[12:13], v[10:11], v[20:21] neg_lo:[0,1] neg_hi:[0,1]
	v_mov_b32_e32 v19, v7
	v_pk_add_f32 v[8:9], v[10:11], v[20:21]
	v_pk_add_f32 v[10:11], v[14:15], v[18:19] op_sel:[1,0] op_sel_hi:[0,1]
	v_pk_add_f32 v[6:7], v[14:15], v[18:19] op_sel:[1,0] op_sel_hi:[0,1] neg_lo:[0,1] neg_hi:[0,1]
	v_mov_b32_e32 v14, v5
	v_mov_b32_e32 v16, v5
	v_pk_mul_f32 v[18:19], v[4:5], v[10:11] op_sel_hi:[0,1]
	v_pk_fma_f32 v[14:15], v[14:15], v[10:11], v[18:19] op_sel:[0,0,1] op_sel_hi:[1,1,0] neg_lo:[1,0,0] neg_hi:[1,0,0]
	v_pk_fma_f32 v[10:11], v[16:17], v[10:11], v[18:19] op_sel:[0,0,1] op_sel_hi:[0,1,0]
	v_mov_b32_e32 v15, v11
	v_pk_add_f32 v[10:11], v[8:9], v[14:15]
	v_pk_add_f32 v[8:9], v[8:9], v[14:15] neg_lo:[0,1] neg_hi:[0,1]
	ds_write_b64 v22, v[10:11]
	ds_write_b64 v24, v[8:9]
	v_pk_mul_f32 v[8:9], v[16:17], v[6:7] op_sel_hi:[0,1]
	v_pk_fma_f32 v[10:11], v[4:5], v[6:7], v[8:9] op_sel:[0,0,1] op_sel_hi:[1,1,0]
	v_pk_fma_f32 v[4:5], v[4:5], v[6:7], v[8:9] op_sel:[0,0,1] op_sel_hi:[0,1,0] neg_lo:[0,0,1] neg_hi:[0,0,1]
	v_mov_b32_e32 v11, v5
	v_pk_add_f32 v[4:5], v[12:13], v[10:11] neg_lo:[0,1] neg_hi:[0,1]
	v_pk_add_f32 v[6:7], v[12:13], v[10:11]
	v_mov_b32_e32 v8, v4
	v_mov_b32_e32 v9, v7
	v_add_u32_e32 v3, 0x600, v3
	ds_write_b64 v23, v[8:9]
	v_and_b32_e32 v9, s10, v3
	v_ashrrev_i32_e32 v3, s0, v3
	v_lshlrev_b32_e32 v3, 2, v3
	v_lshl_add_u32 v10, v3, s0, v9
	v_cvt_f32_u32_e32 v4, v9
	v_ashrrev_i32_e32 v11, 4, v10
	v_add_lshl_u32 v22, v11, v10, 3
	v_add_u32_e32 v10, s1, v10
	v_ashrrev_i32_e32 v11, 4, v10
	v_add_lshl_u32 v23, v11, v10, 3
	v_mul_f32_e32 v4, s5, v4
	v_or_b32_e32 v10, 2, v3
	v_or_b32_e32 v3, 3, v3
	v_mov_b32_e32 v7, v5
	v_fract_f32_e32 v5, v4
	v_lshl_add_u32 v10, v10, s0, v9
	v_lshl_add_u32 v3, v3, s0, v9
	v_cos_f32_e32 v4, v5
	v_sin_f32_e32 v5, v5
	v_ashrrev_i32_e32 v11, 4, v10
	v_ashrrev_i32_e32 v9, 4, v3
	ds_write_b64 v25, v[6:7]
	v_add_lshl_u32 v24, v11, v10, 3
	v_lshlrev_b32_e32 v9, 3, v9
	v_lshlrev_b32_e32 v3, 3, v3
	v_add3_u32 v3, 0, v9, v3
	ds_read_b64 v[10:11], v22
	ds_read_b64 v[12:13], v23
	ds_read_b64 v[14:15], v24
	ds_read_b64 v[16:17], v3
	v_mul_f32_e32 v8, v4, v5
	v_pk_mul_f32 v[6:7], v[4:5], v[4:5]
	v_add_f32_e32 v8, v8, v8
	s_waitcnt lgkmcnt(2)
	v_pk_mul_f32 v[18:19], v[12:13], v[8:9] op_sel_hi:[1,0]
	v_pk_add_f32 v[6:7], v[6:7], v[6:7] op_sel:[0,1] op_sel_hi:[0,1] neg_lo:[0,1] neg_hi:[0,1]
	v_pk_fma_f32 v[20:21], v[12:13], v[6:7], v[18:19] op_sel:[0,0,1] op_sel_hi:[1,1,0] neg_lo:[0,0,1] neg_hi:[0,0,1]
	v_pk_fma_f32 v[12:13], v[12:13], v[6:7], v[18:19] op_sel:[0,0,1] op_sel_hi:[1,1,0]
	s_waitcnt lgkmcnt(0)
	v_pk_mul_f32 v[6:7], v[16:17], v[6:7]
	v_mov_b32_e32 v21, v13
	v_pk_fma_f32 v[18:19], v[16:17], v[8:9], v[6:7] op_sel:[0,0,1] op_sel_hi:[1,1,0]
	v_pk_fma_f32 v[6:7], v[16:17], v[8:9], v[6:7] op_sel:[0,0,1] op_sel_hi:[1,0,0] neg_lo:[1,0,0] neg_hi:[1,0,0]
	v_pk_add_f32 v[12:13], v[10:11], v[20:21] neg_lo:[0,1] neg_hi:[0,1]
	v_mov_b32_e32 v19, v7
	v_pk_add_f32 v[8:9], v[10:11], v[20:21]
	v_pk_add_f32 v[10:11], v[14:15], v[18:19] op_sel:[1,0] op_sel_hi:[0,1]
	v_pk_add_f32 v[6:7], v[14:15], v[18:19] op_sel:[1,0] op_sel_hi:[0,1] neg_lo:[0,1] neg_hi:[0,1]
	v_mov_b32_e32 v14, v5
	v_mov_b32_e32 v16, v5
	v_pk_mul_f32 v[18:19], v[4:5], v[10:11] op_sel_hi:[0,1]
	v_pk_fma_f32 v[14:15], v[14:15], v[10:11], v[18:19] op_sel:[0,0,1] op_sel_hi:[1,1,0] neg_lo:[1,0,0] neg_hi:[1,0,0]
	v_pk_fma_f32 v[10:11], v[16:17], v[10:11], v[18:19] op_sel:[0,0,1] op_sel_hi:[0,1,0]
	v_mov_b32_e32 v15, v11
	v_pk_add_f32 v[10:11], v[8:9], v[14:15]
	v_pk_add_f32 v[8:9], v[8:9], v[14:15] neg_lo:[0,1] neg_hi:[0,1]
	ds_write_b64 v22, v[10:11]
	ds_write_b64 v24, v[8:9]
	v_pk_mul_f32 v[8:9], v[16:17], v[6:7] op_sel_hi:[0,1]
	v_pk_fma_f32 v[10:11], v[4:5], v[6:7], v[8:9] op_sel:[0,0,1] op_sel_hi:[1,1,0]
	v_pk_fma_f32 v[4:5], v[4:5], v[6:7], v[8:9] op_sel:[0,0,1] op_sel_hi:[0,1,0] neg_lo:[0,0,1] neg_hi:[0,0,1]
	v_mov_b32_e32 v11, v5
	v_pk_add_f32 v[4:5], v[12:13], v[10:11] neg_lo:[0,1] neg_hi:[0,1]
	v_pk_add_f32 v[6:7], v[12:13], v[10:11]
	s_addk_i32 s11, 0x800
	v_mov_b32_e32 v8, v4
	v_mov_b32_e32 v9, v7
	v_mov_b32_e32 v7, v5
	s_cmpk_lg_i32 s11, 0x1000
	ds_write_b64 v23, v[8:9]
	ds_write_b64 v3, v[6:7]
	s_cbranch_scc1 .LBB0_501
	s_add_i32 s5, s0, 2
	s_cmp_lt_u32 s0, 11
	s_mov_b32 s1, s4
	s_mov_b32 s0, s5
	s_cbranch_scc1 .LBB0_500
	s_lshl_b32 s4, s34, 9
	s_or_b32 s0, s4, 0x100
	s_add_u32 s0, s0, s6
	s_addc_u32 s1, 0, s7
	s_lshl_b64 s[0:1], s[0:1], 14
	s_add_u32 s4, s4, s6
	v_readlane_b32 s16, v252, 46
	s_addc_u32 s5, 0, s7
	s_add_i32 s54, s6, s71
	v_readlane_b32 s18, v252, 48
	v_readlane_b32 s19, v252, 49
	v_readlane_b32 s22, v252, 52
	v_readlane_b32 s23, v252, 53
	s_lshl_b64 s[4:5], s[4:5], 14
	s_lshl_b64 s[6:7], s[54:55], 2
	s_mov_b64 s[18:19], s[22:23]
	s_add_u32 s6, s18, s6
	s_addc_u32 s7, s19, s7
	s_waitcnt lgkmcnt(0)
	s_barrier
; DI unsigned pack2(float a, float b) { fl2_t f = {a, b}; bf2_t r = __builtin_convertvector(f, bf2_t); return __builtin_bit_cast(unsigned, r); }
; DI void hyena_lat_item(const P& p, int l, int c, int bp, unsigned char* lds) {
;     ...
;         float r0[8], r1[8];
; #pragma unroll
;         for (int e = 0; e < 8; ++e) {
;           int n = ch * 4096 + tid * 8 + e;
;           float2 cv = s[phys(n)], y1 = scr[24576 + n], x2 = scr[16384 + n];
;           r0[e] = x2.x * (cv.x * invN + y1.x * bias);
;           r1[e] = x2.y * (cv.y * invN + y1.y * bias);
;         }
;         *(uint4*)(HYT + ((size_t)(2 * bp) * 256 + c) * L + ch * 4096 + tid * 8) = make_uint4(pack2(r0[0], r0[1]), pack2(r0[2], r0[3]), pack2(r0[4], r0[5]), pack2(r0[6], r0[7]));
;         *(uint4*)(HYT + ((size_t)(2 * bp + 1) * 256 + c) * L + ch * 4096 + tid * 8) = make_uint4(pack2(r1[0], r1[1]), pack2(r1[2], r1[3]), pack2(r1[4], r1[5]), pack2(r1[6], r1[7]));
	global_load_dword v18, v179, s[6:7]
	v_readlane_b32 s6, v253, 18
	s_add_u32 s4, s6, s4
	v_readlane_b32 s7, v253, 19
	s_addc_u32 s5, s7, s5
	s_add_u32 s0, s6, s0
	v_lshlrev_b64 v[2:3], 1, v[50:51]
	s_addc_u32 s1, s7, s1
	v_lshl_add_u64 v[16:17], s[4:5], 0, v[2:3]
	v_lshl_add_u64 v[14:15], s[0:1], 0, v[2:3]
	ds_read2_b64 v[24:27], v63 offset1:1
	global_load_dwordx4 v[2:5], v[60:61], off offset:48
	global_load_dwordx4 v[10:13], v[60:61], off offset:32
	global_load_dwordx4 v[34:37], v[60:61], off offset:16
	global_load_dwordx4 v[40:43], v[60:61], off
	v_add_co_u32_e32 v6, vcc, s51, v58
	s_mov_b64 s[0:1], 0x20000
	s_nop 0
	v_addc_co_u32_e32 v7, vcc, 0, v59, vcc
	v_lshl_add_u64 v[20:21], v[58:59], 0, s[0:1]
	global_load_dwordx4 v[50:53], v[6:7], off
	s_nop 0
	global_load_dwordx4 v[6:9], v[20:21], off offset:48
	global_load_dwordx4 v[58:61], v[20:21], off offset:32
	global_load_dwordx4 v[64:67], v[20:21], off offset:16
	s_waitcnt lgkmcnt(0)
	v_mov_b32_e32 v20, v24
	v_mov_b32_e32 v21, v26
	s_mov_b32 s4, 0x38800000
	v_mov_b32_e32 v26, v25
	v_readlane_b32 s20, v252, 50
	v_readlane_b32 s21, v252, 51
	v_readlane_b32 s24, v252, 54
	v_readlane_b32 s25, v252, 55
	v_readlane_b32 s26, v252, 56
	v_readlane_b32 s27, v252, 57
	v_readlane_b32 s28, v252, 58
	v_readlane_b32 s29, v252, 59
	v_readlane_b32 s30, v252, 60
	v_readlane_b32 s31, v252, 61
	s_mov_b64 s[20:21], s[24:25]
	v_readlane_b32 s17, v252, 47
	s_mov_b64 s[22:23], s[26:27]
	s_mov_b64 s[24:25], s[28:29]
	s_mov_b64 s[26:27], s[30:31]
	s_waitcnt vmcnt(4)
	v_mov_b32_e32 v22, v40
	v_mov_b32_e32 v23, v42
	v_pk_mul_f32 v[22:23], v[18:19], v[22:23] op_sel_hi:[0,1]
	v_pk_fma_f32 v[20:21], v[20:21], s[4:5], v[22:23] op_sel_hi:[1,0,1]
	s_waitcnt vmcnt(3)
	v_mov_b32_e32 v22, v50
	v_mov_b32_e32 v23, v52
	v_mov_b32_e32 v42, v41
	v_pk_mul_f32 v[22:23], v[22:23], v[20:21]
	v_pk_mul_f32 v[20:21], v[18:19], v[42:43] op_sel_hi:[0,1]
	ds_read2_b64 v[40:43], v63 offset0:2 offset1:3
	v_pk_fma_f32 v[20:21], v[26:27], s[4:5], v[20:21] op_sel_hi:[1,0,1]
	v_mov_b32_e32 v26, v34
	v_mov_b32_e32 v27, v36
	v_pk_mul_f32 v[26:27], v[18:19], v[26:27] op_sel_hi:[0,1]
	s_waitcnt lgkmcnt(0)
	v_mov_b32_e32 v24, v40
	v_mov_b32_e32 v25, v42
	v_pk_fma_f32 v[24:25], v[24:25], s[4:5], v[26:27] op_sel_hi:[1,0,1]
	s_waitcnt vmcnt(0)
	v_mov_b32_e32 v26, v64
	v_mov_b32_e32 v27, v66
	v_mov_b32_e32 v36, v35
	v_pk_mul_f32 v[26:27], v[26:27], v[24:25]
	v_pk_mul_f32 v[24:25], v[18:19], v[36:37] op_sel_hi:[0,1]
	ds_read2_b64 v[34:37], v63 offset0:4 offset1:5
	v_mov_b32_e32 v42, v41
	v_mov_b32_e32 v41, v12
	v_mov_b32_e32 v12, v11
	v_mov_b32_e32 v40, v10
	s_waitcnt lgkmcnt(0)
	v_mov_b32_e32 v29, v36
	v_mov_b32_e32 v36, v35
	v_pk_mul_f32 v[10:11], v[18:19], v[12:13] op_sel_hi:[0,1]
	v_mov_b32_e32 v28, v34
	v_pk_fma_f32 v[10:11], v[36:37], s[4:5], v[10:11] op_sel_hi:[1,0,1]
	ds_read2_b64 v[34:37], v63 offset0:6 offset1:7
	v_pk_mul_f32 v[40:41], v[18:19], v[40:41] op_sel_hi:[0,1]
	v_pk_fma_f32 v[28:29], v[28:29], s[4:5], v[40:41] op_sel_hi:[1,0,1]
	v_mov_b32_e32 v40, v58
	v_mov_b32_e32 v41, v60
	v_pk_mul_f32 v[28:29], v[40:41], v[28:29]
	v_mov_b32_e32 v40, v2
	v_mov_b32_e32 v41, v4
	s_waitcnt lgkmcnt(0)
	v_mov_b32_e32 v12, v34
	v_mov_b32_e32 v13, v36
	v_pk_mul_f32 v[40:41], v[18:19], v[40:41] op_sel_hi:[0,1]
	v_mov_b32_e32 v4, v3
	v_pk_fma_f32 v[12:13], v[12:13], s[4:5], v[40:41] op_sel_hi:[1,0,1]
	v_mov_b32_e32 v40, v6
	v_mov_b32_e32 v41, v8
	v_mov_b32_e32 v36, v35
	v_pk_mul_f32 v[2:3], v[18:19], v[4:5] op_sel_hi:[0,1]
	v_mov_b32_e32 v52, v51
	v_pk_fma_f32 v[24:25], v[42:43], s[4:5], v[24:25] op_sel_hi:[1,0,1]
	v_mov_b32_e32 v66, v65
	v_mov_b32_e32 v60, v59
	v_pk_mul_f32 v[12:13], v[40:41], v[12:13]
	v_pk_fma_f32 v[2:3], v[36:37], s[4:5], v[2:3] op_sel_hi:[1,0,1]
	v_mov_b32_e32 v8, v7
	v_pk_mul_f32 v[20:21], v[52:53], v[20:21]
	v_pk_mul_f32 v[24:25], v[66:67], v[24:25]
	v_pk_mul_f32 v[10:11], v[60:61], v[10:11]
	v_pk_mul_f32 v[6:7], v[8:9], v[2:3]
	v_cvt_pk_bf16_f32 v2, v22, v23
	v_cvt_pk_bf16_f32 v3, v26, v27
	v_cvt_pk_bf16_f32 v4, v28, v29
	v_cvt_pk_bf16_f32 v5, v12, v13
	global_store_dwordx4 v[16:17], v[2:5], off
	ds_read2_b64 v[34:37], v1 offset1:1
	v_lshl_add_u64 v[26:27], v[54:55], 0, s[0:1]
	v_cvt_pk_bf16_f32 v2, v20, v21
	v_cvt_pk_bf16_f32 v3, v24, v25
	v_cvt_pk_bf16_f32 v4, v10, v11
	v_cvt_pk_bf16_f32 v5, v6, v7
	global_store_dwordx4 v[14:15], v[2:5], off
	global_load_dwordx2 v[24:25], v[48:49], off
	s_waitcnt vmcnt(0)
; DI unsigned pack2(float a, float b) { fl2_t f = {a, b}; bf2_t r = __builtin_convertvector(f, bf2_t); return __builtin_bit_cast(unsigned, r); }
; DI void hyena_lat_item(const P& p, int l, int c, int bp, unsigned char* lds) {
;     ...
;         float r0[8], r1[8];
; #pragma unroll
;         for (int e = 0; e < 8; ++e) {
;           int n = ch * 4096 + tid * 8 + e;
;           float2 cv = s[phys(n)], y1 = scr[24576 + n], x2 = scr[16384 + n];
;           r0[e] = x2.x * (cv.x * invN + y1.x * bias);
;           r1[e] = x2.y * (cv.y * invN + y1.y * bias);
;         }
;         *(uint4*)(HYT + ((size_t)(2 * bp) * 256 + c) * L + ch * 4096 + tid * 8) = make_uint4(pack2(r0[0], r0[1]), pack2(r0[2], r0[3]), pack2(r0[4], r0[5]), pack2(r0[6], r0[7]));
;         *(uint4*)(HYT + ((size_t)(2 * bp + 1) * 256 + c) * L + ch * 4096 + tid * 8) = make_uint4(pack2(r1[0], r1[1]), pack2(r1[2], r1[3]), pack2(r1[4], r1[5]), pack2(r1[6], r1[7]));
;     ...
;   __syncthreads();
	v_mov_b32_e32 v52, v24
	v_add_co_u32_e32 v2, vcc, s51, v46
	s_nop 1
	v_addc_co_u32_e32 v3, vcc, 0, v47, vcc
	global_load_dwordx2 v[28:29], v[2:3], off
	global_load_dwordx2 v[20:21], v[56:57], off offset:48
	s_nop 0
	global_load_dwordx4 v[2:5], v[56:57], off offset:32
	global_load_dwordx4 v[10:13], v[56:57], off offset:16
	global_load_dwordx4 v[40:43], v[56:57], off
	v_add_co_u32_e32 v6, vcc, s51, v54
	s_waitcnt vmcnt(1)
	v_mov_b32_e32 v39, v10
	v_addc_co_u32_e32 v7, vcc, 0, v55, vcc
	global_load_dwordx4 v[44:47], v[6:7], off
	global_load_dwordx2 v[22:23], v[26:27], off offset:48
	s_nop 0
	global_load_dwordx4 v[6:9], v[26:27], off offset:32
	global_load_dwordx4 v[48:51], v[26:27], off offset:16
	s_waitcnt vmcnt(4)
	v_mov_b32_e32 v53, v40
	v_mov_b32_e32 v40, v25
	s_waitcnt lgkmcnt(0)
	v_mov_b32_e32 v27, v36
	v_mov_b32_e32 v36, v35
	v_pk_mul_f32 v[24:25], v[18:19], v[40:41] op_sel_hi:[0,1]
	v_mov_b32_e32 v26, v34
	v_pk_fma_f32 v[24:25], v[36:37], s[4:5], v[24:25] op_sel_hi:[1,0,1]
	ds_read2_b64 v[34:37], v38 offset1:1
	v_pk_mul_f32 v[52:53], v[18:19], v[52:53] op_sel_hi:[0,1]
	v_mov_b32_e32 v10, v43
	v_pk_fma_f32 v[26:27], v[26:27], s[4:5], v[52:53] op_sel_hi:[1,0,1]
	v_pk_mul_f32 v[10:11], v[18:19], v[10:11] op_sel_hi:[0,1]
	v_mov_b32_e32 v52, v28
	s_waitcnt lgkmcnt(0)
	v_mov_b32_e32 v28, v34
	v_mov_b32_e32 v38, v42
	v_pk_mul_f32 v[38:39], v[18:19], v[38:39] op_sel_hi:[0,1]
	s_waitcnt vmcnt(3)
	v_mov_b32_e32 v53, v44
	v_mov_b32_e32 v44, v29
	v_mov_b32_e32 v29, v36
	v_mov_b32_e32 v36, v35
	v_pk_fma_f32 v[10:11], v[36:37], s[4:5], v[10:11] op_sel_hi:[1,0,1]
	ds_read2_b64 v[34:37], v30 offset1:1
	v_pk_fma_f32 v[28:29], v[28:29], s[4:5], v[38:39] op_sel_hi:[1,0,1]
	v_mov_b32_e32 v38, v46
	s_waitcnt vmcnt(0)
	v_mov_b32_e32 v39, v48
	v_pk_mul_f32 v[28:29], v[38:39], v[28:29]
	s_waitcnt lgkmcnt(0)
	v_mov_b32_e32 v30, v34
	v_mov_b32_e32 v31, v36
	v_mov_b32_e32 v36, v35
	ds_read2_b64 v[32:35], v32 offset1:1
	v_mov_b32_e32 v38, v12
	v_mov_b32_e32 v39, v2
	v_mov_b32_e32 v2, v13
	v_pk_mul_f32 v[38:39], v[18:19], v[38:39] op_sel_hi:[0,1]
	v_pk_mul_f32 v[2:3], v[18:19], v[2:3] op_sel_hi:[0,1]
	v_pk_fma_f32 v[30:31], v[30:31], s[4:5], v[38:39] op_sel_hi:[1,0,1]
	v_mov_b32_e32 v39, v6
	v_pk_fma_f32 v[2:3], v[36:37], s[4:5], v[2:3] op_sel_hi:[1,0,1]
	v_mov_b32_e32 v6, v51
	v_mov_b32_e32 v12, v4
	v_mov_b32_e32 v13, v20
	v_pk_mul_f32 v[2:3], v[6:7], v[2:3]
	s_waitcnt lgkmcnt(0)
	v_mov_b32_e32 v6, v32
	v_mov_b32_e32 v7, v34
	v_pk_mul_f32 v[12:13], v[18:19], v[12:13] op_sel_hi:[0,1]
	v_pk_fma_f32 v[6:7], v[6:7], s[4:5], v[12:13] op_sel_hi:[1,0,1]
	v_mov_b32_e32 v12, v8
	v_mov_b32_e32 v13, v22
	v_mov_b32_e32 v20, v5
	v_mov_b32_e32 v38, v50
	v_pk_mul_f32 v[12:13], v[12:13], v[6:7]
	v_mov_b32_e32 v34, v33
	v_pk_mul_f32 v[4:5], v[18:19], v[20:21] op_sel_hi:[0,1]
	v_pk_mul_f32 v[26:27], v[52:53], v[26:27]
	v_pk_mul_f32 v[30:31], v[38:39], v[30:31]
	v_pk_fma_f32 v[4:5], v[34:35], s[4:5], v[4:5] op_sel_hi:[1,0,1]
	v_mov_b32_e32 v22, v9
	v_cvt_pk_bf16_f32 v7, v12, v13
	v_add_co_u32_e32 v12, vcc, s91, v16
	v_mov_b32_e32 v48, v47
	v_pk_mul_f32 v[8:9], v[22:23], v[4:5]
	v_cvt_pk_bf16_f32 v4, v26, v27
	v_cvt_pk_bf16_f32 v5, v28, v29
	v_cvt_pk_bf16_f32 v6, v30, v31
	v_addc_co_u32_e32 v13, vcc, 0, v17, vcc
	v_pk_mul_f32 v[24:25], v[44:45], v[24:25]
	v_pk_mul_f32 v[10:11], v[48:49], v[10:11]
	global_store_dwordx4 v[12:13], v[4:7], off
	s_nop 1
	v_cvt_pk_bf16_f32 v6, v2, v3
	v_add_co_u32_e32 v2, vcc, 0x2000, v14
	v_cvt_pk_bf16_f32 v4, v24, v25
	v_cvt_pk_bf16_f32 v5, v10, v11
	v_cvt_pk_bf16_f32 v7, v8, v9
	v_addc_co_u32_e32 v3, vcc, 0, v15, vcc
	global_store_dwordx4 v[2:3], v[4:7], off
	s_barrier
